# G1 forward substitution: v_pk_fma_f32 pairs for column groups g>=1 (xv relaid to even-aligned v100..v163, ring in v32..v79), same fma order per accumulator
# speedup vs baseline: 1.0024x; 1.0024x over previous
; #define LAS __attribute__((address_space(3)))
; __device__ __forceinline__ bf16_t f2bf(float f) { return (bf16_t)(pk2(f, f) & 0xFFFFu); }
; __device__ NOINL void g1_phase(const LAS Params* lp, int l, LAS unsigned char* lds) {
;     ...
;         if (w < 6) {
;             const int s = w >> 1, dir = w & 1;
;             const LAS float* Ld = (const LAS float*)(lds + s * SLOT + 18432) + dir * 4096;
;             float xv[64];
; #pragma unroll
;             for (int i = 0; i < 64; ++i) {
;                 float s0 = (i == lane) ? 1.f : 0.f, s1 = 0.f, s2 = 0.f, s3 = 0.f;
; #pragma unroll
;                 for (int j4 = 0; j4 < (i + 3) / 4; ++j4) {
;                     const f32x4 lv = *(const LAS f32x4*)(Ld + i * 64 + j4 * 4);
;                     if (j4 * 4 + 0 < i) s0 -= lv[0] * xv[j4 * 4 + 0];
;                     if (j4 * 4 + 1 < i) s1 -= lv[1] * xv[j4 * 4 + 1];
;                     if (j4 * 4 + 2 < i) s2 -= lv[2] * xv[j4 * 4 + 2];
;                     if (j4 * 4 + 3 < i) s3 -= lv[3] * xv[j4 * 4 + 3];
;                 }
;                 xv[i] = (s0 + s1) + (s2 + s3);
;             }
;             bf16_t* Tg = p.Tbuf + ((((size_t)b * 4 + h) * 36 + c3 * 3 + s) * 2 + dir) * 4096;
; #pragma unroll
;             for (int i = 0; i < 64; ++i) Tg[i * 64 + lane] = f2bf(xv[i]);
.LBB0_1065:
	s_waitcnt lgkmcnt(0)
	s_barrier
	s_and_saveexec_b64 s[58:59], vcc
	s_cbranch_execz .LBB0_1044
	ds_read_b128 v[32:35], v28 offset:18688
	ds_read_b128 v[36:39], v28 offset:18944
	ds_read_b128 v[40:43], v28 offset:19200
	ds_read_b128 v[44:47], v28 offset:19456
	ds_read_b128 v[48:51], v28 offset:19712
	ds_read_b128 v[52:55], v28 offset:19728
	ds_read_b128 v[56:59], v28 offset:19968
	ds_read_b128 v[60:63], v28 offset:19984
	ds_read_b128 v[64:67], v28 offset:20224
	ds_read_b128 v[68:71], v28 offset:20240
	ds_read_b128 v[72:75], v28 offset:20480
	ds_read_b128 v[76:79], v28 offset:20496
	s_lshl_b32 s0, s67, 2
	s_or_b32 s0, s0, s68
	v_mad_i64_i32 v[18:19], s[0:1], s0, 36, v[18:19]
	v_mbcnt_lo_u32_b32 v88, -1, 0
	v_mbcnt_hi_u32_b32 v88, -1, v88
	v_lshlrev_b64 v[18:19], 14, v[18:19]
	v_lshl_add_u64 v[18:19], v[16:17], 0, v[18:19]
	v_add_co_u32_e64 v8, s[56:57], s83, v18
	s_nop 1
	v_addc_co_u32_e64 v9, s[56:57], 0, v19, s[56:57]
	global_store_short v[18:19], v95, off
	v_mov_b32_e32 v100, v31
	v_cmp_eq_u32_e64 s[56:57], 1, v88
	s_waitcnt lgkmcnt(11)
	s_nop 0
	v_cndmask_b32_e64 v84, 0, 1.0, s[56:57]
	v_fma_f32 v84, -v100, v32, v84
	ds_read_b128 v[32:35], v28 offset:20736
	v_mov_b32_e32 v101, v84
	v_cvt_pk_bf16_f32 v90, v101, v101
	global_store_short v[18:19], v90, off offset:128
	v_cmp_eq_u32_e64 s[56:57], 2, v88
	s_waitcnt lgkmcnt(11)
	s_nop 0
	v_cndmask_b32_e64 v80, 0, 1.0, s[56:57]
	v_fma_f32 v80, -v100, v36, v80
	v_fma_f32 v81, -v37, v101, 0
	ds_read_b128 v[36:39], v28 offset:20752
	v_add_f32_e32 v102, v80, v81
	v_cvt_pk_bf16_f32 v91, v102, v102
	global_store_short v[18:19], v91, off offset:256
	v_cmp_eq_u32_e64 s[56:57], 3, v88
	s_waitcnt lgkmcnt(11)
	s_nop 0
	v_cndmask_b32_e64 v84, 0, 1.0, s[56:57]
	v_fma_f32 v84, -v100, v40, v84
	v_fma_f32 v85, -v41, v101, 0
	v_fma_f32 v86, -v42, v102, 0
	ds_read_b128 v[40:43], v28 offset:20768
	v_add_f32_e32 v103, v84, v85
	v_add_f32_e32 v103, v103, v86
	v_cvt_pk_bf16_f32 v92, v103, v103
	global_store_short v[18:19], v92, off offset:384
	v_cmp_eq_u32_e64 s[56:57], 4, v88
	s_waitcnt lgkmcnt(11)
	s_nop 0
	v_cndmask_b32_e64 v80, 0, 1.0, s[56:57]
	v_fma_f32 v80, -v100, v44, v80
	v_fma_f32 v81, -v45, v101, 0
	v_fma_f32 v82, -v46, v102, 0
	v_fma_f32 v83, -v47, v103, 0
	ds_read_b128 v[44:47], v28 offset:20992
	v_add_f32_e32 v80, v80, v81
	v_add_f32_e32 v82, v82, v83
	v_add_f32_e32 v104, v80, v82
	v_cvt_pk_bf16_f32 v89, v104, v104
	global_store_short v[18:19], v89, off offset:512
	v_cmp_eq_u32_e64 s[56:57], 5, v88
	s_waitcnt lgkmcnt(11)
	s_nop 0
	v_cndmask_b32_e64 v84, 0, 1.0, s[56:57]
	v_fma_f32 v84, -v100, v48, v84
	v_fma_f32 v85, -v49, v101, 0
	v_fma_f32 v86, -v50, v102, 0
	v_fma_f32 v87, -v51, v103, 0
	ds_read_b128 v[48:51], v28 offset:21008
	s_waitcnt lgkmcnt(11)
	v_fma_f32 v84, -v52, v104, v84
	ds_read_b128 v[52:55], v28 offset:21024
	v_add_f32_e32 v84, v84, v85
	v_add_f32_e32 v86, v86, v87
	v_add_f32_e32 v105, v84, v86
	v_cvt_pk_bf16_f32 v90, v105, v105
	global_store_short v[18:19], v90, off offset:640
	v_cmp_eq_u32_e64 s[56:57], 6, v88
	s_waitcnt lgkmcnt(11)
	s_nop 0
	v_cndmask_b32_e64 v80, 0, 1.0, s[56:57]
	v_fma_f32 v80, -v100, v56, v80
	v_fma_f32 v81, -v57, v101, 0
	v_fma_f32 v82, -v58, v102, 0
	v_fma_f32 v83, -v59, v103, 0
	ds_read_b128 v[56:59], v28 offset:21248
	s_waitcnt lgkmcnt(11)
	v_pk_fma_f32 v[80:81], v[60:61], v[104:105], v[80:81] neg_lo:[1,0,0] neg_hi:[1,0,0]
	ds_read_b128 v[60:63], v28 offset:21264
	v_add_f32_e32 v80, v80, v81
	v_add_f32_e32 v82, v82, v83
	v_add_f32_e32 v106, v80, v82
	v_cvt_pk_bf16_f32 v91, v106, v106
	global_store_short v[18:19], v91, off offset:768
	v_cmp_eq_u32_e64 s[56:57], 7, v88
	s_waitcnt lgkmcnt(11)
	s_nop 0
	v_cndmask_b32_e64 v84, 0, 1.0, s[56:57]
	v_fma_f32 v84, -v100, v64, v84
	v_fma_f32 v85, -v65, v101, 0
	v_fma_f32 v86, -v66, v102, 0
	v_fma_f32 v87, -v67, v103, 0
	ds_read_b128 v[64:67], v28 offset:21280
	s_waitcnt lgkmcnt(11)
	v_pk_fma_f32 v[84:85], v[68:69], v[104:105], v[84:85] neg_lo:[1,0,0] neg_hi:[1,0,0]
	v_fma_f32 v86, -v70, v106, v86
	ds_read_b128 v[68:71], v28 offset:21504
	v_add_f32_e32 v84, v84, v85
	v_add_f32_e32 v86, v86, v87
	v_add_f32_e32 v107, v84, v86
	v_cvt_pk_bf16_f32 v92, v107, v107
	global_store_short v[18:19], v92, off offset:896
	v_cmp_eq_u32_e64 s[56:57], 8, v88
	s_waitcnt lgkmcnt(11)
	s_nop 0
	v_cndmask_b32_e64 v80, 0, 1.0, s[56:57]
	v_fma_f32 v80, -v100, v72, v80
	v_fma_f32 v81, -v73, v101, 0
	v_fma_f32 v82, -v74, v102, 0
	v_fma_f32 v83, -v75, v103, 0
	ds_read_b128 v[72:75], v28 offset:21520
	s_waitcnt lgkmcnt(11)
	v_pk_fma_f32 v[80:81], v[76:77], v[104:105], v[80:81] neg_lo:[1,0,0] neg_hi:[1,0,0]
	v_pk_fma_f32 v[82:83], v[78:79], v[106:107], v[82:83] neg_lo:[1,0,0] neg_hi:[1,0,0]
	ds_read_b128 v[76:79], v28 offset:21536
	v_add_f32_e32 v80, v80, v81
	v_add_f32_e32 v82, v82, v83
	v_add_f32_e32 v108, v80, v82
	v_cvt_pk_bf16_f32 v89, v108, v108
	global_store_short v[18:19], v89, off offset:1024
	v_cmp_eq_u32_e64 s[56:57], 9, v88
	s_waitcnt lgkmcnt(11)
	s_nop 0
	v_cndmask_b32_e64 v84, 0, 1.0, s[56:57]
	v_fma_f32 v84, -v100, v32, v84
	v_fma_f32 v85, -v33, v101, 0
	v_fma_f32 v86, -v34, v102, 0
	v_fma_f32 v87, -v35, v103, 0
	ds_read_b128 v[32:35], v28 offset:21760
	s_waitcnt lgkmcnt(11)
	v_pk_fma_f32 v[84:85], v[36:37], v[104:105], v[84:85] neg_lo:[1,0,0] neg_hi:[1,0,0]
	v_pk_fma_f32 v[86:87], v[38:39], v[106:107], v[86:87] neg_lo:[1,0,0] neg_hi:[1,0,0]
	ds_read_b128 v[36:39], v28 offset:21776
	s_waitcnt lgkmcnt(11)
	v_fma_f32 v84, -v40, v108, v84
	ds_read_b128 v[40:43], v28 offset:21792
	v_add_f32_e32 v84, v84, v85
	v_add_f32_e32 v86, v86, v87
	v_add_f32_e32 v109, v84, v86
	v_cvt_pk_bf16_f32 v90, v109, v109
	global_store_short v[18:19], v90, off offset:1152
	v_cmp_eq_u32_e64 s[56:57], 10, v88
	s_waitcnt lgkmcnt(11)
; #define LAS __attribute__((address_space(3)))
; __device__ __forceinline__ bf16_t f2bf(float f) { return (bf16_t)(pk2(f, f) & 0xFFFFu); }
; __device__ NOINL void g1_phase(const LAS Params* lp, int l, LAS unsigned char* lds) {
;     ...
; #pragma unroll
;             for (int i = 0; i < 64; ++i) {
;                 float s0 = (i == lane) ? 1.f : 0.f, s1 = 0.f, s2 = 0.f, s3 = 0.f;
; #pragma unroll
;                 for (int j4 = 0; j4 < (i + 3) / 4; ++j4) {
;                     const f32x4 lv = *(const LAS f32x4*)(Ld + i * 64 + j4 * 4);
;                     if (j4 * 4 + 0 < i) s0 -= lv[0] * xv[j4 * 4 + 0];
;                     if (j4 * 4 + 1 < i) s1 -= lv[1] * xv[j4 * 4 + 1];
;                     if (j4 * 4 + 2 < i) s2 -= lv[2] * xv[j4 * 4 + 2];
;                     if (j4 * 4 + 3 < i) s3 -= lv[3] * xv[j4 * 4 + 3];
;                 }
;                 xv[i] = (s0 + s1) + (s2 + s3);
;             }
;             bf16_t* Tg = p.Tbuf + ((((size_t)b * 4 + h) * 36 + c3 * 3 + s) * 2 + dir) * 4096;
; #pragma unroll
;             for (int i = 0; i < 64; ++i) Tg[i * 64 + lane] = f2bf(xv[i]);
	s_nop 0
	v_cndmask_b32_e64 v80, 0, 1.0, s[56:57]
	v_fma_f32 v80, -v100, v44, v80
	v_fma_f32 v81, -v45, v101, 0
	v_fma_f32 v82, -v46, v102, 0
	v_fma_f32 v83, -v47, v103, 0
	ds_read_b128 v[44:47], v28 offset:21808
	s_waitcnt lgkmcnt(11)
	v_pk_fma_f32 v[80:81], v[48:49], v[104:105], v[80:81] neg_lo:[1,0,0] neg_hi:[1,0,0]
	v_pk_fma_f32 v[82:83], v[50:51], v[106:107], v[82:83] neg_lo:[1,0,0] neg_hi:[1,0,0]
	ds_read_b128 v[48:51], v28 offset:22016
	s_waitcnt lgkmcnt(11)
	v_pk_fma_f32 v[80:81], v[52:53], v[108:109], v[80:81] neg_lo:[1,0,0] neg_hi:[1,0,0]
	ds_read_b128 v[52:55], v28 offset:22032
	v_add_f32_e32 v80, v80, v81
	v_add_f32_e32 v82, v82, v83
	v_add_f32_e32 v110, v80, v82
	v_cvt_pk_bf16_f32 v91, v110, v110
	global_store_short v[18:19], v91, off offset:1280
	v_cmp_eq_u32_e64 s[56:57], 11, v88
	s_waitcnt lgkmcnt(11)
	s_nop 0
	v_cndmask_b32_e64 v84, 0, 1.0, s[56:57]
	v_fma_f32 v84, -v100, v56, v84
	v_fma_f32 v85, -v57, v101, 0
	v_fma_f32 v86, -v58, v102, 0
	v_fma_f32 v87, -v59, v103, 0
	ds_read_b128 v[56:59], v28 offset:22048
	s_waitcnt lgkmcnt(11)
	v_pk_fma_f32 v[84:85], v[60:61], v[104:105], v[84:85] neg_lo:[1,0,0] neg_hi:[1,0,0]
	v_pk_fma_f32 v[86:87], v[62:63], v[106:107], v[86:87] neg_lo:[1,0,0] neg_hi:[1,0,0]
	ds_read_b128 v[60:63], v28 offset:22064
	s_waitcnt lgkmcnt(11)
	v_pk_fma_f32 v[84:85], v[64:65], v[108:109], v[84:85] neg_lo:[1,0,0] neg_hi:[1,0,0]
	v_fma_f32 v86, -v66, v110, v86
	ds_read_b128 v[64:67], v28 offset:22272
	v_add_f32_e32 v84, v84, v85
	v_add_f32_e32 v86, v86, v87
	v_add_f32_e32 v111, v84, v86
	v_cvt_pk_bf16_f32 v92, v111, v111
	global_store_short v[18:19], v92, off offset:1408
	v_cmp_eq_u32_e64 s[56:57], 12, v88
	s_waitcnt lgkmcnt(11)
	s_nop 0
	v_cndmask_b32_e64 v80, 0, 1.0, s[56:57]
	v_fma_f32 v80, -v100, v68, v80
	v_fma_f32 v81, -v69, v101, 0
	v_fma_f32 v82, -v70, v102, 0
	v_fma_f32 v83, -v71, v103, 0
	ds_read_b128 v[68:71], v28 offset:22288
	s_waitcnt lgkmcnt(11)
	v_pk_fma_f32 v[80:81], v[72:73], v[104:105], v[80:81] neg_lo:[1,0,0] neg_hi:[1,0,0]
	v_pk_fma_f32 v[82:83], v[74:75], v[106:107], v[82:83] neg_lo:[1,0,0] neg_hi:[1,0,0]
	ds_read_b128 v[72:75], v28 offset:22304
	s_waitcnt lgkmcnt(11)
	v_pk_fma_f32 v[80:81], v[76:77], v[108:109], v[80:81] neg_lo:[1,0,0] neg_hi:[1,0,0]
	v_pk_fma_f32 v[82:83], v[78:79], v[110:111], v[82:83] neg_lo:[1,0,0] neg_hi:[1,0,0]
	ds_read_b128 v[76:79], v28 offset:22320
	v_add_f32_e32 v80, v80, v81
	v_add_f32_e32 v82, v82, v83
	v_add_f32_e32 v112, v80, v82
	v_cvt_pk_bf16_f32 v89, v112, v112
	global_store_short v[18:19], v89, off offset:1536
	v_cmp_eq_u32_e64 s[56:57], 13, v88
	s_waitcnt lgkmcnt(11)
	s_nop 0
	v_cndmask_b32_e64 v84, 0, 1.0, s[56:57]
	v_fma_f32 v84, -v100, v32, v84
	v_fma_f32 v85, -v33, v101, 0
	v_fma_f32 v86, -v34, v102, 0
	v_fma_f32 v87, -v35, v103, 0
	ds_read_b128 v[32:35], v28 offset:22528
	s_waitcnt lgkmcnt(11)
	v_pk_fma_f32 v[84:85], v[36:37], v[104:105], v[84:85] neg_lo:[1,0,0] neg_hi:[1,0,0]
	v_pk_fma_f32 v[86:87], v[38:39], v[106:107], v[86:87] neg_lo:[1,0,0] neg_hi:[1,0,0]
	ds_read_b128 v[36:39], v28 offset:22544
	s_waitcnt lgkmcnt(11)
	v_pk_fma_f32 v[84:85], v[40:41], v[108:109], v[84:85] neg_lo:[1,0,0] neg_hi:[1,0,0]
	v_pk_fma_f32 v[86:87], v[42:43], v[110:111], v[86:87] neg_lo:[1,0,0] neg_hi:[1,0,0]
	ds_read_b128 v[40:43], v28 offset:22560
	s_waitcnt lgkmcnt(11)
	v_fma_f32 v84, -v44, v112, v84
	ds_read_b128 v[44:47], v28 offset:22576
	v_add_f32_e32 v84, v84, v85
	v_add_f32_e32 v86, v86, v87
	v_add_f32_e32 v113, v84, v86
	v_cvt_pk_bf16_f32 v90, v113, v113
	global_store_short v[18:19], v90, off offset:1664
	v_cmp_eq_u32_e64 s[56:57], 14, v88
	s_waitcnt lgkmcnt(11)
	s_nop 0
	v_cndmask_b32_e64 v80, 0, 1.0, s[56:57]
	v_fma_f32 v80, -v100, v48, v80
	v_fma_f32 v81, -v49, v101, 0
	v_fma_f32 v82, -v50, v102, 0
	v_fma_f32 v83, -v51, v103, 0
	ds_read_b128 v[48:51], v28 offset:22784
	s_waitcnt lgkmcnt(11)
	v_pk_fma_f32 v[80:81], v[52:53], v[104:105], v[80:81] neg_lo:[1,0,0] neg_hi:[1,0,0]
	v_pk_fma_f32 v[82:83], v[54:55], v[106:107], v[82:83] neg_lo:[1,0,0] neg_hi:[1,0,0]
	ds_read_b128 v[52:55], v28 offset:22800
	s_waitcnt lgkmcnt(11)
	v_pk_fma_f32 v[80:81], v[56:57], v[108:109], v[80:81] neg_lo:[1,0,0] neg_hi:[1,0,0]
	v_pk_fma_f32 v[82:83], v[58:59], v[110:111], v[82:83] neg_lo:[1,0,0] neg_hi:[1,0,0]
	ds_read_b128 v[56:59], v28 offset:22816
	s_waitcnt lgkmcnt(11)
	v_pk_fma_f32 v[80:81], v[60:61], v[112:113], v[80:81] neg_lo:[1,0,0] neg_hi:[1,0,0]
	ds_read_b128 v[60:63], v28 offset:22832
	v_add_f32_e32 v80, v80, v81
	v_add_f32_e32 v82, v82, v83
	v_add_f32_e32 v114, v80, v82
	v_cvt_pk_bf16_f32 v91, v114, v114
	global_store_short v[18:19], v91, off offset:1792
	v_cmp_eq_u32_e64 s[56:57], 15, v88
	s_waitcnt lgkmcnt(11)
	s_nop 0
	v_cndmask_b32_e64 v84, 0, 1.0, s[56:57]
	v_fma_f32 v84, -v100, v64, v84
	v_fma_f32 v85, -v65, v101, 0
	v_fma_f32 v86, -v66, v102, 0
	v_fma_f32 v87, -v67, v103, 0
	ds_read_b128 v[64:67], v28 offset:22848
	s_waitcnt lgkmcnt(11)
	v_pk_fma_f32 v[84:85], v[68:69], v[104:105], v[84:85] neg_lo:[1,0,0] neg_hi:[1,0,0]
	v_pk_fma_f32 v[86:87], v[70:71], v[106:107], v[86:87] neg_lo:[1,0,0] neg_hi:[1,0,0]
	ds_read_b128 v[68:71], v28 offset:23040
	s_waitcnt lgkmcnt(11)
	v_pk_fma_f32 v[84:85], v[72:73], v[108:109], v[84:85] neg_lo:[1,0,0] neg_hi:[1,0,0]
	v_pk_fma_f32 v[86:87], v[74:75], v[110:111], v[86:87] neg_lo:[1,0,0] neg_hi:[1,0,0]
	ds_read_b128 v[72:75], v28 offset:23056
	s_waitcnt lgkmcnt(11)
	v_pk_fma_f32 v[84:85], v[76:77], v[112:113], v[84:85] neg_lo:[1,0,0] neg_hi:[1,0,0]
	v_fma_f32 v86, -v78, v114, v86
	ds_read_b128 v[76:79], v28 offset:23072
	v_add_f32_e32 v84, v84, v85
	v_add_f32_e32 v86, v86, v87
	v_add_f32_e32 v115, v84, v86
	v_cvt_pk_bf16_f32 v92, v115, v115
	global_store_short v[18:19], v92, off offset:1920
	v_cmp_eq_u32_e64 s[56:57], 16, v88
	s_waitcnt lgkmcnt(11)
; #define LAS __attribute__((address_space(3)))
; __device__ __forceinline__ bf16_t f2bf(float f) { return (bf16_t)(pk2(f, f) & 0xFFFFu); }
; __device__ NOINL void g1_phase(const LAS Params* lp, int l, LAS unsigned char* lds) {
;     ...
;             for (int i = 0; i < 64; ++i) {
;                 float s0 = (i == lane) ? 1.f : 0.f, s1 = 0.f, s2 = 0.f, s3 = 0.f;
; #pragma unroll
;                 for (int j4 = 0; j4 < (i + 3) / 4; ++j4) {
;                     const f32x4 lv = *(const LAS f32x4*)(Ld + i * 64 + j4 * 4);
;                     if (j4 * 4 + 0 < i) s0 -= lv[0] * xv[j4 * 4 + 0];
;                     if (j4 * 4 + 1 < i) s1 -= lv[1] * xv[j4 * 4 + 1];
;                     if (j4 * 4 + 2 < i) s2 -= lv[2] * xv[j4 * 4 + 2];
;                     if (j4 * 4 + 3 < i) s3 -= lv[3] * xv[j4 * 4 + 3];
;                 }
;                 xv[i] = (s0 + s1) + (s2 + s3);
;             }
;             bf16_t* Tg = p.Tbuf + ((((size_t)b * 4 + h) * 36 + c3 * 3 + s) * 2 + dir) * 4096;
; #pragma unroll
;             for (int i = 0; i < 64; ++i) Tg[i * 64 + lane] = f2bf(xv[i]);
	s_nop 0
	v_cndmask_b32_e64 v80, 0, 1.0, s[56:57]
	v_fma_f32 v80, -v100, v32, v80
	v_fma_f32 v81, -v33, v101, 0
	v_fma_f32 v82, -v34, v102, 0
	v_fma_f32 v83, -v35, v103, 0
	ds_read_b128 v[32:35], v28 offset:23088
	s_waitcnt lgkmcnt(11)
	v_pk_fma_f32 v[80:81], v[36:37], v[104:105], v[80:81] neg_lo:[1,0,0] neg_hi:[1,0,0]
	v_pk_fma_f32 v[82:83], v[38:39], v[106:107], v[82:83] neg_lo:[1,0,0] neg_hi:[1,0,0]
	ds_read_b128 v[36:39], v28 offset:23104
	s_waitcnt lgkmcnt(11)
	v_pk_fma_f32 v[80:81], v[40:41], v[108:109], v[80:81] neg_lo:[1,0,0] neg_hi:[1,0,0]
	v_pk_fma_f32 v[82:83], v[42:43], v[110:111], v[82:83] neg_lo:[1,0,0] neg_hi:[1,0,0]
	ds_read_b128 v[40:43], v28 offset:23296
	s_waitcnt lgkmcnt(11)
	v_pk_fma_f32 v[80:81], v[44:45], v[112:113], v[80:81] neg_lo:[1,0,0] neg_hi:[1,0,0]
	v_pk_fma_f32 v[82:83], v[46:47], v[114:115], v[82:83] neg_lo:[1,0,0] neg_hi:[1,0,0]
	ds_read_b128 v[44:47], v28 offset:23312
	v_add_f32_e32 v80, v80, v81
	v_add_f32_e32 v82, v82, v83
	v_add_f32_e32 v116, v80, v82
	v_cvt_pk_bf16_f32 v89, v116, v116
	global_store_short v[18:19], v89, off offset:2048
	v_cmp_eq_u32_e64 s[56:57], 17, v88
	s_waitcnt lgkmcnt(11)
	s_nop 0
	v_cndmask_b32_e64 v84, 0, 1.0, s[56:57]
	v_fma_f32 v84, -v100, v48, v84
	v_fma_f32 v85, -v49, v101, 0
	v_fma_f32 v86, -v50, v102, 0
	v_fma_f32 v87, -v51, v103, 0
	ds_read_b128 v[48:51], v28 offset:23328
	s_waitcnt lgkmcnt(11)
	v_pk_fma_f32 v[84:85], v[52:53], v[104:105], v[84:85] neg_lo:[1,0,0] neg_hi:[1,0,0]
	v_pk_fma_f32 v[86:87], v[54:55], v[106:107], v[86:87] neg_lo:[1,0,0] neg_hi:[1,0,0]
	ds_read_b128 v[52:55], v28 offset:23344
	s_waitcnt lgkmcnt(11)
	v_pk_fma_f32 v[84:85], v[56:57], v[108:109], v[84:85] neg_lo:[1,0,0] neg_hi:[1,0,0]
	v_pk_fma_f32 v[86:87], v[58:59], v[110:111], v[86:87] neg_lo:[1,0,0] neg_hi:[1,0,0]
	ds_read_b128 v[56:59], v28 offset:23360
	s_waitcnt lgkmcnt(11)
	v_pk_fma_f32 v[84:85], v[60:61], v[112:113], v[84:85] neg_lo:[1,0,0] neg_hi:[1,0,0]
	v_pk_fma_f32 v[86:87], v[62:63], v[114:115], v[86:87] neg_lo:[1,0,0] neg_hi:[1,0,0]
	ds_read_b128 v[60:63], v28 offset:23552
	s_waitcnt lgkmcnt(11)
	v_fma_f32 v84, -v64, v116, v84
	ds_read_b128 v[64:67], v28 offset:23568
	v_add_f32_e32 v84, v84, v85
	v_add_f32_e32 v86, v86, v87
	v_add_f32_e32 v117, v84, v86
	v_cvt_pk_bf16_f32 v90, v117, v117
	global_store_short v[18:19], v90, off offset:2176
	v_cmp_eq_u32_e64 s[56:57], 18, v88
	s_waitcnt lgkmcnt(11)
	s_nop 0
	v_cndmask_b32_e64 v80, 0, 1.0, s[56:57]
	v_fma_f32 v80, -v100, v68, v80
	v_fma_f32 v81, -v69, v101, 0
	v_fma_f32 v82, -v70, v102, 0
	v_fma_f32 v83, -v71, v103, 0
	ds_read_b128 v[68:71], v28 offset:23584
	s_waitcnt lgkmcnt(11)
	v_pk_fma_f32 v[80:81], v[72:73], v[104:105], v[80:81] neg_lo:[1,0,0] neg_hi:[1,0,0]
	v_pk_fma_f32 v[82:83], v[74:75], v[106:107], v[82:83] neg_lo:[1,0,0] neg_hi:[1,0,0]
	ds_read_b128 v[72:75], v28 offset:23600
	s_waitcnt lgkmcnt(11)
	v_pk_fma_f32 v[80:81], v[76:77], v[108:109], v[80:81] neg_lo:[1,0,0] neg_hi:[1,0,0]
	v_pk_fma_f32 v[82:83], v[78:79], v[110:111], v[82:83] neg_lo:[1,0,0] neg_hi:[1,0,0]
	ds_read_b128 v[76:79], v28 offset:23616
	s_waitcnt lgkmcnt(11)
	v_pk_fma_f32 v[80:81], v[32:33], v[112:113], v[80:81] neg_lo:[1,0,0] neg_hi:[1,0,0]
	v_pk_fma_f32 v[82:83], v[34:35], v[114:115], v[82:83] neg_lo:[1,0,0] neg_hi:[1,0,0]
	ds_read_b128 v[32:35], v28 offset:23808
	s_waitcnt lgkmcnt(11)
	v_pk_fma_f32 v[80:81], v[36:37], v[116:117], v[80:81] neg_lo:[1,0,0] neg_hi:[1,0,0]
	ds_read_b128 v[36:39], v28 offset:23824
	v_add_f32_e32 v80, v80, v81
	v_add_f32_e32 v82, v82, v83
	v_add_f32_e32 v118, v80, v82
	v_cvt_pk_bf16_f32 v91, v118, v118
	global_store_short v[18:19], v91, off offset:2304
	v_cmp_eq_u32_e64 s[56:57], 19, v88
	s_waitcnt lgkmcnt(11)
	s_nop 0
	v_cndmask_b32_e64 v84, 0, 1.0, s[56:57]
	v_fma_f32 v84, -v100, v40, v84
	v_fma_f32 v85, -v41, v101, 0
	v_fma_f32 v86, -v42, v102, 0
	v_fma_f32 v87, -v43, v103, 0
	ds_read_b128 v[40:43], v28 offset:23840
	s_waitcnt lgkmcnt(11)
	v_pk_fma_f32 v[84:85], v[44:45], v[104:105], v[84:85] neg_lo:[1,0,0] neg_hi:[1,0,0]
	v_pk_fma_f32 v[86:87], v[46:47], v[106:107], v[86:87] neg_lo:[1,0,0] neg_hi:[1,0,0]
	ds_read_b128 v[44:47], v28 offset:23856
	s_waitcnt lgkmcnt(11)
	v_pk_fma_f32 v[84:85], v[48:49], v[108:109], v[84:85] neg_lo:[1,0,0] neg_hi:[1,0,0]
	v_pk_fma_f32 v[86:87], v[50:51], v[110:111], v[86:87] neg_lo:[1,0,0] neg_hi:[1,0,0]
	ds_read_b128 v[48:51], v28 offset:23872
	s_waitcnt lgkmcnt(11)
	v_pk_fma_f32 v[84:85], v[52:53], v[112:113], v[84:85] neg_lo:[1,0,0] neg_hi:[1,0,0]
	v_pk_fma_f32 v[86:87], v[54:55], v[114:115], v[86:87] neg_lo:[1,0,0] neg_hi:[1,0,0]
	ds_read_b128 v[52:55], v28 offset:23888
	s_waitcnt lgkmcnt(11)
	v_pk_fma_f32 v[84:85], v[56:57], v[116:117], v[84:85] neg_lo:[1,0,0] neg_hi:[1,0,0]
	v_fma_f32 v86, -v58, v118, v86
	ds_read_b128 v[56:59], v28 offset:24064
	v_add_f32_e32 v84, v84, v85
	v_add_f32_e32 v86, v86, v87
	v_add_f32_e32 v119, v84, v86
	v_cvt_pk_bf16_f32 v92, v119, v119
	global_store_short v[18:19], v92, off offset:2432
	v_cmp_eq_u32_e64 s[56:57], 20, v88
	s_waitcnt lgkmcnt(11)
	s_nop 0
	v_cndmask_b32_e64 v80, 0, 1.0, s[56:57]
	v_fma_f32 v80, -v100, v60, v80
	v_fma_f32 v81, -v61, v101, 0
	v_fma_f32 v82, -v62, v102, 0
	v_fma_f32 v83, -v63, v103, 0
	ds_read_b128 v[60:63], v28 offset:24080
	s_waitcnt lgkmcnt(11)
	v_pk_fma_f32 v[80:81], v[64:65], v[104:105], v[80:81] neg_lo:[1,0,0] neg_hi:[1,0,0]
	v_pk_fma_f32 v[82:83], v[66:67], v[106:107], v[82:83] neg_lo:[1,0,0] neg_hi:[1,0,0]
	ds_read_b128 v[64:67], v28 offset:24096
	s_waitcnt lgkmcnt(11)
	v_pk_fma_f32 v[80:81], v[68:69], v[108:109], v[80:81] neg_lo:[1,0,0] neg_hi:[1,0,0]
	v_pk_fma_f32 v[82:83], v[70:71], v[110:111], v[82:83] neg_lo:[1,0,0] neg_hi:[1,0,0]
	ds_read_b128 v[68:71], v28 offset:24112
	s_waitcnt lgkmcnt(11)
; #define LAS __attribute__((address_space(3)))
; __device__ __forceinline__ bf16_t f2bf(float f) { return (bf16_t)(pk2(f, f) & 0xFFFFu); }
; __device__ NOINL void g1_phase(const LAS Params* lp, int l, LAS unsigned char* lds) {
;     ...
;             for (int i = 0; i < 64; ++i) {
;                 float s0 = (i == lane) ? 1.f : 0.f, s1 = 0.f, s2 = 0.f, s3 = 0.f;
; #pragma unroll
;                 for (int j4 = 0; j4 < (i + 3) / 4; ++j4) {
;                     const f32x4 lv = *(const LAS f32x4*)(Ld + i * 64 + j4 * 4);
;                     if (j4 * 4 + 0 < i) s0 -= lv[0] * xv[j4 * 4 + 0];
;                     if (j4 * 4 + 1 < i) s1 -= lv[1] * xv[j4 * 4 + 1];
;                     if (j4 * 4 + 2 < i) s2 -= lv[2] * xv[j4 * 4 + 2];
;                     if (j4 * 4 + 3 < i) s3 -= lv[3] * xv[j4 * 4 + 3];
;                 }
;                 xv[i] = (s0 + s1) + (s2 + s3);
;             }
;             bf16_t* Tg = p.Tbuf + ((((size_t)b * 4 + h) * 36 + c3 * 3 + s) * 2 + dir) * 4096;
; #pragma unroll
;             for (int i = 0; i < 64; ++i) Tg[i * 64 + lane] = f2bf(xv[i]);
	v_pk_fma_f32 v[80:81], v[72:73], v[112:113], v[80:81] neg_lo:[1,0,0] neg_hi:[1,0,0]
	v_pk_fma_f32 v[82:83], v[74:75], v[114:115], v[82:83] neg_lo:[1,0,0] neg_hi:[1,0,0]
	ds_read_b128 v[72:75], v28 offset:24128
	s_waitcnt lgkmcnt(11)
	v_pk_fma_f32 v[80:81], v[76:77], v[116:117], v[80:81] neg_lo:[1,0,0] neg_hi:[1,0,0]
	v_pk_fma_f32 v[82:83], v[78:79], v[118:119], v[82:83] neg_lo:[1,0,0] neg_hi:[1,0,0]
	ds_read_b128 v[76:79], v28 offset:24144
	v_add_f32_e32 v80, v80, v81
	v_add_f32_e32 v82, v82, v83
	v_add_f32_e32 v120, v80, v82
	v_cvt_pk_bf16_f32 v89, v120, v120
	global_store_short v[18:19], v89, off offset:2560
	v_cmp_eq_u32_e64 s[56:57], 21, v88
	s_waitcnt lgkmcnt(11)
	s_nop 0
	v_cndmask_b32_e64 v84, 0, 1.0, s[56:57]
	v_fma_f32 v84, -v100, v32, v84
	v_fma_f32 v85, -v33, v101, 0
	v_fma_f32 v86, -v34, v102, 0
	v_fma_f32 v87, -v35, v103, 0
	ds_read_b128 v[32:35], v28 offset:24320
	s_waitcnt lgkmcnt(11)
	v_pk_fma_f32 v[84:85], v[36:37], v[104:105], v[84:85] neg_lo:[1,0,0] neg_hi:[1,0,0]
	v_pk_fma_f32 v[86:87], v[38:39], v[106:107], v[86:87] neg_lo:[1,0,0] neg_hi:[1,0,0]
	ds_read_b128 v[36:39], v28 offset:24336
	s_waitcnt lgkmcnt(11)
	v_pk_fma_f32 v[84:85], v[40:41], v[108:109], v[84:85] neg_lo:[1,0,0] neg_hi:[1,0,0]
	v_pk_fma_f32 v[86:87], v[42:43], v[110:111], v[86:87] neg_lo:[1,0,0] neg_hi:[1,0,0]
	ds_read_b128 v[40:43], v28 offset:24352
	s_waitcnt lgkmcnt(11)
	v_pk_fma_f32 v[84:85], v[44:45], v[112:113], v[84:85] neg_lo:[1,0,0] neg_hi:[1,0,0]
	v_pk_fma_f32 v[86:87], v[46:47], v[114:115], v[86:87] neg_lo:[1,0,0] neg_hi:[1,0,0]
	ds_read_b128 v[44:47], v28 offset:24368
	s_waitcnt lgkmcnt(11)
	v_pk_fma_f32 v[84:85], v[48:49], v[116:117], v[84:85] neg_lo:[1,0,0] neg_hi:[1,0,0]
	v_pk_fma_f32 v[86:87], v[50:51], v[118:119], v[86:87] neg_lo:[1,0,0] neg_hi:[1,0,0]
	ds_read_b128 v[48:51], v28 offset:24384
	s_waitcnt lgkmcnt(11)
	v_fma_f32 v84, -v52, v120, v84
	ds_read_b128 v[52:55], v28 offset:24400
	v_add_f32_e32 v84, v84, v85
	v_add_f32_e32 v86, v86, v87
	v_add_f32_e32 v121, v84, v86
	v_cvt_pk_bf16_f32 v90, v121, v121
	global_store_short v[18:19], v90, off offset:2688
	v_cmp_eq_u32_e64 s[56:57], 22, v88
	s_waitcnt lgkmcnt(11)
	s_nop 0
	v_cndmask_b32_e64 v80, 0, 1.0, s[56:57]
	v_fma_f32 v80, -v100, v56, v80
	v_fma_f32 v81, -v57, v101, 0
	v_fma_f32 v82, -v58, v102, 0
	v_fma_f32 v83, -v59, v103, 0
	ds_read_b128 v[56:59], v28 offset:24576
	s_waitcnt lgkmcnt(11)
	v_pk_fma_f32 v[80:81], v[60:61], v[104:105], v[80:81] neg_lo:[1,0,0] neg_hi:[1,0,0]
	v_pk_fma_f32 v[82:83], v[62:63], v[106:107], v[82:83] neg_lo:[1,0,0] neg_hi:[1,0,0]
	ds_read_b128 v[60:63], v28 offset:24592
	s_waitcnt lgkmcnt(11)
	v_pk_fma_f32 v[80:81], v[64:65], v[108:109], v[80:81] neg_lo:[1,0,0] neg_hi:[1,0,0]
	v_pk_fma_f32 v[82:83], v[66:67], v[110:111], v[82:83] neg_lo:[1,0,0] neg_hi:[1,0,0]
	ds_read_b128 v[64:67], v28 offset:24608
	s_waitcnt lgkmcnt(11)
	v_pk_fma_f32 v[80:81], v[68:69], v[112:113], v[80:81] neg_lo:[1,0,0] neg_hi:[1,0,0]
	v_pk_fma_f32 v[82:83], v[70:71], v[114:115], v[82:83] neg_lo:[1,0,0] neg_hi:[1,0,0]
	ds_read_b128 v[68:71], v28 offset:24624
	s_waitcnt lgkmcnt(11)
	v_pk_fma_f32 v[80:81], v[72:73], v[116:117], v[80:81] neg_lo:[1,0,0] neg_hi:[1,0,0]
	v_pk_fma_f32 v[82:83], v[74:75], v[118:119], v[82:83] neg_lo:[1,0,0] neg_hi:[1,0,0]
	ds_read_b128 v[72:75], v28 offset:24640
	s_waitcnt lgkmcnt(11)
	v_pk_fma_f32 v[80:81], v[76:77], v[120:121], v[80:81] neg_lo:[1,0,0] neg_hi:[1,0,0]
	ds_read_b128 v[76:79], v28 offset:24656
	v_add_f32_e32 v80, v80, v81
	v_add_f32_e32 v82, v82, v83
	v_add_f32_e32 v122, v80, v82
	v_cvt_pk_bf16_f32 v91, v122, v122
	global_store_short v[18:19], v91, off offset:2816
	v_cmp_eq_u32_e64 s[56:57], 23, v88
	s_waitcnt lgkmcnt(11)
	s_nop 0
	v_cndmask_b32_e64 v84, 0, 1.0, s[56:57]
	v_fma_f32 v84, -v100, v32, v84
	v_fma_f32 v85, -v33, v101, 0
	v_fma_f32 v86, -v34, v102, 0
	v_fma_f32 v87, -v35, v103, 0
	ds_read_b128 v[32:35], v28 offset:24832
	s_waitcnt lgkmcnt(11)
	v_pk_fma_f32 v[84:85], v[36:37], v[104:105], v[84:85] neg_lo:[1,0,0] neg_hi:[1,0,0]
	v_pk_fma_f32 v[86:87], v[38:39], v[106:107], v[86:87] neg_lo:[1,0,0] neg_hi:[1,0,0]
	ds_read_b128 v[36:39], v28 offset:24848
	s_waitcnt lgkmcnt(11)
	v_pk_fma_f32 v[84:85], v[40:41], v[108:109], v[84:85] neg_lo:[1,0,0] neg_hi:[1,0,0]
	v_pk_fma_f32 v[86:87], v[42:43], v[110:111], v[86:87] neg_lo:[1,0,0] neg_hi:[1,0,0]
	ds_read_b128 v[40:43], v28 offset:24864
	s_waitcnt lgkmcnt(11)
	v_pk_fma_f32 v[84:85], v[44:45], v[112:113], v[84:85] neg_lo:[1,0,0] neg_hi:[1,0,0]
	v_pk_fma_f32 v[86:87], v[46:47], v[114:115], v[86:87] neg_lo:[1,0,0] neg_hi:[1,0,0]
	ds_read_b128 v[44:47], v28 offset:24880
	s_waitcnt lgkmcnt(11)
	v_pk_fma_f32 v[84:85], v[48:49], v[116:117], v[84:85] neg_lo:[1,0,0] neg_hi:[1,0,0]
	v_pk_fma_f32 v[86:87], v[50:51], v[118:119], v[86:87] neg_lo:[1,0,0] neg_hi:[1,0,0]
	ds_read_b128 v[48:51], v28 offset:24896
	s_waitcnt lgkmcnt(11)
	v_pk_fma_f32 v[84:85], v[52:53], v[120:121], v[84:85] neg_lo:[1,0,0] neg_hi:[1,0,0]
	v_fma_f32 v86, -v54, v122, v86
	ds_read_b128 v[52:55], v28 offset:24912
	v_add_f32_e32 v84, v84, v85
	v_add_f32_e32 v86, v86, v87
	v_add_f32_e32 v123, v84, v86
	v_cvt_pk_bf16_f32 v92, v123, v123
	global_store_short v[18:19], v92, off offset:2944
	v_cmp_eq_u32_e64 s[56:57], 24, v88
	s_waitcnt lgkmcnt(11)
	s_nop 0
	v_cndmask_b32_e64 v80, 0, 1.0, s[56:57]
	v_fma_f32 v80, -v100, v56, v80
	v_fma_f32 v81, -v57, v101, 0
	v_fma_f32 v82, -v58, v102, 0
	v_fma_f32 v83, -v59, v103, 0
	ds_read_b128 v[56:59], v28 offset:24928
	s_waitcnt lgkmcnt(11)
	v_pk_fma_f32 v[80:81], v[60:61], v[104:105], v[80:81] neg_lo:[1,0,0] neg_hi:[1,0,0]
	v_pk_fma_f32 v[82:83], v[62:63], v[106:107], v[82:83] neg_lo:[1,0,0] neg_hi:[1,0,0]
	ds_read_b128 v[60:63], v28 offset:25088
	s_waitcnt lgkmcnt(11)
; #define LAS __attribute__((address_space(3)))
; __device__ __forceinline__ bf16_t f2bf(float f) { return (bf16_t)(pk2(f, f) & 0xFFFFu); }
; __device__ NOINL void g1_phase(const LAS Params* lp, int l, LAS unsigned char* lds) {
;     ...
;             for (int i = 0; i < 64; ++i) {
;                 float s0 = (i == lane) ? 1.f : 0.f, s1 = 0.f, s2 = 0.f, s3 = 0.f;
; #pragma unroll
;                 for (int j4 = 0; j4 < (i + 3) / 4; ++j4) {
;                     const f32x4 lv = *(const LAS f32x4*)(Ld + i * 64 + j4 * 4);
;                     if (j4 * 4 + 0 < i) s0 -= lv[0] * xv[j4 * 4 + 0];
;                     if (j4 * 4 + 1 < i) s1 -= lv[1] * xv[j4 * 4 + 1];
;                     if (j4 * 4 + 2 < i) s2 -= lv[2] * xv[j4 * 4 + 2];
;                     if (j4 * 4 + 3 < i) s3 -= lv[3] * xv[j4 * 4 + 3];
;                 }
;                 xv[i] = (s0 + s1) + (s2 + s3);
;             }
;             bf16_t* Tg = p.Tbuf + ((((size_t)b * 4 + h) * 36 + c3 * 3 + s) * 2 + dir) * 4096;
; #pragma unroll
;             for (int i = 0; i < 64; ++i) Tg[i * 64 + lane] = f2bf(xv[i]);
	v_pk_fma_f32 v[80:81], v[64:65], v[108:109], v[80:81] neg_lo:[1,0,0] neg_hi:[1,0,0]
	v_pk_fma_f32 v[82:83], v[66:67], v[110:111], v[82:83] neg_lo:[1,0,0] neg_hi:[1,0,0]
	ds_read_b128 v[64:67], v28 offset:25104
	s_waitcnt lgkmcnt(11)
	v_pk_fma_f32 v[80:81], v[68:69], v[112:113], v[80:81] neg_lo:[1,0,0] neg_hi:[1,0,0]
	v_pk_fma_f32 v[82:83], v[70:71], v[114:115], v[82:83] neg_lo:[1,0,0] neg_hi:[1,0,0]
	ds_read_b128 v[68:71], v28 offset:25120
	s_waitcnt lgkmcnt(11)
	v_pk_fma_f32 v[80:81], v[72:73], v[116:117], v[80:81] neg_lo:[1,0,0] neg_hi:[1,0,0]
	v_pk_fma_f32 v[82:83], v[74:75], v[118:119], v[82:83] neg_lo:[1,0,0] neg_hi:[1,0,0]
	ds_read_b128 v[72:75], v28 offset:25136
	s_waitcnt lgkmcnt(11)
	v_pk_fma_f32 v[80:81], v[76:77], v[120:121], v[80:81] neg_lo:[1,0,0] neg_hi:[1,0,0]
	v_pk_fma_f32 v[82:83], v[78:79], v[122:123], v[82:83] neg_lo:[1,0,0] neg_hi:[1,0,0]
	ds_read_b128 v[76:79], v28 offset:25152
	v_add_f32_e32 v80, v80, v81
	v_add_f32_e32 v82, v82, v83
	v_add_f32_e32 v124, v80, v82
	v_cvt_pk_bf16_f32 v89, v124, v124
	global_store_short v[18:19], v89, off offset:3072
	v_cmp_eq_u32_e64 s[56:57], 25, v88
	s_waitcnt lgkmcnt(11)
	s_nop 0
	v_cndmask_b32_e64 v84, 0, 1.0, s[56:57]
	v_fma_f32 v84, -v100, v32, v84
	v_fma_f32 v85, -v33, v101, 0
	v_fma_f32 v86, -v34, v102, 0
	v_fma_f32 v87, -v35, v103, 0
	ds_read_b128 v[32:35], v28 offset:25168
	s_waitcnt lgkmcnt(11)
	v_pk_fma_f32 v[84:85], v[36:37], v[104:105], v[84:85] neg_lo:[1,0,0] neg_hi:[1,0,0]
	v_pk_fma_f32 v[86:87], v[38:39], v[106:107], v[86:87] neg_lo:[1,0,0] neg_hi:[1,0,0]
	ds_read_b128 v[36:39], v28 offset:25184
	s_waitcnt lgkmcnt(11)
	v_pk_fma_f32 v[84:85], v[40:41], v[108:109], v[84:85] neg_lo:[1,0,0] neg_hi:[1,0,0]
	v_pk_fma_f32 v[86:87], v[42:43], v[110:111], v[86:87] neg_lo:[1,0,0] neg_hi:[1,0,0]
	ds_read_b128 v[40:43], v28 offset:25344
	s_waitcnt lgkmcnt(11)
	v_pk_fma_f32 v[84:85], v[44:45], v[112:113], v[84:85] neg_lo:[1,0,0] neg_hi:[1,0,0]
	v_pk_fma_f32 v[86:87], v[46:47], v[114:115], v[86:87] neg_lo:[1,0,0] neg_hi:[1,0,0]
	ds_read_b128 v[44:47], v28 offset:25360
	s_waitcnt lgkmcnt(11)
	v_pk_fma_f32 v[84:85], v[48:49], v[116:117], v[84:85] neg_lo:[1,0,0] neg_hi:[1,0,0]
	v_pk_fma_f32 v[86:87], v[50:51], v[118:119], v[86:87] neg_lo:[1,0,0] neg_hi:[1,0,0]
	ds_read_b128 v[48:51], v28 offset:25376
	s_waitcnt lgkmcnt(11)
	v_pk_fma_f32 v[84:85], v[52:53], v[120:121], v[84:85] neg_lo:[1,0,0] neg_hi:[1,0,0]
	v_pk_fma_f32 v[86:87], v[54:55], v[122:123], v[86:87] neg_lo:[1,0,0] neg_hi:[1,0,0]
	ds_read_b128 v[52:55], v28 offset:25392
	s_waitcnt lgkmcnt(11)
	v_fma_f32 v84, -v56, v124, v84
	ds_read_b128 v[56:59], v28 offset:25408
	v_add_f32_e32 v84, v84, v85
	v_add_f32_e32 v86, v86, v87
	v_add_f32_e32 v125, v84, v86
	v_cvt_pk_bf16_f32 v90, v125, v125
	global_store_short v[18:19], v90, off offset:3200
	v_cmp_eq_u32_e64 s[56:57], 26, v88
	s_waitcnt lgkmcnt(11)
	s_nop 0
	v_cndmask_b32_e64 v80, 0, 1.0, s[56:57]
	v_fma_f32 v80, -v100, v60, v80
	v_fma_f32 v81, -v61, v101, 0
	v_fma_f32 v82, -v62, v102, 0
	v_fma_f32 v83, -v63, v103, 0
	ds_read_b128 v[60:63], v28 offset:25424
	s_waitcnt lgkmcnt(11)
	v_pk_fma_f32 v[80:81], v[64:65], v[104:105], v[80:81] neg_lo:[1,0,0] neg_hi:[1,0,0]
	v_pk_fma_f32 v[82:83], v[66:67], v[106:107], v[82:83] neg_lo:[1,0,0] neg_hi:[1,0,0]
	ds_read_b128 v[64:67], v28 offset:25440
	s_waitcnt lgkmcnt(11)
	v_pk_fma_f32 v[80:81], v[68:69], v[108:109], v[80:81] neg_lo:[1,0,0] neg_hi:[1,0,0]
	v_pk_fma_f32 v[82:83], v[70:71], v[110:111], v[82:83] neg_lo:[1,0,0] neg_hi:[1,0,0]
	ds_read_b128 v[68:71], v28 offset:25600
	s_waitcnt lgkmcnt(11)
	v_pk_fma_f32 v[80:81], v[72:73], v[112:113], v[80:81] neg_lo:[1,0,0] neg_hi:[1,0,0]
	v_pk_fma_f32 v[82:83], v[74:75], v[114:115], v[82:83] neg_lo:[1,0,0] neg_hi:[1,0,0]
	ds_read_b128 v[72:75], v28 offset:25616
	s_waitcnt lgkmcnt(11)
	v_pk_fma_f32 v[80:81], v[76:77], v[116:117], v[80:81] neg_lo:[1,0,0] neg_hi:[1,0,0]
	v_pk_fma_f32 v[82:83], v[78:79], v[118:119], v[82:83] neg_lo:[1,0,0] neg_hi:[1,0,0]
	ds_read_b128 v[76:79], v28 offset:25632
	s_waitcnt lgkmcnt(11)
	v_pk_fma_f32 v[80:81], v[32:33], v[120:121], v[80:81] neg_lo:[1,0,0] neg_hi:[1,0,0]
	v_pk_fma_f32 v[82:83], v[34:35], v[122:123], v[82:83] neg_lo:[1,0,0] neg_hi:[1,0,0]
	ds_read_b128 v[32:35], v28 offset:25648
	s_waitcnt lgkmcnt(11)
	v_pk_fma_f32 v[80:81], v[36:37], v[124:125], v[80:81] neg_lo:[1,0,0] neg_hi:[1,0,0]
	ds_read_b128 v[36:39], v28 offset:25664
	v_add_f32_e32 v80, v80, v81
	v_add_f32_e32 v82, v82, v83
	v_add_f32_e32 v126, v80, v82
	v_cvt_pk_bf16_f32 v91, v126, v126
	global_store_short v[18:19], v91, off offset:3328
	v_cmp_eq_u32_e64 s[56:57], 27, v88
	s_waitcnt lgkmcnt(11)
	s_nop 0
	v_cndmask_b32_e64 v84, 0, 1.0, s[56:57]
	v_fma_f32 v84, -v100, v40, v84
	v_fma_f32 v85, -v41, v101, 0
	v_fma_f32 v86, -v42, v102, 0
	v_fma_f32 v87, -v43, v103, 0
	ds_read_b128 v[40:43], v28 offset:25680
	s_waitcnt lgkmcnt(11)
	v_pk_fma_f32 v[84:85], v[44:45], v[104:105], v[84:85] neg_lo:[1,0,0] neg_hi:[1,0,0]
	v_pk_fma_f32 v[86:87], v[46:47], v[106:107], v[86:87] neg_lo:[1,0,0] neg_hi:[1,0,0]
	ds_read_b128 v[44:47], v28 offset:25696
	s_waitcnt lgkmcnt(11)
	v_pk_fma_f32 v[84:85], v[48:49], v[108:109], v[84:85] neg_lo:[1,0,0] neg_hi:[1,0,0]
	v_pk_fma_f32 v[86:87], v[50:51], v[110:111], v[86:87] neg_lo:[1,0,0] neg_hi:[1,0,0]
	ds_read_b128 v[48:51], v28 offset:25856
	s_waitcnt lgkmcnt(11)
	v_pk_fma_f32 v[84:85], v[52:53], v[112:113], v[84:85] neg_lo:[1,0,0] neg_hi:[1,0,0]
	v_pk_fma_f32 v[86:87], v[54:55], v[114:115], v[86:87] neg_lo:[1,0,0] neg_hi:[1,0,0]
	ds_read_b128 v[52:55], v28 offset:25872
	s_waitcnt lgkmcnt(11)
; #define LAS __attribute__((address_space(3)))
; __device__ __forceinline__ bf16_t f2bf(float f) { return (bf16_t)(pk2(f, f) & 0xFFFFu); }
; __device__ NOINL void g1_phase(const LAS Params* lp, int l, LAS unsigned char* lds) {
;     ...
;             for (int i = 0; i < 64; ++i) {
;                 float s0 = (i == lane) ? 1.f : 0.f, s1 = 0.f, s2 = 0.f, s3 = 0.f;
; #pragma unroll
;                 for (int j4 = 0; j4 < (i + 3) / 4; ++j4) {
;                     const f32x4 lv = *(const LAS f32x4*)(Ld + i * 64 + j4 * 4);
;                     if (j4 * 4 + 0 < i) s0 -= lv[0] * xv[j4 * 4 + 0];
;                     if (j4 * 4 + 1 < i) s1 -= lv[1] * xv[j4 * 4 + 1];
;                     if (j4 * 4 + 2 < i) s2 -= lv[2] * xv[j4 * 4 + 2];
;                     if (j4 * 4 + 3 < i) s3 -= lv[3] * xv[j4 * 4 + 3];
;                 }
;                 xv[i] = (s0 + s1) + (s2 + s3);
;             }
;             bf16_t* Tg = p.Tbuf + ((((size_t)b * 4 + h) * 36 + c3 * 3 + s) * 2 + dir) * 4096;
; #pragma unroll
;             for (int i = 0; i < 64; ++i) Tg[i * 64 + lane] = f2bf(xv[i]);
	v_pk_fma_f32 v[84:85], v[56:57], v[116:117], v[84:85] neg_lo:[1,0,0] neg_hi:[1,0,0]
	v_pk_fma_f32 v[86:87], v[58:59], v[118:119], v[86:87] neg_lo:[1,0,0] neg_hi:[1,0,0]
	ds_read_b128 v[56:59], v28 offset:25888
	s_waitcnt lgkmcnt(11)
	v_pk_fma_f32 v[84:85], v[60:61], v[120:121], v[84:85] neg_lo:[1,0,0] neg_hi:[1,0,0]
	v_pk_fma_f32 v[86:87], v[62:63], v[122:123], v[86:87] neg_lo:[1,0,0] neg_hi:[1,0,0]
	ds_read_b128 v[60:63], v28 offset:25904
	s_waitcnt lgkmcnt(11)
	v_pk_fma_f32 v[84:85], v[64:65], v[124:125], v[84:85] neg_lo:[1,0,0] neg_hi:[1,0,0]
	v_fma_f32 v86, -v66, v126, v86
	ds_read_b128 v[64:67], v28 offset:25920
	v_add_f32_e32 v84, v84, v85
	v_add_f32_e32 v86, v86, v87
	v_add_f32_e32 v127, v84, v86
	v_cvt_pk_bf16_f32 v92, v127, v127
	global_store_short v[18:19], v92, off offset:3456
	v_cmp_eq_u32_e64 s[56:57], 28, v88
	s_waitcnt lgkmcnt(11)
	s_nop 0
	v_cndmask_b32_e64 v80, 0, 1.0, s[56:57]
	v_fma_f32 v80, -v100, v68, v80
	v_fma_f32 v81, -v69, v101, 0
	v_fma_f32 v82, -v70, v102, 0
	v_fma_f32 v83, -v71, v103, 0
	ds_read_b128 v[68:71], v28 offset:25936
	s_waitcnt lgkmcnt(11)
	v_pk_fma_f32 v[80:81], v[72:73], v[104:105], v[80:81] neg_lo:[1,0,0] neg_hi:[1,0,0]
	v_pk_fma_f32 v[82:83], v[74:75], v[106:107], v[82:83] neg_lo:[1,0,0] neg_hi:[1,0,0]
	ds_read_b128 v[72:75], v28 offset:25952
	s_waitcnt lgkmcnt(11)
	v_pk_fma_f32 v[80:81], v[76:77], v[108:109], v[80:81] neg_lo:[1,0,0] neg_hi:[1,0,0]
	v_pk_fma_f32 v[82:83], v[78:79], v[110:111], v[82:83] neg_lo:[1,0,0] neg_hi:[1,0,0]
	ds_read_b128 v[76:79], v28 offset:25968
	s_waitcnt lgkmcnt(11)
	v_pk_fma_f32 v[80:81], v[32:33], v[112:113], v[80:81] neg_lo:[1,0,0] neg_hi:[1,0,0]
	v_pk_fma_f32 v[82:83], v[34:35], v[114:115], v[82:83] neg_lo:[1,0,0] neg_hi:[1,0,0]
	ds_read_b128 v[32:35], v28 offset:26112
	s_waitcnt lgkmcnt(11)
	v_pk_fma_f32 v[80:81], v[36:37], v[116:117], v[80:81] neg_lo:[1,0,0] neg_hi:[1,0,0]
	v_pk_fma_f32 v[82:83], v[38:39], v[118:119], v[82:83] neg_lo:[1,0,0] neg_hi:[1,0,0]
	ds_read_b128 v[36:39], v28 offset:26128
	s_waitcnt lgkmcnt(11)
	v_pk_fma_f32 v[80:81], v[40:41], v[120:121], v[80:81] neg_lo:[1,0,0] neg_hi:[1,0,0]
	v_pk_fma_f32 v[82:83], v[42:43], v[122:123], v[82:83] neg_lo:[1,0,0] neg_hi:[1,0,0]
	ds_read_b128 v[40:43], v28 offset:26144
	s_waitcnt lgkmcnt(11)
	v_pk_fma_f32 v[80:81], v[44:45], v[124:125], v[80:81] neg_lo:[1,0,0] neg_hi:[1,0,0]
	v_pk_fma_f32 v[82:83], v[46:47], v[126:127], v[82:83] neg_lo:[1,0,0] neg_hi:[1,0,0]
	ds_read_b128 v[44:47], v28 offset:26160
	v_add_f32_e32 v80, v80, v81
	v_add_f32_e32 v82, v82, v83
	v_add_f32_e32 v128, v80, v82
	v_cvt_pk_bf16_f32 v89, v128, v128
	global_store_short v[18:19], v89, off offset:3584
	v_cmp_eq_u32_e64 s[56:57], 29, v88
	s_waitcnt lgkmcnt(11)
	s_nop 0
	v_cndmask_b32_e64 v84, 0, 1.0, s[56:57]
	v_fma_f32 v84, -v100, v48, v84
	v_fma_f32 v85, -v49, v101, 0
	v_fma_f32 v86, -v50, v102, 0
	v_fma_f32 v87, -v51, v103, 0
	ds_read_b128 v[48:51], v28 offset:26176
	s_waitcnt lgkmcnt(11)
	v_pk_fma_f32 v[84:85], v[52:53], v[104:105], v[84:85] neg_lo:[1,0,0] neg_hi:[1,0,0]
	v_pk_fma_f32 v[86:87], v[54:55], v[106:107], v[86:87] neg_lo:[1,0,0] neg_hi:[1,0,0]
	ds_read_b128 v[52:55], v28 offset:26192
	s_waitcnt lgkmcnt(11)
	v_pk_fma_f32 v[84:85], v[56:57], v[108:109], v[84:85] neg_lo:[1,0,0] neg_hi:[1,0,0]
	v_pk_fma_f32 v[86:87], v[58:59], v[110:111], v[86:87] neg_lo:[1,0,0] neg_hi:[1,0,0]
	ds_read_b128 v[56:59], v28 offset:26208
	s_waitcnt lgkmcnt(11)
	v_pk_fma_f32 v[84:85], v[60:61], v[112:113], v[84:85] neg_lo:[1,0,0] neg_hi:[1,0,0]
	v_pk_fma_f32 v[86:87], v[62:63], v[114:115], v[86:87] neg_lo:[1,0,0] neg_hi:[1,0,0]
	ds_read_b128 v[60:63], v28 offset:26224
	s_waitcnt lgkmcnt(11)
	v_pk_fma_f32 v[84:85], v[64:65], v[116:117], v[84:85] neg_lo:[1,0,0] neg_hi:[1,0,0]
	v_pk_fma_f32 v[86:87], v[66:67], v[118:119], v[86:87] neg_lo:[1,0,0] neg_hi:[1,0,0]
	ds_read_b128 v[64:67], v28 offset:26368
	s_waitcnt lgkmcnt(11)
	v_pk_fma_f32 v[84:85], v[68:69], v[120:121], v[84:85] neg_lo:[1,0,0] neg_hi:[1,0,0]
	v_pk_fma_f32 v[86:87], v[70:71], v[122:123], v[86:87] neg_lo:[1,0,0] neg_hi:[1,0,0]
	ds_read_b128 v[68:71], v28 offset:26384
	s_waitcnt lgkmcnt(11)
	v_pk_fma_f32 v[84:85], v[72:73], v[124:125], v[84:85] neg_lo:[1,0,0] neg_hi:[1,0,0]
	v_pk_fma_f32 v[86:87], v[74:75], v[126:127], v[86:87] neg_lo:[1,0,0] neg_hi:[1,0,0]
	ds_read_b128 v[72:75], v28 offset:26400
	s_waitcnt lgkmcnt(11)
	v_fma_f32 v84, -v76, v128, v84
	ds_read_b128 v[76:79], v28 offset:26416
	v_add_f32_e32 v84, v84, v85
	v_add_f32_e32 v86, v86, v87
	v_add_f32_e32 v129, v84, v86
	v_cvt_pk_bf16_f32 v90, v129, v129
	global_store_short v[18:19], v90, off offset:3712
	v_cmp_eq_u32_e64 s[56:57], 30, v88
	s_waitcnt lgkmcnt(11)
	s_nop 0
	v_cndmask_b32_e64 v80, 0, 1.0, s[56:57]
	v_fma_f32 v80, -v100, v32, v80
	v_fma_f32 v81, -v33, v101, 0
	v_fma_f32 v82, -v34, v102, 0
	v_fma_f32 v83, -v35, v103, 0
	ds_read_b128 v[32:35], v28 offset:26432
	s_waitcnt lgkmcnt(11)
	v_pk_fma_f32 v[80:81], v[36:37], v[104:105], v[80:81] neg_lo:[1,0,0] neg_hi:[1,0,0]
	v_pk_fma_f32 v[82:83], v[38:39], v[106:107], v[82:83] neg_lo:[1,0,0] neg_hi:[1,0,0]
	ds_read_b128 v[36:39], v28 offset:26448
	s_waitcnt lgkmcnt(11)
	v_pk_fma_f32 v[80:81], v[40:41], v[108:109], v[80:81] neg_lo:[1,0,0] neg_hi:[1,0,0]
	v_pk_fma_f32 v[82:83], v[42:43], v[110:111], v[82:83] neg_lo:[1,0,0] neg_hi:[1,0,0]
	ds_read_b128 v[40:43], v28 offset:26464
	s_waitcnt lgkmcnt(11)
	v_pk_fma_f32 v[80:81], v[44:45], v[112:113], v[80:81] neg_lo:[1,0,0] neg_hi:[1,0,0]
	v_pk_fma_f32 v[82:83], v[46:47], v[114:115], v[82:83] neg_lo:[1,0,0] neg_hi:[1,0,0]
	ds_read_b128 v[44:47], v28 offset:26480
	s_waitcnt lgkmcnt(11)
; #define LAS __attribute__((address_space(3)))
; __device__ __forceinline__ bf16_t f2bf(float f) { return (bf16_t)(pk2(f, f) & 0xFFFFu); }
; __device__ NOINL void g1_phase(const LAS Params* lp, int l, LAS unsigned char* lds) {
;     ...
;             for (int i = 0; i < 64; ++i) {
;                 float s0 = (i == lane) ? 1.f : 0.f, s1 = 0.f, s2 = 0.f, s3 = 0.f;
; #pragma unroll
;                 for (int j4 = 0; j4 < (i + 3) / 4; ++j4) {
;                     const f32x4 lv = *(const LAS f32x4*)(Ld + i * 64 + j4 * 4);
;                     if (j4 * 4 + 0 < i) s0 -= lv[0] * xv[j4 * 4 + 0];
;                     if (j4 * 4 + 1 < i) s1 -= lv[1] * xv[j4 * 4 + 1];
;                     if (j4 * 4 + 2 < i) s2 -= lv[2] * xv[j4 * 4 + 2];
;                     if (j4 * 4 + 3 < i) s3 -= lv[3] * xv[j4 * 4 + 3];
;                 }
;                 xv[i] = (s0 + s1) + (s2 + s3);
;             }
;             bf16_t* Tg = p.Tbuf + ((((size_t)b * 4 + h) * 36 + c3 * 3 + s) * 2 + dir) * 4096;
; #pragma unroll
;             for (int i = 0; i < 64; ++i) Tg[i * 64 + lane] = f2bf(xv[i]);
	v_pk_fma_f32 v[80:81], v[48:49], v[116:117], v[80:81] neg_lo:[1,0,0] neg_hi:[1,0,0]
	v_pk_fma_f32 v[82:83], v[50:51], v[118:119], v[82:83] neg_lo:[1,0,0] neg_hi:[1,0,0]
	ds_read_b128 v[48:51], v28 offset:26624
	s_waitcnt lgkmcnt(11)
	v_pk_fma_f32 v[80:81], v[52:53], v[120:121], v[80:81] neg_lo:[1,0,0] neg_hi:[1,0,0]
	v_pk_fma_f32 v[82:83], v[54:55], v[122:123], v[82:83] neg_lo:[1,0,0] neg_hi:[1,0,0]
	ds_read_b128 v[52:55], v28 offset:26640
	s_waitcnt lgkmcnt(11)
	v_pk_fma_f32 v[80:81], v[56:57], v[124:125], v[80:81] neg_lo:[1,0,0] neg_hi:[1,0,0]
	v_pk_fma_f32 v[82:83], v[58:59], v[126:127], v[82:83] neg_lo:[1,0,0] neg_hi:[1,0,0]
	ds_read_b128 v[56:59], v28 offset:26656
	s_waitcnt lgkmcnt(11)
	v_pk_fma_f32 v[80:81], v[60:61], v[128:129], v[80:81] neg_lo:[1,0,0] neg_hi:[1,0,0]
	ds_read_b128 v[60:63], v28 offset:26672
	v_add_f32_e32 v80, v80, v81
	v_add_f32_e32 v82, v82, v83
	v_add_f32_e32 v130, v80, v82
	v_cvt_pk_bf16_f32 v91, v130, v130
	global_store_short v[18:19], v91, off offset:3840
	v_cmp_eq_u32_e64 s[56:57], 31, v88
	s_waitcnt lgkmcnt(11)
	s_nop 0
	v_cndmask_b32_e64 v84, 0, 1.0, s[56:57]
	v_fma_f32 v84, -v100, v64, v84
	v_fma_f32 v85, -v65, v101, 0
	v_fma_f32 v86, -v66, v102, 0
	v_fma_f32 v87, -v67, v103, 0
	ds_read_b128 v[64:67], v28 offset:26688
	s_waitcnt lgkmcnt(11)
	v_pk_fma_f32 v[84:85], v[68:69], v[104:105], v[84:85] neg_lo:[1,0,0] neg_hi:[1,0,0]
	v_pk_fma_f32 v[86:87], v[70:71], v[106:107], v[86:87] neg_lo:[1,0,0] neg_hi:[1,0,0]
	ds_read_b128 v[68:71], v28 offset:26704
	s_waitcnt lgkmcnt(11)
	v_pk_fma_f32 v[84:85], v[72:73], v[108:109], v[84:85] neg_lo:[1,0,0] neg_hi:[1,0,0]
	v_pk_fma_f32 v[86:87], v[74:75], v[110:111], v[86:87] neg_lo:[1,0,0] neg_hi:[1,0,0]
	ds_read_b128 v[72:75], v28 offset:26720
	s_waitcnt lgkmcnt(11)
	v_pk_fma_f32 v[84:85], v[76:77], v[112:113], v[84:85] neg_lo:[1,0,0] neg_hi:[1,0,0]
	v_pk_fma_f32 v[86:87], v[78:79], v[114:115], v[86:87] neg_lo:[1,0,0] neg_hi:[1,0,0]
	ds_read_b128 v[76:79], v28 offset:26736
	s_waitcnt lgkmcnt(11)
	v_pk_fma_f32 v[84:85], v[32:33], v[116:117], v[84:85] neg_lo:[1,0,0] neg_hi:[1,0,0]
	v_pk_fma_f32 v[86:87], v[34:35], v[118:119], v[86:87] neg_lo:[1,0,0] neg_hi:[1,0,0]
	ds_read_b128 v[32:35], v28 offset:26880
	s_waitcnt lgkmcnt(11)
	v_pk_fma_f32 v[84:85], v[36:37], v[120:121], v[84:85] neg_lo:[1,0,0] neg_hi:[1,0,0]
	v_pk_fma_f32 v[86:87], v[38:39], v[122:123], v[86:87] neg_lo:[1,0,0] neg_hi:[1,0,0]
	ds_read_b128 v[36:39], v28 offset:26896
	s_waitcnt lgkmcnt(11)
	v_pk_fma_f32 v[84:85], v[40:41], v[124:125], v[84:85] neg_lo:[1,0,0] neg_hi:[1,0,0]
	v_pk_fma_f32 v[86:87], v[42:43], v[126:127], v[86:87] neg_lo:[1,0,0] neg_hi:[1,0,0]
	ds_read_b128 v[40:43], v28 offset:26912
	s_waitcnt lgkmcnt(11)
	v_pk_fma_f32 v[84:85], v[44:45], v[128:129], v[84:85] neg_lo:[1,0,0] neg_hi:[1,0,0]
	v_fma_f32 v86, -v46, v130, v86
	ds_read_b128 v[44:47], v28 offset:26928
	v_add_f32_e32 v84, v84, v85
	v_add_f32_e32 v86, v86, v87
	v_add_f32_e32 v131, v84, v86
	v_cvt_pk_bf16_f32 v92, v131, v131
	global_store_short v[18:19], v92, off offset:3968
	v_cmp_eq_u32_e64 s[56:57], 32, v88
	s_waitcnt lgkmcnt(11)
	s_nop 0
	v_cndmask_b32_e64 v80, 0, 1.0, s[56:57]
	v_fma_f32 v80, -v100, v48, v80
	v_fma_f32 v81, -v49, v101, 0
	v_fma_f32 v82, -v50, v102, 0
	v_fma_f32 v83, -v51, v103, 0
	ds_read_b128 v[48:51], v28 offset:26944
	s_waitcnt lgkmcnt(11)
	v_pk_fma_f32 v[80:81], v[52:53], v[104:105], v[80:81] neg_lo:[1,0,0] neg_hi:[1,0,0]
	v_pk_fma_f32 v[82:83], v[54:55], v[106:107], v[82:83] neg_lo:[1,0,0] neg_hi:[1,0,0]
	ds_read_b128 v[52:55], v28 offset:26960
	s_waitcnt lgkmcnt(11)
	v_pk_fma_f32 v[80:81], v[56:57], v[108:109], v[80:81] neg_lo:[1,0,0] neg_hi:[1,0,0]
	v_pk_fma_f32 v[82:83], v[58:59], v[110:111], v[82:83] neg_lo:[1,0,0] neg_hi:[1,0,0]
	ds_read_b128 v[56:59], v28 offset:26976
	s_waitcnt lgkmcnt(11)
	v_pk_fma_f32 v[80:81], v[60:61], v[112:113], v[80:81] neg_lo:[1,0,0] neg_hi:[1,0,0]
	v_pk_fma_f32 v[82:83], v[62:63], v[114:115], v[82:83] neg_lo:[1,0,0] neg_hi:[1,0,0]
	ds_read_b128 v[60:63], v28 offset:26992
	s_waitcnt lgkmcnt(11)
	v_pk_fma_f32 v[80:81], v[64:65], v[116:117], v[80:81] neg_lo:[1,0,0] neg_hi:[1,0,0]
	v_pk_fma_f32 v[82:83], v[66:67], v[118:119], v[82:83] neg_lo:[1,0,0] neg_hi:[1,0,0]
	ds_read_b128 v[64:67], v28 offset:27008
	s_waitcnt lgkmcnt(11)
	v_pk_fma_f32 v[80:81], v[68:69], v[120:121], v[80:81] neg_lo:[1,0,0] neg_hi:[1,0,0]
	v_pk_fma_f32 v[82:83], v[70:71], v[122:123], v[82:83] neg_lo:[1,0,0] neg_hi:[1,0,0]
	ds_read_b128 v[68:71], v28 offset:27136
	s_waitcnt lgkmcnt(11)
	v_pk_fma_f32 v[80:81], v[72:73], v[124:125], v[80:81] neg_lo:[1,0,0] neg_hi:[1,0,0]
	v_pk_fma_f32 v[82:83], v[74:75], v[126:127], v[82:83] neg_lo:[1,0,0] neg_hi:[1,0,0]
	ds_read_b128 v[72:75], v28 offset:27152
	s_waitcnt lgkmcnt(11)
	v_pk_fma_f32 v[80:81], v[76:77], v[128:129], v[80:81] neg_lo:[1,0,0] neg_hi:[1,0,0]
	v_pk_fma_f32 v[82:83], v[78:79], v[130:131], v[82:83] neg_lo:[1,0,0] neg_hi:[1,0,0]
	ds_read_b128 v[76:79], v28 offset:27168
	v_add_f32_e32 v80, v80, v81
	v_add_f32_e32 v82, v82, v83
	v_add_f32_e32 v132, v80, v82
	v_cvt_pk_bf16_f32 v89, v132, v132
	global_store_short v[8:9], v89, off
	v_cmp_eq_u32_e64 s[56:57], 33, v88
	s_waitcnt lgkmcnt(11)
	s_nop 0
	v_cndmask_b32_e64 v84, 0, 1.0, s[56:57]
	v_fma_f32 v84, -v100, v32, v84
	v_fma_f32 v85, -v33, v101, 0
	v_fma_f32 v86, -v34, v102, 0
	v_fma_f32 v87, -v35, v103, 0
	ds_read_b128 v[32:35], v28 offset:27184
	s_waitcnt lgkmcnt(11)
	v_pk_fma_f32 v[84:85], v[36:37], v[104:105], v[84:85] neg_lo:[1,0,0] neg_hi:[1,0,0]
	v_pk_fma_f32 v[86:87], v[38:39], v[106:107], v[86:87] neg_lo:[1,0,0] neg_hi:[1,0,0]
	ds_read_b128 v[36:39], v28 offset:27200
	s_waitcnt lgkmcnt(11)
; #define LAS __attribute__((address_space(3)))
; __device__ __forceinline__ bf16_t f2bf(float f) { return (bf16_t)(pk2(f, f) & 0xFFFFu); }
; __device__ NOINL void g1_phase(const LAS Params* lp, int l, LAS unsigned char* lds) {
;     ...
;             for (int i = 0; i < 64; ++i) {
;                 float s0 = (i == lane) ? 1.f : 0.f, s1 = 0.f, s2 = 0.f, s3 = 0.f;
; #pragma unroll
;                 for (int j4 = 0; j4 < (i + 3) / 4; ++j4) {
;                     const f32x4 lv = *(const LAS f32x4*)(Ld + i * 64 + j4 * 4);
;                     if (j4 * 4 + 0 < i) s0 -= lv[0] * xv[j4 * 4 + 0];
;                     if (j4 * 4 + 1 < i) s1 -= lv[1] * xv[j4 * 4 + 1];
;                     if (j4 * 4 + 2 < i) s2 -= lv[2] * xv[j4 * 4 + 2];
;                     if (j4 * 4 + 3 < i) s3 -= lv[3] * xv[j4 * 4 + 3];
;                 }
;                 xv[i] = (s0 + s1) + (s2 + s3);
;             }
;             bf16_t* Tg = p.Tbuf + ((((size_t)b * 4 + h) * 36 + c3 * 3 + s) * 2 + dir) * 4096;
; #pragma unroll
;             for (int i = 0; i < 64; ++i) Tg[i * 64 + lane] = f2bf(xv[i]);
	v_pk_fma_f32 v[84:85], v[40:41], v[108:109], v[84:85] neg_lo:[1,0,0] neg_hi:[1,0,0]
	v_pk_fma_f32 v[86:87], v[42:43], v[110:111], v[86:87] neg_lo:[1,0,0] neg_hi:[1,0,0]
	ds_read_b128 v[40:43], v28 offset:27216
	s_waitcnt lgkmcnt(11)
	v_pk_fma_f32 v[84:85], v[44:45], v[112:113], v[84:85] neg_lo:[1,0,0] neg_hi:[1,0,0]
	v_pk_fma_f32 v[86:87], v[46:47], v[114:115], v[86:87] neg_lo:[1,0,0] neg_hi:[1,0,0]
	ds_read_b128 v[44:47], v28 offset:27232
	s_waitcnt lgkmcnt(11)
	v_pk_fma_f32 v[84:85], v[48:49], v[116:117], v[84:85] neg_lo:[1,0,0] neg_hi:[1,0,0]
	v_pk_fma_f32 v[86:87], v[50:51], v[118:119], v[86:87] neg_lo:[1,0,0] neg_hi:[1,0,0]
	ds_read_b128 v[48:51], v28 offset:27248
	s_waitcnt lgkmcnt(11)
	v_pk_fma_f32 v[84:85], v[52:53], v[120:121], v[84:85] neg_lo:[1,0,0] neg_hi:[1,0,0]
	v_pk_fma_f32 v[86:87], v[54:55], v[122:123], v[86:87] neg_lo:[1,0,0] neg_hi:[1,0,0]
	ds_read_b128 v[52:55], v28 offset:27264
	s_waitcnt lgkmcnt(11)
	v_pk_fma_f32 v[84:85], v[56:57], v[124:125], v[84:85] neg_lo:[1,0,0] neg_hi:[1,0,0]
	v_pk_fma_f32 v[86:87], v[58:59], v[126:127], v[86:87] neg_lo:[1,0,0] neg_hi:[1,0,0]
	ds_read_b128 v[56:59], v28 offset:27392
	s_waitcnt lgkmcnt(11)
	v_pk_fma_f32 v[84:85], v[60:61], v[128:129], v[84:85] neg_lo:[1,0,0] neg_hi:[1,0,0]
	v_pk_fma_f32 v[86:87], v[62:63], v[130:131], v[86:87] neg_lo:[1,0,0] neg_hi:[1,0,0]
	ds_read_b128 v[60:63], v28 offset:27408
	s_waitcnt lgkmcnt(11)
	v_fma_f32 v84, -v64, v132, v84
	ds_read_b128 v[64:67], v28 offset:27424
	v_add_f32_e32 v84, v84, v85
	v_add_f32_e32 v86, v86, v87
	v_add_f32_e32 v133, v84, v86
	v_cvt_pk_bf16_f32 v90, v133, v133
	global_store_short v[8:9], v90, off offset:128
	v_cmp_eq_u32_e64 s[56:57], 34, v88
	s_waitcnt lgkmcnt(11)
	s_nop 0
	v_cndmask_b32_e64 v80, 0, 1.0, s[56:57]
	v_fma_f32 v80, -v100, v68, v80
	v_fma_f32 v81, -v69, v101, 0
	v_fma_f32 v82, -v70, v102, 0
	v_fma_f32 v83, -v71, v103, 0
	ds_read_b128 v[68:71], v28 offset:27440
	s_waitcnt lgkmcnt(11)
	v_pk_fma_f32 v[80:81], v[72:73], v[104:105], v[80:81] neg_lo:[1,0,0] neg_hi:[1,0,0]
	v_pk_fma_f32 v[82:83], v[74:75], v[106:107], v[82:83] neg_lo:[1,0,0] neg_hi:[1,0,0]
	ds_read_b128 v[72:75], v28 offset:27456
	s_waitcnt lgkmcnt(11)
	v_pk_fma_f32 v[80:81], v[76:77], v[108:109], v[80:81] neg_lo:[1,0,0] neg_hi:[1,0,0]
	v_pk_fma_f32 v[82:83], v[78:79], v[110:111], v[82:83] neg_lo:[1,0,0] neg_hi:[1,0,0]
	ds_read_b128 v[76:79], v28 offset:27472
	s_waitcnt lgkmcnt(11)
	v_pk_fma_f32 v[80:81], v[32:33], v[112:113], v[80:81] neg_lo:[1,0,0] neg_hi:[1,0,0]
	v_pk_fma_f32 v[82:83], v[34:35], v[114:115], v[82:83] neg_lo:[1,0,0] neg_hi:[1,0,0]
	ds_read_b128 v[32:35], v28 offset:27488
	s_waitcnt lgkmcnt(11)
	v_pk_fma_f32 v[80:81], v[36:37], v[116:117], v[80:81] neg_lo:[1,0,0] neg_hi:[1,0,0]
	v_pk_fma_f32 v[82:83], v[38:39], v[118:119], v[82:83] neg_lo:[1,0,0] neg_hi:[1,0,0]
	ds_read_b128 v[36:39], v28 offset:27504
	s_waitcnt lgkmcnt(11)
	v_pk_fma_f32 v[80:81], v[40:41], v[120:121], v[80:81] neg_lo:[1,0,0] neg_hi:[1,0,0]
	v_pk_fma_f32 v[82:83], v[42:43], v[122:123], v[82:83] neg_lo:[1,0,0] neg_hi:[1,0,0]
	ds_read_b128 v[40:43], v28 offset:27520
	s_waitcnt lgkmcnt(11)
	v_pk_fma_f32 v[80:81], v[44:45], v[124:125], v[80:81] neg_lo:[1,0,0] neg_hi:[1,0,0]
	v_pk_fma_f32 v[82:83], v[46:47], v[126:127], v[82:83] neg_lo:[1,0,0] neg_hi:[1,0,0]
	ds_read_b128 v[44:47], v28 offset:27648
	s_waitcnt lgkmcnt(11)
	v_pk_fma_f32 v[80:81], v[48:49], v[128:129], v[80:81] neg_lo:[1,0,0] neg_hi:[1,0,0]
	v_pk_fma_f32 v[82:83], v[50:51], v[130:131], v[82:83] neg_lo:[1,0,0] neg_hi:[1,0,0]
	ds_read_b128 v[48:51], v28 offset:27664
	s_waitcnt lgkmcnt(11)
	v_pk_fma_f32 v[80:81], v[52:53], v[132:133], v[80:81] neg_lo:[1,0,0] neg_hi:[1,0,0]
	ds_read_b128 v[52:55], v28 offset:27680
	v_add_f32_e32 v80, v80, v81
	v_add_f32_e32 v82, v82, v83
	v_add_f32_e32 v134, v80, v82
	v_cvt_pk_bf16_f32 v91, v134, v134
	global_store_short v[8:9], v91, off offset:256
	v_cmp_eq_u32_e64 s[56:57], 35, v88
	s_waitcnt lgkmcnt(11)
	s_nop 0
	v_cndmask_b32_e64 v84, 0, 1.0, s[56:57]
	v_fma_f32 v84, -v100, v56, v84
	v_fma_f32 v85, -v57, v101, 0
	v_fma_f32 v86, -v58, v102, 0
	v_fma_f32 v87, -v59, v103, 0
	ds_read_b128 v[56:59], v28 offset:27696
	s_waitcnt lgkmcnt(11)
	v_pk_fma_f32 v[84:85], v[60:61], v[104:105], v[84:85] neg_lo:[1,0,0] neg_hi:[1,0,0]
	v_pk_fma_f32 v[86:87], v[62:63], v[106:107], v[86:87] neg_lo:[1,0,0] neg_hi:[1,0,0]
	ds_read_b128 v[60:63], v28 offset:27712
	s_waitcnt lgkmcnt(11)
	v_pk_fma_f32 v[84:85], v[64:65], v[108:109], v[84:85] neg_lo:[1,0,0] neg_hi:[1,0,0]
	v_pk_fma_f32 v[86:87], v[66:67], v[110:111], v[86:87] neg_lo:[1,0,0] neg_hi:[1,0,0]
	ds_read_b128 v[64:67], v28 offset:27728
	s_waitcnt lgkmcnt(11)
	v_pk_fma_f32 v[84:85], v[68:69], v[112:113], v[84:85] neg_lo:[1,0,0] neg_hi:[1,0,0]
	v_pk_fma_f32 v[86:87], v[70:71], v[114:115], v[86:87] neg_lo:[1,0,0] neg_hi:[1,0,0]
	ds_read_b128 v[68:71], v28 offset:27744
	s_waitcnt lgkmcnt(11)
	v_pk_fma_f32 v[84:85], v[72:73], v[116:117], v[84:85] neg_lo:[1,0,0] neg_hi:[1,0,0]
	v_pk_fma_f32 v[86:87], v[74:75], v[118:119], v[86:87] neg_lo:[1,0,0] neg_hi:[1,0,0]
	ds_read_b128 v[72:75], v28 offset:27760
	s_waitcnt lgkmcnt(11)
	v_pk_fma_f32 v[84:85], v[76:77], v[120:121], v[84:85] neg_lo:[1,0,0] neg_hi:[1,0,0]
	v_pk_fma_f32 v[86:87], v[78:79], v[122:123], v[86:87] neg_lo:[1,0,0] neg_hi:[1,0,0]
	ds_read_b128 v[76:79], v28 offset:27776
	s_waitcnt lgkmcnt(11)
	v_pk_fma_f32 v[84:85], v[32:33], v[124:125], v[84:85] neg_lo:[1,0,0] neg_hi:[1,0,0]
	v_pk_fma_f32 v[86:87], v[34:35], v[126:127], v[86:87] neg_lo:[1,0,0] neg_hi:[1,0,0]
	ds_read_b128 v[32:35], v28 offset:27904
	s_waitcnt lgkmcnt(11)
; #define LAS __attribute__((address_space(3)))
; __device__ __forceinline__ bf16_t f2bf(float f) { return (bf16_t)(pk2(f, f) & 0xFFFFu); }
; __device__ NOINL void g1_phase(const LAS Params* lp, int l, LAS unsigned char* lds) {
;     ...
;             for (int i = 0; i < 64; ++i) {
;                 float s0 = (i == lane) ? 1.f : 0.f, s1 = 0.f, s2 = 0.f, s3 = 0.f;
; #pragma unroll
;                 for (int j4 = 0; j4 < (i + 3) / 4; ++j4) {
;                     const f32x4 lv = *(const LAS f32x4*)(Ld + i * 64 + j4 * 4);
;                     if (j4 * 4 + 0 < i) s0 -= lv[0] * xv[j4 * 4 + 0];
;                     if (j4 * 4 + 1 < i) s1 -= lv[1] * xv[j4 * 4 + 1];
;                     if (j4 * 4 + 2 < i) s2 -= lv[2] * xv[j4 * 4 + 2];
;                     if (j4 * 4 + 3 < i) s3 -= lv[3] * xv[j4 * 4 + 3];
;                 }
;                 xv[i] = (s0 + s1) + (s2 + s3);
;             }
;             bf16_t* Tg = p.Tbuf + ((((size_t)b * 4 + h) * 36 + c3 * 3 + s) * 2 + dir) * 4096;
; #pragma unroll
;             for (int i = 0; i < 64; ++i) Tg[i * 64 + lane] = f2bf(xv[i]);
	v_pk_fma_f32 v[84:85], v[36:37], v[128:129], v[84:85] neg_lo:[1,0,0] neg_hi:[1,0,0]
	v_pk_fma_f32 v[86:87], v[38:39], v[130:131], v[86:87] neg_lo:[1,0,0] neg_hi:[1,0,0]
	ds_read_b128 v[36:39], v28 offset:27920
	s_waitcnt lgkmcnt(11)
	v_pk_fma_f32 v[84:85], v[40:41], v[132:133], v[84:85] neg_lo:[1,0,0] neg_hi:[1,0,0]
	v_fma_f32 v86, -v42, v134, v86
	ds_read_b128 v[40:43], v28 offset:27936
	v_add_f32_e32 v84, v84, v85
	v_add_f32_e32 v86, v86, v87
	v_add_f32_e32 v135, v84, v86
	v_cvt_pk_bf16_f32 v92, v135, v135
	global_store_short v[8:9], v92, off offset:384
	v_cmp_eq_u32_e64 s[56:57], 36, v88
	s_waitcnt lgkmcnt(11)
	s_nop 0
	v_cndmask_b32_e64 v80, 0, 1.0, s[56:57]
	v_fma_f32 v80, -v100, v44, v80
	v_fma_f32 v81, -v45, v101, 0
	v_fma_f32 v82, -v46, v102, 0
	v_fma_f32 v83, -v47, v103, 0
	ds_read_b128 v[44:47], v28 offset:27952
	s_waitcnt lgkmcnt(11)
	v_pk_fma_f32 v[80:81], v[48:49], v[104:105], v[80:81] neg_lo:[1,0,0] neg_hi:[1,0,0]
	v_pk_fma_f32 v[82:83], v[50:51], v[106:107], v[82:83] neg_lo:[1,0,0] neg_hi:[1,0,0]
	ds_read_b128 v[48:51], v28 offset:27968
	s_waitcnt lgkmcnt(11)
	v_pk_fma_f32 v[80:81], v[52:53], v[108:109], v[80:81] neg_lo:[1,0,0] neg_hi:[1,0,0]
	v_pk_fma_f32 v[82:83], v[54:55], v[110:111], v[82:83] neg_lo:[1,0,0] neg_hi:[1,0,0]
	ds_read_b128 v[52:55], v28 offset:27984
	s_waitcnt lgkmcnt(11)
	v_pk_fma_f32 v[80:81], v[56:57], v[112:113], v[80:81] neg_lo:[1,0,0] neg_hi:[1,0,0]
	v_pk_fma_f32 v[82:83], v[58:59], v[114:115], v[82:83] neg_lo:[1,0,0] neg_hi:[1,0,0]
	ds_read_b128 v[56:59], v28 offset:28000
	s_waitcnt lgkmcnt(11)
	v_pk_fma_f32 v[80:81], v[60:61], v[116:117], v[80:81] neg_lo:[1,0,0] neg_hi:[1,0,0]
	v_pk_fma_f32 v[82:83], v[62:63], v[118:119], v[82:83] neg_lo:[1,0,0] neg_hi:[1,0,0]
	ds_read_b128 v[60:63], v28 offset:28016
	s_waitcnt lgkmcnt(11)
	v_pk_fma_f32 v[80:81], v[64:65], v[120:121], v[80:81] neg_lo:[1,0,0] neg_hi:[1,0,0]
	v_pk_fma_f32 v[82:83], v[66:67], v[122:123], v[82:83] neg_lo:[1,0,0] neg_hi:[1,0,0]
	ds_read_b128 v[64:67], v28 offset:28032
	s_waitcnt lgkmcnt(11)
	v_pk_fma_f32 v[80:81], v[68:69], v[124:125], v[80:81] neg_lo:[1,0,0] neg_hi:[1,0,0]
	v_pk_fma_f32 v[82:83], v[70:71], v[126:127], v[82:83] neg_lo:[1,0,0] neg_hi:[1,0,0]
	ds_read_b128 v[68:71], v28 offset:28048
	s_waitcnt lgkmcnt(11)
	v_pk_fma_f32 v[80:81], v[72:73], v[128:129], v[80:81] neg_lo:[1,0,0] neg_hi:[1,0,0]
	v_pk_fma_f32 v[82:83], v[74:75], v[130:131], v[82:83] neg_lo:[1,0,0] neg_hi:[1,0,0]
	ds_read_b128 v[72:75], v28 offset:28160
	s_waitcnt lgkmcnt(11)
	v_pk_fma_f32 v[80:81], v[76:77], v[132:133], v[80:81] neg_lo:[1,0,0] neg_hi:[1,0,0]
	v_pk_fma_f32 v[82:83], v[78:79], v[134:135], v[82:83] neg_lo:[1,0,0] neg_hi:[1,0,0]
	ds_read_b128 v[76:79], v28 offset:28176
	v_add_f32_e32 v80, v80, v81
	v_add_f32_e32 v82, v82, v83
	v_add_f32_e32 v136, v80, v82
	v_cvt_pk_bf16_f32 v89, v136, v136
	global_store_short v[8:9], v89, off offset:512
	v_cmp_eq_u32_e64 s[56:57], 37, v88
	s_waitcnt lgkmcnt(11)
	s_nop 0
	v_cndmask_b32_e64 v84, 0, 1.0, s[56:57]
	v_fma_f32 v84, -v100, v32, v84
	v_fma_f32 v85, -v33, v101, 0
	v_fma_f32 v86, -v34, v102, 0
	v_fma_f32 v87, -v35, v103, 0
	ds_read_b128 v[32:35], v28 offset:28192
	s_waitcnt lgkmcnt(11)
	v_pk_fma_f32 v[84:85], v[36:37], v[104:105], v[84:85] neg_lo:[1,0,0] neg_hi:[1,0,0]
	v_pk_fma_f32 v[86:87], v[38:39], v[106:107], v[86:87] neg_lo:[1,0,0] neg_hi:[1,0,0]
	ds_read_b128 v[36:39], v28 offset:28208
	s_waitcnt lgkmcnt(11)
	v_pk_fma_f32 v[84:85], v[40:41], v[108:109], v[84:85] neg_lo:[1,0,0] neg_hi:[1,0,0]
	v_pk_fma_f32 v[86:87], v[42:43], v[110:111], v[86:87] neg_lo:[1,0,0] neg_hi:[1,0,0]
	ds_read_b128 v[40:43], v28 offset:28224
	s_waitcnt lgkmcnt(11)
	v_pk_fma_f32 v[84:85], v[44:45], v[112:113], v[84:85] neg_lo:[1,0,0] neg_hi:[1,0,0]
	v_pk_fma_f32 v[86:87], v[46:47], v[114:115], v[86:87] neg_lo:[1,0,0] neg_hi:[1,0,0]
	ds_read_b128 v[44:47], v28 offset:28240
	s_waitcnt lgkmcnt(11)
	v_pk_fma_f32 v[84:85], v[48:49], v[116:117], v[84:85] neg_lo:[1,0,0] neg_hi:[1,0,0]
	v_pk_fma_f32 v[86:87], v[50:51], v[118:119], v[86:87] neg_lo:[1,0,0] neg_hi:[1,0,0]
	ds_read_b128 v[48:51], v28 offset:28256
	s_waitcnt lgkmcnt(11)
	v_pk_fma_f32 v[84:85], v[52:53], v[120:121], v[84:85] neg_lo:[1,0,0] neg_hi:[1,0,0]
	v_pk_fma_f32 v[86:87], v[54:55], v[122:123], v[86:87] neg_lo:[1,0,0] neg_hi:[1,0,0]
	ds_read_b128 v[52:55], v28 offset:28272
	s_waitcnt lgkmcnt(11)
	v_pk_fma_f32 v[84:85], v[56:57], v[124:125], v[84:85] neg_lo:[1,0,0] neg_hi:[1,0,0]
	v_pk_fma_f32 v[86:87], v[58:59], v[126:127], v[86:87] neg_lo:[1,0,0] neg_hi:[1,0,0]
	ds_read_b128 v[56:59], v28 offset:28288
	s_waitcnt lgkmcnt(11)
	v_pk_fma_f32 v[84:85], v[60:61], v[128:129], v[84:85] neg_lo:[1,0,0] neg_hi:[1,0,0]
	v_pk_fma_f32 v[86:87], v[62:63], v[130:131], v[86:87] neg_lo:[1,0,0] neg_hi:[1,0,0]
	ds_read_b128 v[60:63], v28 offset:28304
	s_waitcnt lgkmcnt(11)
	v_pk_fma_f32 v[84:85], v[64:65], v[132:133], v[84:85] neg_lo:[1,0,0] neg_hi:[1,0,0]
	v_pk_fma_f32 v[86:87], v[66:67], v[134:135], v[86:87] neg_lo:[1,0,0] neg_hi:[1,0,0]
	ds_read_b128 v[64:67], v28 offset:28416
	s_waitcnt lgkmcnt(11)
	v_fma_f32 v84, -v68, v136, v84
	ds_read_b128 v[68:71], v28 offset:28432
	v_add_f32_e32 v84, v84, v85
	v_add_f32_e32 v86, v86, v87
	v_add_f32_e32 v137, v84, v86
	v_cvt_pk_bf16_f32 v90, v137, v137
	global_store_short v[8:9], v90, off offset:640
	v_cmp_eq_u32_e64 s[56:57], 38, v88
	s_waitcnt lgkmcnt(11)
	s_nop 0
	v_cndmask_b32_e64 v80, 0, 1.0, s[56:57]
	v_fma_f32 v80, -v100, v72, v80
	v_fma_f32 v81, -v73, v101, 0
	v_fma_f32 v82, -v74, v102, 0
	v_fma_f32 v83, -v75, v103, 0
	ds_read_b128 v[72:75], v28 offset:28448
	s_waitcnt lgkmcnt(11)
; #define LAS __attribute__((address_space(3)))
; __device__ __forceinline__ bf16_t f2bf(float f) { return (bf16_t)(pk2(f, f) & 0xFFFFu); }
; __device__ NOINL void g1_phase(const LAS Params* lp, int l, LAS unsigned char* lds) {
;     ...
;             for (int i = 0; i < 64; ++i) {
;                 float s0 = (i == lane) ? 1.f : 0.f, s1 = 0.f, s2 = 0.f, s3 = 0.f;
; #pragma unroll
;                 for (int j4 = 0; j4 < (i + 3) / 4; ++j4) {
;                     const f32x4 lv = *(const LAS f32x4*)(Ld + i * 64 + j4 * 4);
;                     if (j4 * 4 + 0 < i) s0 -= lv[0] * xv[j4 * 4 + 0];
;                     if (j4 * 4 + 1 < i) s1 -= lv[1] * xv[j4 * 4 + 1];
;                     if (j4 * 4 + 2 < i) s2 -= lv[2] * xv[j4 * 4 + 2];
;                     if (j4 * 4 + 3 < i) s3 -= lv[3] * xv[j4 * 4 + 3];
;                 }
;                 xv[i] = (s0 + s1) + (s2 + s3);
;             }
;             bf16_t* Tg = p.Tbuf + ((((size_t)b * 4 + h) * 36 + c3 * 3 + s) * 2 + dir) * 4096;
; #pragma unroll
;             for (int i = 0; i < 64; ++i) Tg[i * 64 + lane] = f2bf(xv[i]);
	v_pk_fma_f32 v[80:81], v[76:77], v[104:105], v[80:81] neg_lo:[1,0,0] neg_hi:[1,0,0]
	v_pk_fma_f32 v[82:83], v[78:79], v[106:107], v[82:83] neg_lo:[1,0,0] neg_hi:[1,0,0]
	ds_read_b128 v[76:79], v28 offset:28464
	s_waitcnt lgkmcnt(11)
	v_pk_fma_f32 v[80:81], v[32:33], v[108:109], v[80:81] neg_lo:[1,0,0] neg_hi:[1,0,0]
	v_pk_fma_f32 v[82:83], v[34:35], v[110:111], v[82:83] neg_lo:[1,0,0] neg_hi:[1,0,0]
	ds_read_b128 v[32:35], v28 offset:28480
	s_waitcnt lgkmcnt(11)
	v_pk_fma_f32 v[80:81], v[36:37], v[112:113], v[80:81] neg_lo:[1,0,0] neg_hi:[1,0,0]
	v_pk_fma_f32 v[82:83], v[38:39], v[114:115], v[82:83] neg_lo:[1,0,0] neg_hi:[1,0,0]
	ds_read_b128 v[36:39], v28 offset:28496
	s_waitcnt lgkmcnt(11)
	v_pk_fma_f32 v[80:81], v[40:41], v[116:117], v[80:81] neg_lo:[1,0,0] neg_hi:[1,0,0]
	v_pk_fma_f32 v[82:83], v[42:43], v[118:119], v[82:83] neg_lo:[1,0,0] neg_hi:[1,0,0]
	ds_read_b128 v[40:43], v28 offset:28512
	s_waitcnt lgkmcnt(11)
	v_pk_fma_f32 v[80:81], v[44:45], v[120:121], v[80:81] neg_lo:[1,0,0] neg_hi:[1,0,0]
	v_pk_fma_f32 v[82:83], v[46:47], v[122:123], v[82:83] neg_lo:[1,0,0] neg_hi:[1,0,0]
	ds_read_b128 v[44:47], v28 offset:28528
	s_waitcnt lgkmcnt(11)
	v_pk_fma_f32 v[80:81], v[48:49], v[124:125], v[80:81] neg_lo:[1,0,0] neg_hi:[1,0,0]
	v_pk_fma_f32 v[82:83], v[50:51], v[126:127], v[82:83] neg_lo:[1,0,0] neg_hi:[1,0,0]
	ds_read_b128 v[48:51], v28 offset:28544
	s_waitcnt lgkmcnt(11)
	v_pk_fma_f32 v[80:81], v[52:53], v[128:129], v[80:81] neg_lo:[1,0,0] neg_hi:[1,0,0]
	v_pk_fma_f32 v[82:83], v[54:55], v[130:131], v[82:83] neg_lo:[1,0,0] neg_hi:[1,0,0]
	ds_read_b128 v[52:55], v28 offset:28560
	s_waitcnt lgkmcnt(11)
	v_pk_fma_f32 v[80:81], v[56:57], v[132:133], v[80:81] neg_lo:[1,0,0] neg_hi:[1,0,0]
	v_pk_fma_f32 v[82:83], v[58:59], v[134:135], v[82:83] neg_lo:[1,0,0] neg_hi:[1,0,0]
	ds_read_b128 v[56:59], v28 offset:28672
	s_waitcnt lgkmcnt(11)
	v_pk_fma_f32 v[80:81], v[60:61], v[136:137], v[80:81] neg_lo:[1,0,0] neg_hi:[1,0,0]
	ds_read_b128 v[60:63], v28 offset:28688
	v_add_f32_e32 v80, v80, v81
	v_add_f32_e32 v82, v82, v83
	v_add_f32_e32 v138, v80, v82
	v_cvt_pk_bf16_f32 v91, v138, v138
	global_store_short v[8:9], v91, off offset:768
	v_cmp_eq_u32_e64 s[56:57], 39, v88
	s_waitcnt lgkmcnt(11)
	s_nop 0
	v_cndmask_b32_e64 v84, 0, 1.0, s[56:57]
	v_fma_f32 v84, -v100, v64, v84
	v_fma_f32 v85, -v65, v101, 0
	v_fma_f32 v86, -v66, v102, 0
	v_fma_f32 v87, -v67, v103, 0
	ds_read_b128 v[64:67], v28 offset:28704
	s_waitcnt lgkmcnt(11)
	v_pk_fma_f32 v[84:85], v[68:69], v[104:105], v[84:85] neg_lo:[1,0,0] neg_hi:[1,0,0]
	v_pk_fma_f32 v[86:87], v[70:71], v[106:107], v[86:87] neg_lo:[1,0,0] neg_hi:[1,0,0]
	ds_read_b128 v[68:71], v28 offset:28720
	s_waitcnt lgkmcnt(11)
	v_pk_fma_f32 v[84:85], v[72:73], v[108:109], v[84:85] neg_lo:[1,0,0] neg_hi:[1,0,0]
	v_pk_fma_f32 v[86:87], v[74:75], v[110:111], v[86:87] neg_lo:[1,0,0] neg_hi:[1,0,0]
	ds_read_b128 v[72:75], v28 offset:28736
	s_waitcnt lgkmcnt(11)
	v_pk_fma_f32 v[84:85], v[76:77], v[112:113], v[84:85] neg_lo:[1,0,0] neg_hi:[1,0,0]
	v_pk_fma_f32 v[86:87], v[78:79], v[114:115], v[86:87] neg_lo:[1,0,0] neg_hi:[1,0,0]
	ds_read_b128 v[76:79], v28 offset:28752
	s_waitcnt lgkmcnt(11)
	v_pk_fma_f32 v[84:85], v[32:33], v[116:117], v[84:85] neg_lo:[1,0,0] neg_hi:[1,0,0]
	v_pk_fma_f32 v[86:87], v[34:35], v[118:119], v[86:87] neg_lo:[1,0,0] neg_hi:[1,0,0]
	ds_read_b128 v[32:35], v28 offset:28768
	s_waitcnt lgkmcnt(11)
	v_pk_fma_f32 v[84:85], v[36:37], v[120:121], v[84:85] neg_lo:[1,0,0] neg_hi:[1,0,0]
	v_pk_fma_f32 v[86:87], v[38:39], v[122:123], v[86:87] neg_lo:[1,0,0] neg_hi:[1,0,0]
	ds_read_b128 v[36:39], v28 offset:28784
	s_waitcnt lgkmcnt(11)
	v_pk_fma_f32 v[84:85], v[40:41], v[124:125], v[84:85] neg_lo:[1,0,0] neg_hi:[1,0,0]
	v_pk_fma_f32 v[86:87], v[42:43], v[126:127], v[86:87] neg_lo:[1,0,0] neg_hi:[1,0,0]
	ds_read_b128 v[40:43], v28 offset:28800
	s_waitcnt lgkmcnt(11)
	v_pk_fma_f32 v[84:85], v[44:45], v[128:129], v[84:85] neg_lo:[1,0,0] neg_hi:[1,0,0]
	v_pk_fma_f32 v[86:87], v[46:47], v[130:131], v[86:87] neg_lo:[1,0,0] neg_hi:[1,0,0]
	ds_read_b128 v[44:47], v28 offset:28816
	s_waitcnt lgkmcnt(11)
	v_pk_fma_f32 v[84:85], v[48:49], v[132:133], v[84:85] neg_lo:[1,0,0] neg_hi:[1,0,0]
	v_pk_fma_f32 v[86:87], v[50:51], v[134:135], v[86:87] neg_lo:[1,0,0] neg_hi:[1,0,0]
	ds_read_b128 v[48:51], v28 offset:28928
	s_waitcnt lgkmcnt(11)
	v_pk_fma_f32 v[84:85], v[52:53], v[136:137], v[84:85] neg_lo:[1,0,0] neg_hi:[1,0,0]
	v_fma_f32 v86, -v54, v138, v86
	ds_read_b128 v[52:55], v28 offset:28944
	v_add_f32_e32 v84, v84, v85
	v_add_f32_e32 v86, v86, v87
	v_add_f32_e32 v139, v84, v86
	v_cvt_pk_bf16_f32 v92, v139, v139
	global_store_short v[8:9], v92, off offset:896
	v_cmp_eq_u32_e64 s[56:57], 40, v88
	s_waitcnt lgkmcnt(11)
	s_nop 0
	v_cndmask_b32_e64 v80, 0, 1.0, s[56:57]
	v_fma_f32 v80, -v100, v56, v80
	v_fma_f32 v81, -v57, v101, 0
	v_fma_f32 v82, -v58, v102, 0
	v_fma_f32 v83, -v59, v103, 0
	ds_read_b128 v[56:59], v28 offset:28960
	s_waitcnt lgkmcnt(11)
	v_pk_fma_f32 v[80:81], v[60:61], v[104:105], v[80:81] neg_lo:[1,0,0] neg_hi:[1,0,0]
	v_pk_fma_f32 v[82:83], v[62:63], v[106:107], v[82:83] neg_lo:[1,0,0] neg_hi:[1,0,0]
	ds_read_b128 v[60:63], v28 offset:28976
	s_waitcnt lgkmcnt(11)
	v_pk_fma_f32 v[80:81], v[64:65], v[108:109], v[80:81] neg_lo:[1,0,0] neg_hi:[1,0,0]
	v_pk_fma_f32 v[82:83], v[66:67], v[110:111], v[82:83] neg_lo:[1,0,0] neg_hi:[1,0,0]
	ds_read_b128 v[64:67], v28 offset:28992
	s_waitcnt lgkmcnt(11)
	v_pk_fma_f32 v[80:81], v[68:69], v[112:113], v[80:81] neg_lo:[1,0,0] neg_hi:[1,0,0]
	v_pk_fma_f32 v[82:83], v[70:71], v[114:115], v[82:83] neg_lo:[1,0,0] neg_hi:[1,0,0]
	ds_read_b128 v[68:71], v28 offset:29008
	s_waitcnt lgkmcnt(11)
; #define LAS __attribute__((address_space(3)))
; __device__ __forceinline__ bf16_t f2bf(float f) { return (bf16_t)(pk2(f, f) & 0xFFFFu); }
; __device__ NOINL void g1_phase(const LAS Params* lp, int l, LAS unsigned char* lds) {
;     ...
;             for (int i = 0; i < 64; ++i) {
;                 float s0 = (i == lane) ? 1.f : 0.f, s1 = 0.f, s2 = 0.f, s3 = 0.f;
; #pragma unroll
;                 for (int j4 = 0; j4 < (i + 3) / 4; ++j4) {
;                     const f32x4 lv = *(const LAS f32x4*)(Ld + i * 64 + j4 * 4);
;                     if (j4 * 4 + 0 < i) s0 -= lv[0] * xv[j4 * 4 + 0];
;                     if (j4 * 4 + 1 < i) s1 -= lv[1] * xv[j4 * 4 + 1];
;                     if (j4 * 4 + 2 < i) s2 -= lv[2] * xv[j4 * 4 + 2];
;                     if (j4 * 4 + 3 < i) s3 -= lv[3] * xv[j4 * 4 + 3];
;                 }
;                 xv[i] = (s0 + s1) + (s2 + s3);
;             }
;             bf16_t* Tg = p.Tbuf + ((((size_t)b * 4 + h) * 36 + c3 * 3 + s) * 2 + dir) * 4096;
; #pragma unroll
;             for (int i = 0; i < 64; ++i) Tg[i * 64 + lane] = f2bf(xv[i]);
	v_pk_fma_f32 v[80:81], v[72:73], v[116:117], v[80:81] neg_lo:[1,0,0] neg_hi:[1,0,0]
	v_pk_fma_f32 v[82:83], v[74:75], v[118:119], v[82:83] neg_lo:[1,0,0] neg_hi:[1,0,0]
	ds_read_b128 v[72:75], v28 offset:29024
	s_waitcnt lgkmcnt(11)
	v_pk_fma_f32 v[80:81], v[76:77], v[120:121], v[80:81] neg_lo:[1,0,0] neg_hi:[1,0,0]
	v_pk_fma_f32 v[82:83], v[78:79], v[122:123], v[82:83] neg_lo:[1,0,0] neg_hi:[1,0,0]
	ds_read_b128 v[76:79], v28 offset:29040
	s_waitcnt lgkmcnt(11)
	v_pk_fma_f32 v[80:81], v[32:33], v[124:125], v[80:81] neg_lo:[1,0,0] neg_hi:[1,0,0]
	v_pk_fma_f32 v[82:83], v[34:35], v[126:127], v[82:83] neg_lo:[1,0,0] neg_hi:[1,0,0]
	ds_read_b128 v[32:35], v28 offset:29056
	s_waitcnt lgkmcnt(11)
	v_pk_fma_f32 v[80:81], v[36:37], v[128:129], v[80:81] neg_lo:[1,0,0] neg_hi:[1,0,0]
	v_pk_fma_f32 v[82:83], v[38:39], v[130:131], v[82:83] neg_lo:[1,0,0] neg_hi:[1,0,0]
	ds_read_b128 v[36:39], v28 offset:29072
	s_waitcnt lgkmcnt(11)
	v_pk_fma_f32 v[80:81], v[40:41], v[132:133], v[80:81] neg_lo:[1,0,0] neg_hi:[1,0,0]
	v_pk_fma_f32 v[82:83], v[42:43], v[134:135], v[82:83] neg_lo:[1,0,0] neg_hi:[1,0,0]
	ds_read_b128 v[40:43], v28 offset:29088
	s_waitcnt lgkmcnt(11)
	v_pk_fma_f32 v[80:81], v[44:45], v[136:137], v[80:81] neg_lo:[1,0,0] neg_hi:[1,0,0]
	v_pk_fma_f32 v[82:83], v[46:47], v[138:139], v[82:83] neg_lo:[1,0,0] neg_hi:[1,0,0]
	ds_read_b128 v[44:47], v28 offset:29184
	v_add_f32_e32 v80, v80, v81
	v_add_f32_e32 v82, v82, v83
	v_add_f32_e32 v140, v80, v82
	v_cvt_pk_bf16_f32 v89, v140, v140
	global_store_short v[8:9], v89, off offset:1024
	v_cmp_eq_u32_e64 s[56:57], 41, v88
	s_waitcnt lgkmcnt(11)
	s_nop 0
	v_cndmask_b32_e64 v84, 0, 1.0, s[56:57]
	v_fma_f32 v84, -v100, v48, v84
	v_fma_f32 v85, -v49, v101, 0
	v_fma_f32 v86, -v50, v102, 0
	v_fma_f32 v87, -v51, v103, 0
	ds_read_b128 v[48:51], v28 offset:29200
	s_waitcnt lgkmcnt(11)
	v_pk_fma_f32 v[84:85], v[52:53], v[104:105], v[84:85] neg_lo:[1,0,0] neg_hi:[1,0,0]
	v_pk_fma_f32 v[86:87], v[54:55], v[106:107], v[86:87] neg_lo:[1,0,0] neg_hi:[1,0,0]
	ds_read_b128 v[52:55], v28 offset:29216
	s_waitcnt lgkmcnt(11)
	v_pk_fma_f32 v[84:85], v[56:57], v[108:109], v[84:85] neg_lo:[1,0,0] neg_hi:[1,0,0]
	v_pk_fma_f32 v[86:87], v[58:59], v[110:111], v[86:87] neg_lo:[1,0,0] neg_hi:[1,0,0]
	ds_read_b128 v[56:59], v28 offset:29232
	s_waitcnt lgkmcnt(11)
	v_pk_fma_f32 v[84:85], v[60:61], v[112:113], v[84:85] neg_lo:[1,0,0] neg_hi:[1,0,0]
	v_pk_fma_f32 v[86:87], v[62:63], v[114:115], v[86:87] neg_lo:[1,0,0] neg_hi:[1,0,0]
	ds_read_b128 v[60:63], v28 offset:29248
	s_waitcnt lgkmcnt(11)
	v_pk_fma_f32 v[84:85], v[64:65], v[116:117], v[84:85] neg_lo:[1,0,0] neg_hi:[1,0,0]
	v_pk_fma_f32 v[86:87], v[66:67], v[118:119], v[86:87] neg_lo:[1,0,0] neg_hi:[1,0,0]
	ds_read_b128 v[64:67], v28 offset:29264
	s_waitcnt lgkmcnt(11)
	v_pk_fma_f32 v[84:85], v[68:69], v[120:121], v[84:85] neg_lo:[1,0,0] neg_hi:[1,0,0]
	v_pk_fma_f32 v[86:87], v[70:71], v[122:123], v[86:87] neg_lo:[1,0,0] neg_hi:[1,0,0]
	ds_read_b128 v[68:71], v28 offset:29280
	s_waitcnt lgkmcnt(11)
	v_pk_fma_f32 v[84:85], v[72:73], v[124:125], v[84:85] neg_lo:[1,0,0] neg_hi:[1,0,0]
	v_pk_fma_f32 v[86:87], v[74:75], v[126:127], v[86:87] neg_lo:[1,0,0] neg_hi:[1,0,0]
	ds_read_b128 v[72:75], v28 offset:29296
	s_waitcnt lgkmcnt(11)
	v_pk_fma_f32 v[84:85], v[76:77], v[128:129], v[84:85] neg_lo:[1,0,0] neg_hi:[1,0,0]
	v_pk_fma_f32 v[86:87], v[78:79], v[130:131], v[86:87] neg_lo:[1,0,0] neg_hi:[1,0,0]
	ds_read_b128 v[76:79], v28 offset:29312
	s_waitcnt lgkmcnt(11)
	v_pk_fma_f32 v[84:85], v[32:33], v[132:133], v[84:85] neg_lo:[1,0,0] neg_hi:[1,0,0]
	v_pk_fma_f32 v[86:87], v[34:35], v[134:135], v[86:87] neg_lo:[1,0,0] neg_hi:[1,0,0]
	ds_read_b128 v[32:35], v28 offset:29328
	s_waitcnt lgkmcnt(11)
	v_pk_fma_f32 v[84:85], v[36:37], v[136:137], v[84:85] neg_lo:[1,0,0] neg_hi:[1,0,0]
	v_pk_fma_f32 v[86:87], v[38:39], v[138:139], v[86:87] neg_lo:[1,0,0] neg_hi:[1,0,0]
	ds_read_b128 v[36:39], v28 offset:29344
	s_waitcnt lgkmcnt(11)
	v_fma_f32 v84, -v40, v140, v84
	ds_read_b128 v[40:43], v28 offset:29440
	v_add_f32_e32 v84, v84, v85
	v_add_f32_e32 v86, v86, v87
	v_add_f32_e32 v141, v84, v86
	v_cvt_pk_bf16_f32 v90, v141, v141
	global_store_short v[8:9], v90, off offset:1152
	v_cmp_eq_u32_e64 s[56:57], 42, v88
	s_waitcnt lgkmcnt(11)
	s_nop 0
	v_cndmask_b32_e64 v80, 0, 1.0, s[56:57]
	v_fma_f32 v80, -v100, v44, v80
	v_fma_f32 v81, -v45, v101, 0
	v_fma_f32 v82, -v46, v102, 0
	v_fma_f32 v83, -v47, v103, 0
	ds_read_b128 v[44:47], v28 offset:29456
	s_waitcnt lgkmcnt(11)
	v_pk_fma_f32 v[80:81], v[48:49], v[104:105], v[80:81] neg_lo:[1,0,0] neg_hi:[1,0,0]
	v_pk_fma_f32 v[82:83], v[50:51], v[106:107], v[82:83] neg_lo:[1,0,0] neg_hi:[1,0,0]
	ds_read_b128 v[48:51], v28 offset:29472
	s_waitcnt lgkmcnt(11)
	v_pk_fma_f32 v[80:81], v[52:53], v[108:109], v[80:81] neg_lo:[1,0,0] neg_hi:[1,0,0]
	v_pk_fma_f32 v[82:83], v[54:55], v[110:111], v[82:83] neg_lo:[1,0,0] neg_hi:[1,0,0]
	ds_read_b128 v[52:55], v28 offset:29488
	s_waitcnt lgkmcnt(11)
	v_pk_fma_f32 v[80:81], v[56:57], v[112:113], v[80:81] neg_lo:[1,0,0] neg_hi:[1,0,0]
	v_pk_fma_f32 v[82:83], v[58:59], v[114:115], v[82:83] neg_lo:[1,0,0] neg_hi:[1,0,0]
	ds_read_b128 v[56:59], v28 offset:29504
	s_waitcnt lgkmcnt(11)
	v_pk_fma_f32 v[80:81], v[60:61], v[116:117], v[80:81] neg_lo:[1,0,0] neg_hi:[1,0,0]
	v_pk_fma_f32 v[82:83], v[62:63], v[118:119], v[82:83] neg_lo:[1,0,0] neg_hi:[1,0,0]
	ds_read_b128 v[60:63], v28 offset:29520
	s_waitcnt lgkmcnt(11)
	v_pk_fma_f32 v[80:81], v[64:65], v[120:121], v[80:81] neg_lo:[1,0,0] neg_hi:[1,0,0]
	v_pk_fma_f32 v[82:83], v[66:67], v[122:123], v[82:83] neg_lo:[1,0,0] neg_hi:[1,0,0]
	ds_read_b128 v[64:67], v28 offset:29536
	s_waitcnt lgkmcnt(11)
; #define LAS __attribute__((address_space(3)))
; __device__ __forceinline__ bf16_t f2bf(float f) { return (bf16_t)(pk2(f, f) & 0xFFFFu); }
; __device__ NOINL void g1_phase(const LAS Params* lp, int l, LAS unsigned char* lds) {
;     ...
;             for (int i = 0; i < 64; ++i) {
;                 float s0 = (i == lane) ? 1.f : 0.f, s1 = 0.f, s2 = 0.f, s3 = 0.f;
; #pragma unroll
;                 for (int j4 = 0; j4 < (i + 3) / 4; ++j4) {
;                     const f32x4 lv = *(const LAS f32x4*)(Ld + i * 64 + j4 * 4);
;                     if (j4 * 4 + 0 < i) s0 -= lv[0] * xv[j4 * 4 + 0];
;                     if (j4 * 4 + 1 < i) s1 -= lv[1] * xv[j4 * 4 + 1];
;                     if (j4 * 4 + 2 < i) s2 -= lv[2] * xv[j4 * 4 + 2];
;                     if (j4 * 4 + 3 < i) s3 -= lv[3] * xv[j4 * 4 + 3];
;                 }
;                 xv[i] = (s0 + s1) + (s2 + s3);
;             }
;             bf16_t* Tg = p.Tbuf + ((((size_t)b * 4 + h) * 36 + c3 * 3 + s) * 2 + dir) * 4096;
; #pragma unroll
;             for (int i = 0; i < 64; ++i) Tg[i * 64 + lane] = f2bf(xv[i]);
	v_pk_fma_f32 v[80:81], v[68:69], v[124:125], v[80:81] neg_lo:[1,0,0] neg_hi:[1,0,0]
	v_pk_fma_f32 v[82:83], v[70:71], v[126:127], v[82:83] neg_lo:[1,0,0] neg_hi:[1,0,0]
	ds_read_b128 v[68:71], v28 offset:29552
	s_waitcnt lgkmcnt(11)
	v_pk_fma_f32 v[80:81], v[72:73], v[128:129], v[80:81] neg_lo:[1,0,0] neg_hi:[1,0,0]
	v_pk_fma_f32 v[82:83], v[74:75], v[130:131], v[82:83] neg_lo:[1,0,0] neg_hi:[1,0,0]
	ds_read_b128 v[72:75], v28 offset:29568
	s_waitcnt lgkmcnt(11)
	v_pk_fma_f32 v[80:81], v[76:77], v[132:133], v[80:81] neg_lo:[1,0,0] neg_hi:[1,0,0]
	v_pk_fma_f32 v[82:83], v[78:79], v[134:135], v[82:83] neg_lo:[1,0,0] neg_hi:[1,0,0]
	ds_read_b128 v[76:79], v28 offset:29584
	s_waitcnt lgkmcnt(11)
	v_pk_fma_f32 v[80:81], v[32:33], v[136:137], v[80:81] neg_lo:[1,0,0] neg_hi:[1,0,0]
	v_pk_fma_f32 v[82:83], v[34:35], v[138:139], v[82:83] neg_lo:[1,0,0] neg_hi:[1,0,0]
	ds_read_b128 v[32:35], v28 offset:29600
	s_waitcnt lgkmcnt(11)
	v_pk_fma_f32 v[80:81], v[36:37], v[140:141], v[80:81] neg_lo:[1,0,0] neg_hi:[1,0,0]
	ds_read_b128 v[36:39], v28 offset:29696
	v_add_f32_e32 v80, v80, v81
	v_add_f32_e32 v82, v82, v83
	v_add_f32_e32 v142, v80, v82
	v_cvt_pk_bf16_f32 v91, v142, v142
	global_store_short v[8:9], v91, off offset:1280
	v_cmp_eq_u32_e64 s[56:57], 43, v88
	s_waitcnt lgkmcnt(11)
	s_nop 0
	v_cndmask_b32_e64 v84, 0, 1.0, s[56:57]
	v_fma_f32 v84, -v100, v40, v84
	v_fma_f32 v85, -v41, v101, 0
	v_fma_f32 v86, -v42, v102, 0
	v_fma_f32 v87, -v43, v103, 0
	ds_read_b128 v[40:43], v28 offset:29712
	s_waitcnt lgkmcnt(11)
	v_pk_fma_f32 v[84:85], v[44:45], v[104:105], v[84:85] neg_lo:[1,0,0] neg_hi:[1,0,0]
	v_pk_fma_f32 v[86:87], v[46:47], v[106:107], v[86:87] neg_lo:[1,0,0] neg_hi:[1,0,0]
	ds_read_b128 v[44:47], v28 offset:29728
	s_waitcnt lgkmcnt(11)
	v_pk_fma_f32 v[84:85], v[48:49], v[108:109], v[84:85] neg_lo:[1,0,0] neg_hi:[1,0,0]
	v_pk_fma_f32 v[86:87], v[50:51], v[110:111], v[86:87] neg_lo:[1,0,0] neg_hi:[1,0,0]
	ds_read_b128 v[48:51], v28 offset:29744
	s_waitcnt lgkmcnt(11)
	v_pk_fma_f32 v[84:85], v[52:53], v[112:113], v[84:85] neg_lo:[1,0,0] neg_hi:[1,0,0]
	v_pk_fma_f32 v[86:87], v[54:55], v[114:115], v[86:87] neg_lo:[1,0,0] neg_hi:[1,0,0]
	ds_read_b128 v[52:55], v28 offset:29760
	s_waitcnt lgkmcnt(11)
	v_pk_fma_f32 v[84:85], v[56:57], v[116:117], v[84:85] neg_lo:[1,0,0] neg_hi:[1,0,0]
	v_pk_fma_f32 v[86:87], v[58:59], v[118:119], v[86:87] neg_lo:[1,0,0] neg_hi:[1,0,0]
	ds_read_b128 v[56:59], v28 offset:29776
	s_waitcnt lgkmcnt(11)
	v_pk_fma_f32 v[84:85], v[60:61], v[120:121], v[84:85] neg_lo:[1,0,0] neg_hi:[1,0,0]
	v_pk_fma_f32 v[86:87], v[62:63], v[122:123], v[86:87] neg_lo:[1,0,0] neg_hi:[1,0,0]
	ds_read_b128 v[60:63], v28 offset:29792
	s_waitcnt lgkmcnt(11)
	v_pk_fma_f32 v[84:85], v[64:65], v[124:125], v[84:85] neg_lo:[1,0,0] neg_hi:[1,0,0]
	v_pk_fma_f32 v[86:87], v[66:67], v[126:127], v[86:87] neg_lo:[1,0,0] neg_hi:[1,0,0]
	ds_read_b128 v[64:67], v28 offset:29808
	s_waitcnt lgkmcnt(11)
	v_pk_fma_f32 v[84:85], v[68:69], v[128:129], v[84:85] neg_lo:[1,0,0] neg_hi:[1,0,0]
	v_pk_fma_f32 v[86:87], v[70:71], v[130:131], v[86:87] neg_lo:[1,0,0] neg_hi:[1,0,0]
	ds_read_b128 v[68:71], v28 offset:29824
	s_waitcnt lgkmcnt(11)
	v_pk_fma_f32 v[84:85], v[72:73], v[132:133], v[84:85] neg_lo:[1,0,0] neg_hi:[1,0,0]
	v_pk_fma_f32 v[86:87], v[74:75], v[134:135], v[86:87] neg_lo:[1,0,0] neg_hi:[1,0,0]
	ds_read_b128 v[72:75], v28 offset:29840
	s_waitcnt lgkmcnt(11)
	v_pk_fma_f32 v[84:85], v[76:77], v[136:137], v[84:85] neg_lo:[1,0,0] neg_hi:[1,0,0]
	v_pk_fma_f32 v[86:87], v[78:79], v[138:139], v[86:87] neg_lo:[1,0,0] neg_hi:[1,0,0]
	ds_read_b128 v[76:79], v28 offset:29856
	s_waitcnt lgkmcnt(11)
	v_pk_fma_f32 v[84:85], v[32:33], v[140:141], v[84:85] neg_lo:[1,0,0] neg_hi:[1,0,0]
	v_fma_f32 v86, -v34, v142, v86
	ds_read_b128 v[32:35], v28 offset:29952
	v_add_f32_e32 v84, v84, v85
	v_add_f32_e32 v86, v86, v87
	v_add_f32_e32 v143, v84, v86
	v_cvt_pk_bf16_f32 v92, v143, v143
	global_store_short v[8:9], v92, off offset:1408
	v_cmp_eq_u32_e64 s[56:57], 44, v88
	s_waitcnt lgkmcnt(11)
	s_nop 0
	v_cndmask_b32_e64 v80, 0, 1.0, s[56:57]
	v_fma_f32 v80, -v100, v36, v80
	v_fma_f32 v81, -v37, v101, 0
	v_fma_f32 v82, -v38, v102, 0
	v_fma_f32 v83, -v39, v103, 0
	ds_read_b128 v[36:39], v28 offset:29968
	s_waitcnt lgkmcnt(11)
	v_pk_fma_f32 v[80:81], v[40:41], v[104:105], v[80:81] neg_lo:[1,0,0] neg_hi:[1,0,0]
	v_pk_fma_f32 v[82:83], v[42:43], v[106:107], v[82:83] neg_lo:[1,0,0] neg_hi:[1,0,0]
	ds_read_b128 v[40:43], v28 offset:29984
	s_waitcnt lgkmcnt(11)
	v_pk_fma_f32 v[80:81], v[44:45], v[108:109], v[80:81] neg_lo:[1,0,0] neg_hi:[1,0,0]
	v_pk_fma_f32 v[82:83], v[46:47], v[110:111], v[82:83] neg_lo:[1,0,0] neg_hi:[1,0,0]
	ds_read_b128 v[44:47], v28 offset:30000
	s_waitcnt lgkmcnt(11)
	v_pk_fma_f32 v[80:81], v[48:49], v[112:113], v[80:81] neg_lo:[1,0,0] neg_hi:[1,0,0]
	v_pk_fma_f32 v[82:83], v[50:51], v[114:115], v[82:83] neg_lo:[1,0,0] neg_hi:[1,0,0]
	ds_read_b128 v[48:51], v28 offset:30016
	s_waitcnt lgkmcnt(11)
	v_pk_fma_f32 v[80:81], v[52:53], v[116:117], v[80:81] neg_lo:[1,0,0] neg_hi:[1,0,0]
	v_pk_fma_f32 v[82:83], v[54:55], v[118:119], v[82:83] neg_lo:[1,0,0] neg_hi:[1,0,0]
	ds_read_b128 v[52:55], v28 offset:30032
	s_waitcnt lgkmcnt(11)
	v_pk_fma_f32 v[80:81], v[56:57], v[120:121], v[80:81] neg_lo:[1,0,0] neg_hi:[1,0,0]
	v_pk_fma_f32 v[82:83], v[58:59], v[122:123], v[82:83] neg_lo:[1,0,0] neg_hi:[1,0,0]
	ds_read_b128 v[56:59], v28 offset:30048
	s_waitcnt lgkmcnt(11)
	v_pk_fma_f32 v[80:81], v[60:61], v[124:125], v[80:81] neg_lo:[1,0,0] neg_hi:[1,0,0]
	v_pk_fma_f32 v[82:83], v[62:63], v[126:127], v[82:83] neg_lo:[1,0,0] neg_hi:[1,0,0]
	ds_read_b128 v[60:63], v28 offset:30064
	s_waitcnt lgkmcnt(11)
; #define LAS __attribute__((address_space(3)))
; __device__ __forceinline__ bf16_t f2bf(float f) { return (bf16_t)(pk2(f, f) & 0xFFFFu); }
; __device__ NOINL void g1_phase(const LAS Params* lp, int l, LAS unsigned char* lds) {
;     ...
;             for (int i = 0; i < 64; ++i) {
;                 float s0 = (i == lane) ? 1.f : 0.f, s1 = 0.f, s2 = 0.f, s3 = 0.f;
; #pragma unroll
;                 for (int j4 = 0; j4 < (i + 3) / 4; ++j4) {
;                     const f32x4 lv = *(const LAS f32x4*)(Ld + i * 64 + j4 * 4);
;                     if (j4 * 4 + 0 < i) s0 -= lv[0] * xv[j4 * 4 + 0];
;                     if (j4 * 4 + 1 < i) s1 -= lv[1] * xv[j4 * 4 + 1];
;                     if (j4 * 4 + 2 < i) s2 -= lv[2] * xv[j4 * 4 + 2];
;                     if (j4 * 4 + 3 < i) s3 -= lv[3] * xv[j4 * 4 + 3];
;                 }
;                 xv[i] = (s0 + s1) + (s2 + s3);
;             }
;             bf16_t* Tg = p.Tbuf + ((((size_t)b * 4 + h) * 36 + c3 * 3 + s) * 2 + dir) * 4096;
; #pragma unroll
;             for (int i = 0; i < 64; ++i) Tg[i * 64 + lane] = f2bf(xv[i]);
	v_pk_fma_f32 v[80:81], v[64:65], v[128:129], v[80:81] neg_lo:[1,0,0] neg_hi:[1,0,0]
	v_pk_fma_f32 v[82:83], v[66:67], v[130:131], v[82:83] neg_lo:[1,0,0] neg_hi:[1,0,0]
	ds_read_b128 v[64:67], v28 offset:30080
	s_waitcnt lgkmcnt(11)
	v_pk_fma_f32 v[80:81], v[68:69], v[132:133], v[80:81] neg_lo:[1,0,0] neg_hi:[1,0,0]
	v_pk_fma_f32 v[82:83], v[70:71], v[134:135], v[82:83] neg_lo:[1,0,0] neg_hi:[1,0,0]
	ds_read_b128 v[68:71], v28 offset:30096
	s_waitcnt lgkmcnt(11)
	v_pk_fma_f32 v[80:81], v[72:73], v[136:137], v[80:81] neg_lo:[1,0,0] neg_hi:[1,0,0]
	v_pk_fma_f32 v[82:83], v[74:75], v[138:139], v[82:83] neg_lo:[1,0,0] neg_hi:[1,0,0]
	ds_read_b128 v[72:75], v28 offset:30112
	s_waitcnt lgkmcnt(11)
	v_pk_fma_f32 v[80:81], v[76:77], v[140:141], v[80:81] neg_lo:[1,0,0] neg_hi:[1,0,0]
	v_pk_fma_f32 v[82:83], v[78:79], v[142:143], v[82:83] neg_lo:[1,0,0] neg_hi:[1,0,0]
	ds_read_b128 v[76:79], v28 offset:30128
	v_add_f32_e32 v80, v80, v81
	v_add_f32_e32 v82, v82, v83
	v_add_f32_e32 v144, v80, v82
	v_cvt_pk_bf16_f32 v89, v144, v144
	global_store_short v[8:9], v89, off offset:1536
	v_cmp_eq_u32_e64 s[56:57], 45, v88
	s_waitcnt lgkmcnt(11)
	s_nop 0
	v_cndmask_b32_e64 v84, 0, 1.0, s[56:57]
	v_fma_f32 v84, -v100, v32, v84
	v_fma_f32 v85, -v33, v101, 0
	v_fma_f32 v86, -v34, v102, 0
	v_fma_f32 v87, -v35, v103, 0
	ds_read_b128 v[32:35], v28 offset:30208
	s_waitcnt lgkmcnt(11)
	v_pk_fma_f32 v[84:85], v[36:37], v[104:105], v[84:85] neg_lo:[1,0,0] neg_hi:[1,0,0]
	v_pk_fma_f32 v[86:87], v[38:39], v[106:107], v[86:87] neg_lo:[1,0,0] neg_hi:[1,0,0]
	ds_read_b128 v[36:39], v28 offset:30224
	s_waitcnt lgkmcnt(11)
	v_pk_fma_f32 v[84:85], v[40:41], v[108:109], v[84:85] neg_lo:[1,0,0] neg_hi:[1,0,0]
	v_pk_fma_f32 v[86:87], v[42:43], v[110:111], v[86:87] neg_lo:[1,0,0] neg_hi:[1,0,0]
	ds_read_b128 v[40:43], v28 offset:30240
	s_waitcnt lgkmcnt(11)
	v_pk_fma_f32 v[84:85], v[44:45], v[112:113], v[84:85] neg_lo:[1,0,0] neg_hi:[1,0,0]
	v_pk_fma_f32 v[86:87], v[46:47], v[114:115], v[86:87] neg_lo:[1,0,0] neg_hi:[1,0,0]
	ds_read_b128 v[44:47], v28 offset:30256
	s_waitcnt lgkmcnt(11)
	v_pk_fma_f32 v[84:85], v[48:49], v[116:117], v[84:85] neg_lo:[1,0,0] neg_hi:[1,0,0]
	v_pk_fma_f32 v[86:87], v[50:51], v[118:119], v[86:87] neg_lo:[1,0,0] neg_hi:[1,0,0]
	ds_read_b128 v[48:51], v28 offset:30272
	s_waitcnt lgkmcnt(11)
	v_pk_fma_f32 v[84:85], v[52:53], v[120:121], v[84:85] neg_lo:[1,0,0] neg_hi:[1,0,0]
	v_pk_fma_f32 v[86:87], v[54:55], v[122:123], v[86:87] neg_lo:[1,0,0] neg_hi:[1,0,0]
	ds_read_b128 v[52:55], v28 offset:30288
	s_waitcnt lgkmcnt(11)
	v_pk_fma_f32 v[84:85], v[56:57], v[124:125], v[84:85] neg_lo:[1,0,0] neg_hi:[1,0,0]
	v_pk_fma_f32 v[86:87], v[58:59], v[126:127], v[86:87] neg_lo:[1,0,0] neg_hi:[1,0,0]
	ds_read_b128 v[56:59], v28 offset:30304
	s_waitcnt lgkmcnt(11)
	v_pk_fma_f32 v[84:85], v[60:61], v[128:129], v[84:85] neg_lo:[1,0,0] neg_hi:[1,0,0]
	v_pk_fma_f32 v[86:87], v[62:63], v[130:131], v[86:87] neg_lo:[1,0,0] neg_hi:[1,0,0]
	ds_read_b128 v[60:63], v28 offset:30320
	s_waitcnt lgkmcnt(11)
	v_pk_fma_f32 v[84:85], v[64:65], v[132:133], v[84:85] neg_lo:[1,0,0] neg_hi:[1,0,0]
	v_pk_fma_f32 v[86:87], v[66:67], v[134:135], v[86:87] neg_lo:[1,0,0] neg_hi:[1,0,0]
	ds_read_b128 v[64:67], v28 offset:30336
	s_waitcnt lgkmcnt(11)
	v_pk_fma_f32 v[84:85], v[68:69], v[136:137], v[84:85] neg_lo:[1,0,0] neg_hi:[1,0,0]
	v_pk_fma_f32 v[86:87], v[70:71], v[138:139], v[86:87] neg_lo:[1,0,0] neg_hi:[1,0,0]
	ds_read_b128 v[68:71], v28 offset:30352
	s_waitcnt lgkmcnt(11)
	v_pk_fma_f32 v[84:85], v[72:73], v[140:141], v[84:85] neg_lo:[1,0,0] neg_hi:[1,0,0]
	v_pk_fma_f32 v[86:87], v[74:75], v[142:143], v[86:87] neg_lo:[1,0,0] neg_hi:[1,0,0]
	ds_read_b128 v[72:75], v28 offset:30368
	s_waitcnt lgkmcnt(11)
	v_fma_f32 v84, -v76, v144, v84
	ds_read_b128 v[76:79], v28 offset:30384
	v_add_f32_e32 v84, v84, v85
	v_add_f32_e32 v86, v86, v87
	v_add_f32_e32 v145, v84, v86
	v_cvt_pk_bf16_f32 v90, v145, v145
	global_store_short v[8:9], v90, off offset:1664
	v_cmp_eq_u32_e64 s[56:57], 46, v88
	s_waitcnt lgkmcnt(11)
	s_nop 0
	v_cndmask_b32_e64 v80, 0, 1.0, s[56:57]
	v_fma_f32 v80, -v100, v32, v80
	v_fma_f32 v81, -v33, v101, 0
	v_fma_f32 v82, -v34, v102, 0
	v_fma_f32 v83, -v35, v103, 0
	ds_read_b128 v[32:35], v28 offset:30464
	s_waitcnt lgkmcnt(11)
	v_pk_fma_f32 v[80:81], v[36:37], v[104:105], v[80:81] neg_lo:[1,0,0] neg_hi:[1,0,0]
	v_pk_fma_f32 v[82:83], v[38:39], v[106:107], v[82:83] neg_lo:[1,0,0] neg_hi:[1,0,0]
	ds_read_b128 v[36:39], v28 offset:30480
	s_waitcnt lgkmcnt(11)
	v_pk_fma_f32 v[80:81], v[40:41], v[108:109], v[80:81] neg_lo:[1,0,0] neg_hi:[1,0,0]
	v_pk_fma_f32 v[82:83], v[42:43], v[110:111], v[82:83] neg_lo:[1,0,0] neg_hi:[1,0,0]
	ds_read_b128 v[40:43], v28 offset:30496
	s_waitcnt lgkmcnt(11)
	v_pk_fma_f32 v[80:81], v[44:45], v[112:113], v[80:81] neg_lo:[1,0,0] neg_hi:[1,0,0]
	v_pk_fma_f32 v[82:83], v[46:47], v[114:115], v[82:83] neg_lo:[1,0,0] neg_hi:[1,0,0]
	ds_read_b128 v[44:47], v28 offset:30512
	s_waitcnt lgkmcnt(11)
	v_pk_fma_f32 v[80:81], v[48:49], v[116:117], v[80:81] neg_lo:[1,0,0] neg_hi:[1,0,0]
	v_pk_fma_f32 v[82:83], v[50:51], v[118:119], v[82:83] neg_lo:[1,0,0] neg_hi:[1,0,0]
	ds_read_b128 v[48:51], v28 offset:30528
	s_waitcnt lgkmcnt(11)
	v_pk_fma_f32 v[80:81], v[52:53], v[120:121], v[80:81] neg_lo:[1,0,0] neg_hi:[1,0,0]
	v_pk_fma_f32 v[82:83], v[54:55], v[122:123], v[82:83] neg_lo:[1,0,0] neg_hi:[1,0,0]
	ds_read_b128 v[52:55], v28 offset:30544
	s_waitcnt lgkmcnt(11)
	v_pk_fma_f32 v[80:81], v[56:57], v[124:125], v[80:81] neg_lo:[1,0,0] neg_hi:[1,0,0]
	v_pk_fma_f32 v[82:83], v[58:59], v[126:127], v[82:83] neg_lo:[1,0,0] neg_hi:[1,0,0]
	ds_read_b128 v[56:59], v28 offset:30560
	s_waitcnt lgkmcnt(11)
; #define LAS __attribute__((address_space(3)))
; __device__ __forceinline__ bf16_t f2bf(float f) { return (bf16_t)(pk2(f, f) & 0xFFFFu); }
; __device__ NOINL void g1_phase(const LAS Params* lp, int l, LAS unsigned char* lds) {
;     ...
;             for (int i = 0; i < 64; ++i) {
;                 float s0 = (i == lane) ? 1.f : 0.f, s1 = 0.f, s2 = 0.f, s3 = 0.f;
; #pragma unroll
;                 for (int j4 = 0; j4 < (i + 3) / 4; ++j4) {
;                     const f32x4 lv = *(const LAS f32x4*)(Ld + i * 64 + j4 * 4);
;                     if (j4 * 4 + 0 < i) s0 -= lv[0] * xv[j4 * 4 + 0];
;                     if (j4 * 4 + 1 < i) s1 -= lv[1] * xv[j4 * 4 + 1];
;                     if (j4 * 4 + 2 < i) s2 -= lv[2] * xv[j4 * 4 + 2];
;                     if (j4 * 4 + 3 < i) s3 -= lv[3] * xv[j4 * 4 + 3];
;                 }
;                 xv[i] = (s0 + s1) + (s2 + s3);
;             }
;             bf16_t* Tg = p.Tbuf + ((((size_t)b * 4 + h) * 36 + c3 * 3 + s) * 2 + dir) * 4096;
; #pragma unroll
;             for (int i = 0; i < 64; ++i) Tg[i * 64 + lane] = f2bf(xv[i]);
	v_pk_fma_f32 v[80:81], v[60:61], v[128:129], v[80:81] neg_lo:[1,0,0] neg_hi:[1,0,0]
	v_pk_fma_f32 v[82:83], v[62:63], v[130:131], v[82:83] neg_lo:[1,0,0] neg_hi:[1,0,0]
	ds_read_b128 v[60:63], v28 offset:30576
	s_waitcnt lgkmcnt(11)
	v_pk_fma_f32 v[80:81], v[64:65], v[132:133], v[80:81] neg_lo:[1,0,0] neg_hi:[1,0,0]
	v_pk_fma_f32 v[82:83], v[66:67], v[134:135], v[82:83] neg_lo:[1,0,0] neg_hi:[1,0,0]
	ds_read_b128 v[64:67], v28 offset:30592
	s_waitcnt lgkmcnt(11)
	v_pk_fma_f32 v[80:81], v[68:69], v[136:137], v[80:81] neg_lo:[1,0,0] neg_hi:[1,0,0]
	v_pk_fma_f32 v[82:83], v[70:71], v[138:139], v[82:83] neg_lo:[1,0,0] neg_hi:[1,0,0]
	ds_read_b128 v[68:71], v28 offset:30608
	s_waitcnt lgkmcnt(11)
	v_pk_fma_f32 v[80:81], v[72:73], v[140:141], v[80:81] neg_lo:[1,0,0] neg_hi:[1,0,0]
	v_pk_fma_f32 v[82:83], v[74:75], v[142:143], v[82:83] neg_lo:[1,0,0] neg_hi:[1,0,0]
	ds_read_b128 v[72:75], v28 offset:30624
	s_waitcnt lgkmcnt(11)
	v_pk_fma_f32 v[80:81], v[76:77], v[144:145], v[80:81] neg_lo:[1,0,0] neg_hi:[1,0,0]
	ds_read_b128 v[76:79], v28 offset:30640
	v_add_f32_e32 v80, v80, v81
	v_add_f32_e32 v82, v82, v83
	v_add_f32_e32 v146, v80, v82
	v_cvt_pk_bf16_f32 v91, v146, v146
	global_store_short v[8:9], v91, off offset:1792
	v_cmp_eq_u32_e64 s[56:57], 47, v88
	s_waitcnt lgkmcnt(11)
	s_nop 0
	v_cndmask_b32_e64 v84, 0, 1.0, s[56:57]
	v_fma_f32 v84, -v100, v32, v84
	v_fma_f32 v85, -v33, v101, 0
	v_fma_f32 v86, -v34, v102, 0
	v_fma_f32 v87, -v35, v103, 0
	ds_read_b128 v[32:35], v28 offset:30720
	s_waitcnt lgkmcnt(11)
	v_pk_fma_f32 v[84:85], v[36:37], v[104:105], v[84:85] neg_lo:[1,0,0] neg_hi:[1,0,0]
	v_pk_fma_f32 v[86:87], v[38:39], v[106:107], v[86:87] neg_lo:[1,0,0] neg_hi:[1,0,0]
	ds_read_b128 v[36:39], v28 offset:30736
	s_waitcnt lgkmcnt(11)
	v_pk_fma_f32 v[84:85], v[40:41], v[108:109], v[84:85] neg_lo:[1,0,0] neg_hi:[1,0,0]
	v_pk_fma_f32 v[86:87], v[42:43], v[110:111], v[86:87] neg_lo:[1,0,0] neg_hi:[1,0,0]
	ds_read_b128 v[40:43], v28 offset:30752
	s_waitcnt lgkmcnt(11)
	v_pk_fma_f32 v[84:85], v[44:45], v[112:113], v[84:85] neg_lo:[1,0,0] neg_hi:[1,0,0]
	v_pk_fma_f32 v[86:87], v[46:47], v[114:115], v[86:87] neg_lo:[1,0,0] neg_hi:[1,0,0]
	ds_read_b128 v[44:47], v28 offset:30768
	s_waitcnt lgkmcnt(11)
	v_pk_fma_f32 v[84:85], v[48:49], v[116:117], v[84:85] neg_lo:[1,0,0] neg_hi:[1,0,0]
	v_pk_fma_f32 v[86:87], v[50:51], v[118:119], v[86:87] neg_lo:[1,0,0] neg_hi:[1,0,0]
	ds_read_b128 v[48:51], v28 offset:30784
	s_waitcnt lgkmcnt(11)
	v_pk_fma_f32 v[84:85], v[52:53], v[120:121], v[84:85] neg_lo:[1,0,0] neg_hi:[1,0,0]
	v_pk_fma_f32 v[86:87], v[54:55], v[122:123], v[86:87] neg_lo:[1,0,0] neg_hi:[1,0,0]
	ds_read_b128 v[52:55], v28 offset:30800
	s_waitcnt lgkmcnt(11)
	v_pk_fma_f32 v[84:85], v[56:57], v[124:125], v[84:85] neg_lo:[1,0,0] neg_hi:[1,0,0]
	v_pk_fma_f32 v[86:87], v[58:59], v[126:127], v[86:87] neg_lo:[1,0,0] neg_hi:[1,0,0]
	ds_read_b128 v[56:59], v28 offset:30816
	s_waitcnt lgkmcnt(11)
	v_pk_fma_f32 v[84:85], v[60:61], v[128:129], v[84:85] neg_lo:[1,0,0] neg_hi:[1,0,0]
	v_pk_fma_f32 v[86:87], v[62:63], v[130:131], v[86:87] neg_lo:[1,0,0] neg_hi:[1,0,0]
	ds_read_b128 v[60:63], v28 offset:30832
	s_waitcnt lgkmcnt(11)
	v_pk_fma_f32 v[84:85], v[64:65], v[132:133], v[84:85] neg_lo:[1,0,0] neg_hi:[1,0,0]
	v_pk_fma_f32 v[86:87], v[66:67], v[134:135], v[86:87] neg_lo:[1,0,0] neg_hi:[1,0,0]
	ds_read_b128 v[64:67], v28 offset:30848
	s_waitcnt lgkmcnt(11)
	v_pk_fma_f32 v[84:85], v[68:69], v[136:137], v[84:85] neg_lo:[1,0,0] neg_hi:[1,0,0]
	v_pk_fma_f32 v[86:87], v[70:71], v[138:139], v[86:87] neg_lo:[1,0,0] neg_hi:[1,0,0]
	ds_read_b128 v[68:71], v28 offset:30864
	s_waitcnt lgkmcnt(11)
	v_pk_fma_f32 v[84:85], v[72:73], v[140:141], v[84:85] neg_lo:[1,0,0] neg_hi:[1,0,0]
	v_pk_fma_f32 v[86:87], v[74:75], v[142:143], v[86:87] neg_lo:[1,0,0] neg_hi:[1,0,0]
	ds_read_b128 v[72:75], v28 offset:30880
	s_waitcnt lgkmcnt(11)
	v_pk_fma_f32 v[84:85], v[76:77], v[144:145], v[84:85] neg_lo:[1,0,0] neg_hi:[1,0,0]
	v_fma_f32 v86, -v78, v146, v86
	ds_read_b128 v[76:79], v28 offset:30896
	v_add_f32_e32 v84, v84, v85
	v_add_f32_e32 v86, v86, v87
	v_add_f32_e32 v147, v84, v86
	v_cvt_pk_bf16_f32 v92, v147, v147
	global_store_short v[8:9], v92, off offset:1920
	v_cmp_eq_u32_e64 s[56:57], 48, v88
	s_waitcnt lgkmcnt(11)
	s_nop 0
	v_cndmask_b32_e64 v80, 0, 1.0, s[56:57]
	v_fma_f32 v80, -v100, v32, v80
	v_fma_f32 v81, -v33, v101, 0
	v_fma_f32 v82, -v34, v102, 0
	v_fma_f32 v83, -v35, v103, 0
	ds_read_b128 v[32:35], v28 offset:30976
	s_waitcnt lgkmcnt(11)
	v_pk_fma_f32 v[80:81], v[36:37], v[104:105], v[80:81] neg_lo:[1,0,0] neg_hi:[1,0,0]
	v_pk_fma_f32 v[82:83], v[38:39], v[106:107], v[82:83] neg_lo:[1,0,0] neg_hi:[1,0,0]
	ds_read_b128 v[36:39], v28 offset:30992
	s_waitcnt lgkmcnt(11)
	v_pk_fma_f32 v[80:81], v[40:41], v[108:109], v[80:81] neg_lo:[1,0,0] neg_hi:[1,0,0]
	v_pk_fma_f32 v[82:83], v[42:43], v[110:111], v[82:83] neg_lo:[1,0,0] neg_hi:[1,0,0]
	ds_read_b128 v[40:43], v28 offset:31008
	s_waitcnt lgkmcnt(11)
	v_pk_fma_f32 v[80:81], v[44:45], v[112:113], v[80:81] neg_lo:[1,0,0] neg_hi:[1,0,0]
	v_pk_fma_f32 v[82:83], v[46:47], v[114:115], v[82:83] neg_lo:[1,0,0] neg_hi:[1,0,0]
	ds_read_b128 v[44:47], v28 offset:31024
	s_waitcnt lgkmcnt(11)
	v_pk_fma_f32 v[80:81], v[48:49], v[116:117], v[80:81] neg_lo:[1,0,0] neg_hi:[1,0,0]
	v_pk_fma_f32 v[82:83], v[50:51], v[118:119], v[82:83] neg_lo:[1,0,0] neg_hi:[1,0,0]
	ds_read_b128 v[48:51], v28 offset:31040
	s_waitcnt lgkmcnt(11)
	v_pk_fma_f32 v[80:81], v[52:53], v[120:121], v[80:81] neg_lo:[1,0,0] neg_hi:[1,0,0]
	v_pk_fma_f32 v[82:83], v[54:55], v[122:123], v[82:83] neg_lo:[1,0,0] neg_hi:[1,0,0]
	ds_read_b128 v[52:55], v28 offset:31056
	s_waitcnt lgkmcnt(11)
; #define LAS __attribute__((address_space(3)))
; __device__ __forceinline__ bf16_t f2bf(float f) { return (bf16_t)(pk2(f, f) & 0xFFFFu); }
; __device__ NOINL void g1_phase(const LAS Params* lp, int l, LAS unsigned char* lds) {
;     ...
;             for (int i = 0; i < 64; ++i) {
;                 float s0 = (i == lane) ? 1.f : 0.f, s1 = 0.f, s2 = 0.f, s3 = 0.f;
; #pragma unroll
;                 for (int j4 = 0; j4 < (i + 3) / 4; ++j4) {
;                     const f32x4 lv = *(const LAS f32x4*)(Ld + i * 64 + j4 * 4);
;                     if (j4 * 4 + 0 < i) s0 -= lv[0] * xv[j4 * 4 + 0];
;                     if (j4 * 4 + 1 < i) s1 -= lv[1] * xv[j4 * 4 + 1];
;                     if (j4 * 4 + 2 < i) s2 -= lv[2] * xv[j4 * 4 + 2];
;                     if (j4 * 4 + 3 < i) s3 -= lv[3] * xv[j4 * 4 + 3];
;                 }
;                 xv[i] = (s0 + s1) + (s2 + s3);
;             }
;             bf16_t* Tg = p.Tbuf + ((((size_t)b * 4 + h) * 36 + c3 * 3 + s) * 2 + dir) * 4096;
; #pragma unroll
;             for (int i = 0; i < 64; ++i) Tg[i * 64 + lane] = f2bf(xv[i]);
	v_pk_fma_f32 v[80:81], v[56:57], v[124:125], v[80:81] neg_lo:[1,0,0] neg_hi:[1,0,0]
	v_pk_fma_f32 v[82:83], v[58:59], v[126:127], v[82:83] neg_lo:[1,0,0] neg_hi:[1,0,0]
	ds_read_b128 v[56:59], v28 offset:31072
	s_waitcnt lgkmcnt(11)
	v_pk_fma_f32 v[80:81], v[60:61], v[128:129], v[80:81] neg_lo:[1,0,0] neg_hi:[1,0,0]
	v_pk_fma_f32 v[82:83], v[62:63], v[130:131], v[82:83] neg_lo:[1,0,0] neg_hi:[1,0,0]
	ds_read_b128 v[60:63], v28 offset:31088
	s_waitcnt lgkmcnt(11)
	v_pk_fma_f32 v[80:81], v[64:65], v[132:133], v[80:81] neg_lo:[1,0,0] neg_hi:[1,0,0]
	v_pk_fma_f32 v[82:83], v[66:67], v[134:135], v[82:83] neg_lo:[1,0,0] neg_hi:[1,0,0]
	ds_read_b128 v[64:67], v28 offset:31104
	s_waitcnt lgkmcnt(11)
	v_pk_fma_f32 v[80:81], v[68:69], v[136:137], v[80:81] neg_lo:[1,0,0] neg_hi:[1,0,0]
	v_pk_fma_f32 v[82:83], v[70:71], v[138:139], v[82:83] neg_lo:[1,0,0] neg_hi:[1,0,0]
	ds_read_b128 v[68:71], v28 offset:31120
	s_waitcnt lgkmcnt(11)
	v_pk_fma_f32 v[80:81], v[72:73], v[140:141], v[80:81] neg_lo:[1,0,0] neg_hi:[1,0,0]
	v_pk_fma_f32 v[82:83], v[74:75], v[142:143], v[82:83] neg_lo:[1,0,0] neg_hi:[1,0,0]
	ds_read_b128 v[72:75], v28 offset:31136
	s_waitcnt lgkmcnt(11)
	v_pk_fma_f32 v[80:81], v[76:77], v[144:145], v[80:81] neg_lo:[1,0,0] neg_hi:[1,0,0]
	v_pk_fma_f32 v[82:83], v[78:79], v[146:147], v[82:83] neg_lo:[1,0,0] neg_hi:[1,0,0]
	ds_read_b128 v[76:79], v28 offset:31152
	v_add_f32_e32 v80, v80, v81
	v_add_f32_e32 v82, v82, v83
	v_add_f32_e32 v148, v80, v82
	v_cvt_pk_bf16_f32 v89, v148, v148
	global_store_short v[8:9], v89, off offset:2048
	v_cmp_eq_u32_e64 s[56:57], 49, v88
	s_waitcnt lgkmcnt(11)
	s_nop 0
	v_cndmask_b32_e64 v84, 0, 1.0, s[56:57]
	v_fma_f32 v84, -v100, v32, v84
	v_fma_f32 v85, -v33, v101, 0
	v_fma_f32 v86, -v34, v102, 0
	v_fma_f32 v87, -v35, v103, 0
	ds_read_b128 v[32:35], v28 offset:31168
	s_waitcnt lgkmcnt(11)
	v_pk_fma_f32 v[84:85], v[36:37], v[104:105], v[84:85] neg_lo:[1,0,0] neg_hi:[1,0,0]
	v_pk_fma_f32 v[86:87], v[38:39], v[106:107], v[86:87] neg_lo:[1,0,0] neg_hi:[1,0,0]
	ds_read_b128 v[36:39], v28 offset:31232
	s_waitcnt lgkmcnt(11)
	v_pk_fma_f32 v[84:85], v[40:41], v[108:109], v[84:85] neg_lo:[1,0,0] neg_hi:[1,0,0]
	v_pk_fma_f32 v[86:87], v[42:43], v[110:111], v[86:87] neg_lo:[1,0,0] neg_hi:[1,0,0]
	ds_read_b128 v[40:43], v28 offset:31248
	s_waitcnt lgkmcnt(11)
	v_pk_fma_f32 v[84:85], v[44:45], v[112:113], v[84:85] neg_lo:[1,0,0] neg_hi:[1,0,0]
	v_pk_fma_f32 v[86:87], v[46:47], v[114:115], v[86:87] neg_lo:[1,0,0] neg_hi:[1,0,0]
	ds_read_b128 v[44:47], v28 offset:31264
	s_waitcnt lgkmcnt(11)
	v_pk_fma_f32 v[84:85], v[48:49], v[116:117], v[84:85] neg_lo:[1,0,0] neg_hi:[1,0,0]
	v_pk_fma_f32 v[86:87], v[50:51], v[118:119], v[86:87] neg_lo:[1,0,0] neg_hi:[1,0,0]
	ds_read_b128 v[48:51], v28 offset:31280
	s_waitcnt lgkmcnt(11)
	v_pk_fma_f32 v[84:85], v[52:53], v[120:121], v[84:85] neg_lo:[1,0,0] neg_hi:[1,0,0]
	v_pk_fma_f32 v[86:87], v[54:55], v[122:123], v[86:87] neg_lo:[1,0,0] neg_hi:[1,0,0]
	ds_read_b128 v[52:55], v28 offset:31296
	s_waitcnt lgkmcnt(11)
	v_pk_fma_f32 v[84:85], v[56:57], v[124:125], v[84:85] neg_lo:[1,0,0] neg_hi:[1,0,0]
	v_pk_fma_f32 v[86:87], v[58:59], v[126:127], v[86:87] neg_lo:[1,0,0] neg_hi:[1,0,0]
	ds_read_b128 v[56:59], v28 offset:31312
	s_waitcnt lgkmcnt(11)
	v_pk_fma_f32 v[84:85], v[60:61], v[128:129], v[84:85] neg_lo:[1,0,0] neg_hi:[1,0,0]
	v_pk_fma_f32 v[86:87], v[62:63], v[130:131], v[86:87] neg_lo:[1,0,0] neg_hi:[1,0,0]
	ds_read_b128 v[60:63], v28 offset:31328
	s_waitcnt lgkmcnt(11)
	v_pk_fma_f32 v[84:85], v[64:65], v[132:133], v[84:85] neg_lo:[1,0,0] neg_hi:[1,0,0]
	v_pk_fma_f32 v[86:87], v[66:67], v[134:135], v[86:87] neg_lo:[1,0,0] neg_hi:[1,0,0]
	ds_read_b128 v[64:67], v28 offset:31344
	s_waitcnt lgkmcnt(11)
	v_pk_fma_f32 v[84:85], v[68:69], v[136:137], v[84:85] neg_lo:[1,0,0] neg_hi:[1,0,0]
	v_pk_fma_f32 v[86:87], v[70:71], v[138:139], v[86:87] neg_lo:[1,0,0] neg_hi:[1,0,0]
	ds_read_b128 v[68:71], v28 offset:31360
	s_waitcnt lgkmcnt(11)
	v_pk_fma_f32 v[84:85], v[72:73], v[140:141], v[84:85] neg_lo:[1,0,0] neg_hi:[1,0,0]
	v_pk_fma_f32 v[86:87], v[74:75], v[142:143], v[86:87] neg_lo:[1,0,0] neg_hi:[1,0,0]
	ds_read_b128 v[72:75], v28 offset:31376
	s_waitcnt lgkmcnt(11)
	v_pk_fma_f32 v[84:85], v[76:77], v[144:145], v[84:85] neg_lo:[1,0,0] neg_hi:[1,0,0]
	v_pk_fma_f32 v[86:87], v[78:79], v[146:147], v[86:87] neg_lo:[1,0,0] neg_hi:[1,0,0]
	ds_read_b128 v[76:79], v28 offset:31392
	s_waitcnt lgkmcnt(11)
	v_fma_f32 v84, -v32, v148, v84
	ds_read_b128 v[32:35], v28 offset:31408
	v_add_f32_e32 v84, v84, v85
	v_add_f32_e32 v86, v86, v87
	v_add_f32_e32 v149, v84, v86
	v_cvt_pk_bf16_f32 v90, v149, v149
	global_store_short v[8:9], v90, off offset:2176
	v_cmp_eq_u32_e64 s[56:57], 50, v88
	s_waitcnt lgkmcnt(11)
	s_nop 0
	v_cndmask_b32_e64 v80, 0, 1.0, s[56:57]
	v_fma_f32 v80, -v100, v36, v80
	v_fma_f32 v81, -v37, v101, 0
	v_fma_f32 v82, -v38, v102, 0
	v_fma_f32 v83, -v39, v103, 0
	ds_read_b128 v[36:39], v28 offset:31424
	s_waitcnt lgkmcnt(11)
	v_pk_fma_f32 v[80:81], v[40:41], v[104:105], v[80:81] neg_lo:[1,0,0] neg_hi:[1,0,0]
	v_pk_fma_f32 v[82:83], v[42:43], v[106:107], v[82:83] neg_lo:[1,0,0] neg_hi:[1,0,0]
	ds_read_b128 v[40:43], v28 offset:31488
	s_waitcnt lgkmcnt(11)
	v_pk_fma_f32 v[80:81], v[44:45], v[108:109], v[80:81] neg_lo:[1,0,0] neg_hi:[1,0,0]
	v_pk_fma_f32 v[82:83], v[46:47], v[110:111], v[82:83] neg_lo:[1,0,0] neg_hi:[1,0,0]
	ds_read_b128 v[44:47], v28 offset:31504
	s_waitcnt lgkmcnt(11)
	v_pk_fma_f32 v[80:81], v[48:49], v[112:113], v[80:81] neg_lo:[1,0,0] neg_hi:[1,0,0]
	v_pk_fma_f32 v[82:83], v[50:51], v[114:115], v[82:83] neg_lo:[1,0,0] neg_hi:[1,0,0]
	ds_read_b128 v[48:51], v28 offset:31520
	s_waitcnt lgkmcnt(11)
; #define LAS __attribute__((address_space(3)))
; __device__ __forceinline__ bf16_t f2bf(float f) { return (bf16_t)(pk2(f, f) & 0xFFFFu); }
; __device__ NOINL void g1_phase(const LAS Params* lp, int l, LAS unsigned char* lds) {
;     ...
;             for (int i = 0; i < 64; ++i) {
;                 float s0 = (i == lane) ? 1.f : 0.f, s1 = 0.f, s2 = 0.f, s3 = 0.f;
; #pragma unroll
;                 for (int j4 = 0; j4 < (i + 3) / 4; ++j4) {
;                     const f32x4 lv = *(const LAS f32x4*)(Ld + i * 64 + j4 * 4);
;                     if (j4 * 4 + 0 < i) s0 -= lv[0] * xv[j4 * 4 + 0];
;                     if (j4 * 4 + 1 < i) s1 -= lv[1] * xv[j4 * 4 + 1];
;                     if (j4 * 4 + 2 < i) s2 -= lv[2] * xv[j4 * 4 + 2];
;                     if (j4 * 4 + 3 < i) s3 -= lv[3] * xv[j4 * 4 + 3];
;                 }
;                 xv[i] = (s0 + s1) + (s2 + s3);
;             }
;             bf16_t* Tg = p.Tbuf + ((((size_t)b * 4 + h) * 36 + c3 * 3 + s) * 2 + dir) * 4096;
; #pragma unroll
;             for (int i = 0; i < 64; ++i) Tg[i * 64 + lane] = f2bf(xv[i]);
	v_pk_fma_f32 v[80:81], v[52:53], v[116:117], v[80:81] neg_lo:[1,0,0] neg_hi:[1,0,0]
	v_pk_fma_f32 v[82:83], v[54:55], v[118:119], v[82:83] neg_lo:[1,0,0] neg_hi:[1,0,0]
	ds_read_b128 v[52:55], v28 offset:31536
	s_waitcnt lgkmcnt(11)
	v_pk_fma_f32 v[80:81], v[56:57], v[120:121], v[80:81] neg_lo:[1,0,0] neg_hi:[1,0,0]
	v_pk_fma_f32 v[82:83], v[58:59], v[122:123], v[82:83] neg_lo:[1,0,0] neg_hi:[1,0,0]
	ds_read_b128 v[56:59], v28 offset:31552
	s_waitcnt lgkmcnt(11)
	v_pk_fma_f32 v[80:81], v[60:61], v[124:125], v[80:81] neg_lo:[1,0,0] neg_hi:[1,0,0]
	v_pk_fma_f32 v[82:83], v[62:63], v[126:127], v[82:83] neg_lo:[1,0,0] neg_hi:[1,0,0]
	ds_read_b128 v[60:63], v28 offset:31568
	s_waitcnt lgkmcnt(11)
	v_pk_fma_f32 v[80:81], v[64:65], v[128:129], v[80:81] neg_lo:[1,0,0] neg_hi:[1,0,0]
	v_pk_fma_f32 v[82:83], v[66:67], v[130:131], v[82:83] neg_lo:[1,0,0] neg_hi:[1,0,0]
	ds_read_b128 v[64:67], v28 offset:31584
	s_waitcnt lgkmcnt(11)
	v_pk_fma_f32 v[80:81], v[68:69], v[132:133], v[80:81] neg_lo:[1,0,0] neg_hi:[1,0,0]
	v_pk_fma_f32 v[82:83], v[70:71], v[134:135], v[82:83] neg_lo:[1,0,0] neg_hi:[1,0,0]
	ds_read_b128 v[68:71], v28 offset:31600
	s_waitcnt lgkmcnt(11)
	v_pk_fma_f32 v[80:81], v[72:73], v[136:137], v[80:81] neg_lo:[1,0,0] neg_hi:[1,0,0]
	v_pk_fma_f32 v[82:83], v[74:75], v[138:139], v[82:83] neg_lo:[1,0,0] neg_hi:[1,0,0]
	ds_read_b128 v[72:75], v28 offset:31616
	s_waitcnt lgkmcnt(11)
	v_pk_fma_f32 v[80:81], v[76:77], v[140:141], v[80:81] neg_lo:[1,0,0] neg_hi:[1,0,0]
	v_pk_fma_f32 v[82:83], v[78:79], v[142:143], v[82:83] neg_lo:[1,0,0] neg_hi:[1,0,0]
	ds_read_b128 v[76:79], v28 offset:31632
	s_waitcnt lgkmcnt(11)
	v_pk_fma_f32 v[80:81], v[32:33], v[144:145], v[80:81] neg_lo:[1,0,0] neg_hi:[1,0,0]
	v_pk_fma_f32 v[82:83], v[34:35], v[146:147], v[82:83] neg_lo:[1,0,0] neg_hi:[1,0,0]
	ds_read_b128 v[32:35], v28 offset:31648
	s_waitcnt lgkmcnt(11)
	v_pk_fma_f32 v[80:81], v[36:37], v[148:149], v[80:81] neg_lo:[1,0,0] neg_hi:[1,0,0]
	ds_read_b128 v[36:39], v28 offset:31664
	v_add_f32_e32 v80, v80, v81
	v_add_f32_e32 v82, v82, v83
	v_add_f32_e32 v150, v80, v82
	v_cvt_pk_bf16_f32 v91, v150, v150
	global_store_short v[8:9], v91, off offset:2304
	v_cmp_eq_u32_e64 s[56:57], 51, v88
	s_waitcnt lgkmcnt(11)
	s_nop 0
	v_cndmask_b32_e64 v84, 0, 1.0, s[56:57]
	v_fma_f32 v84, -v100, v40, v84
	v_fma_f32 v85, -v41, v101, 0
	v_fma_f32 v86, -v42, v102, 0
	v_fma_f32 v87, -v43, v103, 0
	ds_read_b128 v[40:43], v28 offset:31680
	s_waitcnt lgkmcnt(11)
	v_pk_fma_f32 v[84:85], v[44:45], v[104:105], v[84:85] neg_lo:[1,0,0] neg_hi:[1,0,0]
	v_pk_fma_f32 v[86:87], v[46:47], v[106:107], v[86:87] neg_lo:[1,0,0] neg_hi:[1,0,0]
	ds_read_b128 v[44:47], v28 offset:31744
	s_waitcnt lgkmcnt(11)
	v_pk_fma_f32 v[84:85], v[48:49], v[108:109], v[84:85] neg_lo:[1,0,0] neg_hi:[1,0,0]
	v_pk_fma_f32 v[86:87], v[50:51], v[110:111], v[86:87] neg_lo:[1,0,0] neg_hi:[1,0,0]
	ds_read_b128 v[48:51], v28 offset:31760
	s_waitcnt lgkmcnt(11)
	v_pk_fma_f32 v[84:85], v[52:53], v[112:113], v[84:85] neg_lo:[1,0,0] neg_hi:[1,0,0]
	v_pk_fma_f32 v[86:87], v[54:55], v[114:115], v[86:87] neg_lo:[1,0,0] neg_hi:[1,0,0]
	ds_read_b128 v[52:55], v28 offset:31776
	s_waitcnt lgkmcnt(11)
	v_pk_fma_f32 v[84:85], v[56:57], v[116:117], v[84:85] neg_lo:[1,0,0] neg_hi:[1,0,0]
	v_pk_fma_f32 v[86:87], v[58:59], v[118:119], v[86:87] neg_lo:[1,0,0] neg_hi:[1,0,0]
	ds_read_b128 v[56:59], v28 offset:31792
	s_waitcnt lgkmcnt(11)
	v_pk_fma_f32 v[84:85], v[60:61], v[120:121], v[84:85] neg_lo:[1,0,0] neg_hi:[1,0,0]
	v_pk_fma_f32 v[86:87], v[62:63], v[122:123], v[86:87] neg_lo:[1,0,0] neg_hi:[1,0,0]
	ds_read_b128 v[60:63], v28 offset:31808
	s_waitcnt lgkmcnt(11)
	v_pk_fma_f32 v[84:85], v[64:65], v[124:125], v[84:85] neg_lo:[1,0,0] neg_hi:[1,0,0]
	v_pk_fma_f32 v[86:87], v[66:67], v[126:127], v[86:87] neg_lo:[1,0,0] neg_hi:[1,0,0]
	ds_read_b128 v[64:67], v28 offset:31824
	s_waitcnt lgkmcnt(11)
	v_pk_fma_f32 v[84:85], v[68:69], v[128:129], v[84:85] neg_lo:[1,0,0] neg_hi:[1,0,0]
	v_pk_fma_f32 v[86:87], v[70:71], v[130:131], v[86:87] neg_lo:[1,0,0] neg_hi:[1,0,0]
	ds_read_b128 v[68:71], v28 offset:31840
	s_waitcnt lgkmcnt(11)
	v_pk_fma_f32 v[84:85], v[72:73], v[132:133], v[84:85] neg_lo:[1,0,0] neg_hi:[1,0,0]
	v_pk_fma_f32 v[86:87], v[74:75], v[134:135], v[86:87] neg_lo:[1,0,0] neg_hi:[1,0,0]
	ds_read_b128 v[72:75], v28 offset:31856
	s_waitcnt lgkmcnt(11)
	v_pk_fma_f32 v[84:85], v[76:77], v[136:137], v[84:85] neg_lo:[1,0,0] neg_hi:[1,0,0]
	v_pk_fma_f32 v[86:87], v[78:79], v[138:139], v[86:87] neg_lo:[1,0,0] neg_hi:[1,0,0]
	ds_read_b128 v[76:79], v28 offset:31872
	s_waitcnt lgkmcnt(11)
	v_pk_fma_f32 v[84:85], v[32:33], v[140:141], v[84:85] neg_lo:[1,0,0] neg_hi:[1,0,0]
	v_pk_fma_f32 v[86:87], v[34:35], v[142:143], v[86:87] neg_lo:[1,0,0] neg_hi:[1,0,0]
	ds_read_b128 v[32:35], v28 offset:31888
	s_waitcnt lgkmcnt(11)
	v_pk_fma_f32 v[84:85], v[36:37], v[144:145], v[84:85] neg_lo:[1,0,0] neg_hi:[1,0,0]
	v_pk_fma_f32 v[86:87], v[38:39], v[146:147], v[86:87] neg_lo:[1,0,0] neg_hi:[1,0,0]
	ds_read_b128 v[36:39], v28 offset:31904
	s_waitcnt lgkmcnt(11)
	v_pk_fma_f32 v[84:85], v[40:41], v[148:149], v[84:85] neg_lo:[1,0,0] neg_hi:[1,0,0]
	v_fma_f32 v86, -v42, v150, v86
	ds_read_b128 v[40:43], v28 offset:31920
	v_add_f32_e32 v84, v84, v85
	v_add_f32_e32 v86, v86, v87
	v_add_f32_e32 v151, v84, v86
	v_cvt_pk_bf16_f32 v92, v151, v151
	global_store_short v[8:9], v92, off offset:2432
	v_cmp_eq_u32_e64 s[56:57], 52, v88
	s_waitcnt lgkmcnt(11)
	s_nop 0
	v_cndmask_b32_e64 v80, 0, 1.0, s[56:57]
	v_fma_f32 v80, -v100, v44, v80
	v_fma_f32 v81, -v45, v101, 0
	v_fma_f32 v82, -v46, v102, 0
	v_fma_f32 v83, -v47, v103, 0
	ds_read_b128 v[44:47], v28 offset:31936
	s_waitcnt lgkmcnt(11)
; #define LAS __attribute__((address_space(3)))
; __device__ __forceinline__ bf16_t f2bf(float f) { return (bf16_t)(pk2(f, f) & 0xFFFFu); }
; __device__ NOINL void g1_phase(const LAS Params* lp, int l, LAS unsigned char* lds) {
;     ...
;             for (int i = 0; i < 64; ++i) {
;                 float s0 = (i == lane) ? 1.f : 0.f, s1 = 0.f, s2 = 0.f, s3 = 0.f;
; #pragma unroll
;                 for (int j4 = 0; j4 < (i + 3) / 4; ++j4) {
;                     const f32x4 lv = *(const LAS f32x4*)(Ld + i * 64 + j4 * 4);
;                     if (j4 * 4 + 0 < i) s0 -= lv[0] * xv[j4 * 4 + 0];
;                     if (j4 * 4 + 1 < i) s1 -= lv[1] * xv[j4 * 4 + 1];
;                     if (j4 * 4 + 2 < i) s2 -= lv[2] * xv[j4 * 4 + 2];
;                     if (j4 * 4 + 3 < i) s3 -= lv[3] * xv[j4 * 4 + 3];
;                 }
;                 xv[i] = (s0 + s1) + (s2 + s3);
;             }
;             bf16_t* Tg = p.Tbuf + ((((size_t)b * 4 + h) * 36 + c3 * 3 + s) * 2 + dir) * 4096;
; #pragma unroll
;             for (int i = 0; i < 64; ++i) Tg[i * 64 + lane] = f2bf(xv[i]);
	v_pk_fma_f32 v[80:81], v[48:49], v[104:105], v[80:81] neg_lo:[1,0,0] neg_hi:[1,0,0]
	v_pk_fma_f32 v[82:83], v[50:51], v[106:107], v[82:83] neg_lo:[1,0,0] neg_hi:[1,0,0]
	ds_read_b128 v[48:51], v28 offset:32000
	s_waitcnt lgkmcnt(11)
	v_pk_fma_f32 v[80:81], v[52:53], v[108:109], v[80:81] neg_lo:[1,0,0] neg_hi:[1,0,0]
	v_pk_fma_f32 v[82:83], v[54:55], v[110:111], v[82:83] neg_lo:[1,0,0] neg_hi:[1,0,0]
	ds_read_b128 v[52:55], v28 offset:32016
	s_waitcnt lgkmcnt(11)
	v_pk_fma_f32 v[80:81], v[56:57], v[112:113], v[80:81] neg_lo:[1,0,0] neg_hi:[1,0,0]
	v_pk_fma_f32 v[82:83], v[58:59], v[114:115], v[82:83] neg_lo:[1,0,0] neg_hi:[1,0,0]
	ds_read_b128 v[56:59], v28 offset:32032
	s_waitcnt lgkmcnt(11)
	v_pk_fma_f32 v[80:81], v[60:61], v[116:117], v[80:81] neg_lo:[1,0,0] neg_hi:[1,0,0]
	v_pk_fma_f32 v[82:83], v[62:63], v[118:119], v[82:83] neg_lo:[1,0,0] neg_hi:[1,0,0]
	ds_read_b128 v[60:63], v28 offset:32048
	s_waitcnt lgkmcnt(11)
	v_pk_fma_f32 v[80:81], v[64:65], v[120:121], v[80:81] neg_lo:[1,0,0] neg_hi:[1,0,0]
	v_pk_fma_f32 v[82:83], v[66:67], v[122:123], v[82:83] neg_lo:[1,0,0] neg_hi:[1,0,0]
	ds_read_b128 v[64:67], v28 offset:32064
	s_waitcnt lgkmcnt(11)
	v_pk_fma_f32 v[80:81], v[68:69], v[124:125], v[80:81] neg_lo:[1,0,0] neg_hi:[1,0,0]
	v_pk_fma_f32 v[82:83], v[70:71], v[126:127], v[82:83] neg_lo:[1,0,0] neg_hi:[1,0,0]
	ds_read_b128 v[68:71], v28 offset:32080
	s_waitcnt lgkmcnt(11)
	v_pk_fma_f32 v[80:81], v[72:73], v[128:129], v[80:81] neg_lo:[1,0,0] neg_hi:[1,0,0]
	v_pk_fma_f32 v[82:83], v[74:75], v[130:131], v[82:83] neg_lo:[1,0,0] neg_hi:[1,0,0]
	ds_read_b128 v[72:75], v28 offset:32096
	s_waitcnt lgkmcnt(11)
	v_pk_fma_f32 v[80:81], v[76:77], v[132:133], v[80:81] neg_lo:[1,0,0] neg_hi:[1,0,0]
	v_pk_fma_f32 v[82:83], v[78:79], v[134:135], v[82:83] neg_lo:[1,0,0] neg_hi:[1,0,0]
	ds_read_b128 v[76:79], v28 offset:32112
	s_waitcnt lgkmcnt(11)
	v_pk_fma_f32 v[80:81], v[32:33], v[136:137], v[80:81] neg_lo:[1,0,0] neg_hi:[1,0,0]
	v_pk_fma_f32 v[82:83], v[34:35], v[138:139], v[82:83] neg_lo:[1,0,0] neg_hi:[1,0,0]
	ds_read_b128 v[32:35], v28 offset:32128
	s_waitcnt lgkmcnt(11)
	v_pk_fma_f32 v[80:81], v[36:37], v[140:141], v[80:81] neg_lo:[1,0,0] neg_hi:[1,0,0]
	v_pk_fma_f32 v[82:83], v[38:39], v[142:143], v[82:83] neg_lo:[1,0,0] neg_hi:[1,0,0]
	ds_read_b128 v[36:39], v28 offset:32144
	s_waitcnt lgkmcnt(11)
	v_pk_fma_f32 v[80:81], v[40:41], v[144:145], v[80:81] neg_lo:[1,0,0] neg_hi:[1,0,0]
	v_pk_fma_f32 v[82:83], v[42:43], v[146:147], v[82:83] neg_lo:[1,0,0] neg_hi:[1,0,0]
	ds_read_b128 v[40:43], v28 offset:32160
	s_waitcnt lgkmcnt(11)
	v_pk_fma_f32 v[80:81], v[44:45], v[148:149], v[80:81] neg_lo:[1,0,0] neg_hi:[1,0,0]
	v_pk_fma_f32 v[82:83], v[46:47], v[150:151], v[82:83] neg_lo:[1,0,0] neg_hi:[1,0,0]
	ds_read_b128 v[44:47], v28 offset:32176
	v_add_f32_e32 v80, v80, v81
	v_add_f32_e32 v82, v82, v83
	v_add_f32_e32 v152, v80, v82
	v_cvt_pk_bf16_f32 v89, v152, v152
	global_store_short v[8:9], v89, off offset:2560
	v_cmp_eq_u32_e64 s[56:57], 53, v88
	s_waitcnt lgkmcnt(11)
	s_nop 0
	v_cndmask_b32_e64 v84, 0, 1.0, s[56:57]
	v_fma_f32 v84, -v100, v48, v84
	v_fma_f32 v85, -v49, v101, 0
	v_fma_f32 v86, -v50, v102, 0
	v_fma_f32 v87, -v51, v103, 0
	ds_read_b128 v[48:51], v28 offset:32192
	s_waitcnt lgkmcnt(11)
	v_pk_fma_f32 v[84:85], v[52:53], v[104:105], v[84:85] neg_lo:[1,0,0] neg_hi:[1,0,0]
	v_pk_fma_f32 v[86:87], v[54:55], v[106:107], v[86:87] neg_lo:[1,0,0] neg_hi:[1,0,0]
	ds_read_b128 v[52:55], v28 offset:32208
	s_waitcnt lgkmcnt(11)
	v_pk_fma_f32 v[84:85], v[56:57], v[108:109], v[84:85] neg_lo:[1,0,0] neg_hi:[1,0,0]
	v_pk_fma_f32 v[86:87], v[58:59], v[110:111], v[86:87] neg_lo:[1,0,0] neg_hi:[1,0,0]
	ds_read_b128 v[56:59], v28 offset:32256
	s_waitcnt lgkmcnt(11)
	v_pk_fma_f32 v[84:85], v[60:61], v[112:113], v[84:85] neg_lo:[1,0,0] neg_hi:[1,0,0]
	v_pk_fma_f32 v[86:87], v[62:63], v[114:115], v[86:87] neg_lo:[1,0,0] neg_hi:[1,0,0]
	ds_read_b128 v[60:63], v28 offset:32272
	s_waitcnt lgkmcnt(11)
	v_pk_fma_f32 v[84:85], v[64:65], v[116:117], v[84:85] neg_lo:[1,0,0] neg_hi:[1,0,0]
	v_pk_fma_f32 v[86:87], v[66:67], v[118:119], v[86:87] neg_lo:[1,0,0] neg_hi:[1,0,0]
	ds_read_b128 v[64:67], v28 offset:32288
	s_waitcnt lgkmcnt(11)
	v_pk_fma_f32 v[84:85], v[68:69], v[120:121], v[84:85] neg_lo:[1,0,0] neg_hi:[1,0,0]
	v_pk_fma_f32 v[86:87], v[70:71], v[122:123], v[86:87] neg_lo:[1,0,0] neg_hi:[1,0,0]
	ds_read_b128 v[68:71], v28 offset:32304
	s_waitcnt lgkmcnt(11)
	v_pk_fma_f32 v[84:85], v[72:73], v[124:125], v[84:85] neg_lo:[1,0,0] neg_hi:[1,0,0]
	v_pk_fma_f32 v[86:87], v[74:75], v[126:127], v[86:87] neg_lo:[1,0,0] neg_hi:[1,0,0]
	ds_read_b128 v[72:75], v28 offset:32320
	s_waitcnt lgkmcnt(11)
	v_pk_fma_f32 v[84:85], v[76:77], v[128:129], v[84:85] neg_lo:[1,0,0] neg_hi:[1,0,0]
	v_pk_fma_f32 v[86:87], v[78:79], v[130:131], v[86:87] neg_lo:[1,0,0] neg_hi:[1,0,0]
	ds_read_b128 v[76:79], v28 offset:32336
	s_waitcnt lgkmcnt(11)
	v_pk_fma_f32 v[84:85], v[32:33], v[132:133], v[84:85] neg_lo:[1,0,0] neg_hi:[1,0,0]
	v_pk_fma_f32 v[86:87], v[34:35], v[134:135], v[86:87] neg_lo:[1,0,0] neg_hi:[1,0,0]
	ds_read_b128 v[32:35], v28 offset:32352
	s_waitcnt lgkmcnt(11)
	v_pk_fma_f32 v[84:85], v[36:37], v[136:137], v[84:85] neg_lo:[1,0,0] neg_hi:[1,0,0]
	v_pk_fma_f32 v[86:87], v[38:39], v[138:139], v[86:87] neg_lo:[1,0,0] neg_hi:[1,0,0]
	ds_read_b128 v[36:39], v28 offset:32368
	s_waitcnt lgkmcnt(11)
	v_pk_fma_f32 v[84:85], v[40:41], v[140:141], v[84:85] neg_lo:[1,0,0] neg_hi:[1,0,0]
	v_pk_fma_f32 v[86:87], v[42:43], v[142:143], v[86:87] neg_lo:[1,0,0] neg_hi:[1,0,0]
	ds_read_b128 v[40:43], v28 offset:32384
	s_waitcnt lgkmcnt(11)
; #define LAS __attribute__((address_space(3)))
; __device__ __forceinline__ bf16_t f2bf(float f) { return (bf16_t)(pk2(f, f) & 0xFFFFu); }
; __device__ NOINL void g1_phase(const LAS Params* lp, int l, LAS unsigned char* lds) {
;     ...
;             for (int i = 0; i < 64; ++i) {
;                 float s0 = (i == lane) ? 1.f : 0.f, s1 = 0.f, s2 = 0.f, s3 = 0.f;
; #pragma unroll
;                 for (int j4 = 0; j4 < (i + 3) / 4; ++j4) {
;                     const f32x4 lv = *(const LAS f32x4*)(Ld + i * 64 + j4 * 4);
;                     if (j4 * 4 + 0 < i) s0 -= lv[0] * xv[j4 * 4 + 0];
;                     if (j4 * 4 + 1 < i) s1 -= lv[1] * xv[j4 * 4 + 1];
;                     if (j4 * 4 + 2 < i) s2 -= lv[2] * xv[j4 * 4 + 2];
;                     if (j4 * 4 + 3 < i) s3 -= lv[3] * xv[j4 * 4 + 3];
;                 }
;                 xv[i] = (s0 + s1) + (s2 + s3);
;             }
;             bf16_t* Tg = p.Tbuf + ((((size_t)b * 4 + h) * 36 + c3 * 3 + s) * 2 + dir) * 4096;
; #pragma unroll
;             for (int i = 0; i < 64; ++i) Tg[i * 64 + lane] = f2bf(xv[i]);
	v_pk_fma_f32 v[84:85], v[44:45], v[144:145], v[84:85] neg_lo:[1,0,0] neg_hi:[1,0,0]
	v_pk_fma_f32 v[86:87], v[46:47], v[146:147], v[86:87] neg_lo:[1,0,0] neg_hi:[1,0,0]
	ds_read_b128 v[44:47], v28 offset:32400
	s_waitcnt lgkmcnt(11)
	v_pk_fma_f32 v[84:85], v[48:49], v[148:149], v[84:85] neg_lo:[1,0,0] neg_hi:[1,0,0]
	v_pk_fma_f32 v[86:87], v[50:51], v[150:151], v[86:87] neg_lo:[1,0,0] neg_hi:[1,0,0]
	ds_read_b128 v[48:51], v28 offset:32416
	s_waitcnt lgkmcnt(11)
	v_fma_f32 v84, -v52, v152, v84
	ds_read_b128 v[52:55], v28 offset:32432
	v_add_f32_e32 v84, v84, v85
	v_add_f32_e32 v86, v86, v87
	v_add_f32_e32 v153, v84, v86
	v_cvt_pk_bf16_f32 v90, v153, v153
	global_store_short v[8:9], v90, off offset:2688
	v_cmp_eq_u32_e64 s[56:57], 54, v88
	s_waitcnt lgkmcnt(11)
	s_nop 0
	v_cndmask_b32_e64 v80, 0, 1.0, s[56:57]
	v_fma_f32 v80, -v100, v56, v80
	v_fma_f32 v81, -v57, v101, 0
	v_fma_f32 v82, -v58, v102, 0
	v_fma_f32 v83, -v59, v103, 0
	ds_read_b128 v[56:59], v28 offset:32448
	s_waitcnt lgkmcnt(11)
	v_pk_fma_f32 v[80:81], v[60:61], v[104:105], v[80:81] neg_lo:[1,0,0] neg_hi:[1,0,0]
	v_pk_fma_f32 v[82:83], v[62:63], v[106:107], v[82:83] neg_lo:[1,0,0] neg_hi:[1,0,0]
	ds_read_b128 v[60:63], v28 offset:32464
	s_waitcnt lgkmcnt(11)
	v_pk_fma_f32 v[80:81], v[64:65], v[108:109], v[80:81] neg_lo:[1,0,0] neg_hi:[1,0,0]
	v_pk_fma_f32 v[82:83], v[66:67], v[110:111], v[82:83] neg_lo:[1,0,0] neg_hi:[1,0,0]
	ds_read_b128 v[64:67], v28 offset:32512
	s_waitcnt lgkmcnt(11)
	v_pk_fma_f32 v[80:81], v[68:69], v[112:113], v[80:81] neg_lo:[1,0,0] neg_hi:[1,0,0]
	v_pk_fma_f32 v[82:83], v[70:71], v[114:115], v[82:83] neg_lo:[1,0,0] neg_hi:[1,0,0]
	ds_read_b128 v[68:71], v28 offset:32528
	s_waitcnt lgkmcnt(11)
	v_pk_fma_f32 v[80:81], v[72:73], v[116:117], v[80:81] neg_lo:[1,0,0] neg_hi:[1,0,0]
	v_pk_fma_f32 v[82:83], v[74:75], v[118:119], v[82:83] neg_lo:[1,0,0] neg_hi:[1,0,0]
	ds_read_b128 v[72:75], v28 offset:32544
	s_waitcnt lgkmcnt(11)
	v_pk_fma_f32 v[80:81], v[76:77], v[120:121], v[80:81] neg_lo:[1,0,0] neg_hi:[1,0,0]
	v_pk_fma_f32 v[82:83], v[78:79], v[122:123], v[82:83] neg_lo:[1,0,0] neg_hi:[1,0,0]
	ds_read_b128 v[76:79], v28 offset:32560
	s_waitcnt lgkmcnt(11)
	v_pk_fma_f32 v[80:81], v[32:33], v[124:125], v[80:81] neg_lo:[1,0,0] neg_hi:[1,0,0]
	v_pk_fma_f32 v[82:83], v[34:35], v[126:127], v[82:83] neg_lo:[1,0,0] neg_hi:[1,0,0]
	ds_read_b128 v[32:35], v28 offset:32576
	s_waitcnt lgkmcnt(11)
	v_pk_fma_f32 v[80:81], v[36:37], v[128:129], v[80:81] neg_lo:[1,0,0] neg_hi:[1,0,0]
	v_pk_fma_f32 v[82:83], v[38:39], v[130:131], v[82:83] neg_lo:[1,0,0] neg_hi:[1,0,0]
	ds_read_b128 v[36:39], v28 offset:32592
	s_waitcnt lgkmcnt(11)
	v_pk_fma_f32 v[80:81], v[40:41], v[132:133], v[80:81] neg_lo:[1,0,0] neg_hi:[1,0,0]
	v_pk_fma_f32 v[82:83], v[42:43], v[134:135], v[82:83] neg_lo:[1,0,0] neg_hi:[1,0,0]
	ds_read_b128 v[40:43], v28 offset:32608
	s_waitcnt lgkmcnt(11)
	v_pk_fma_f32 v[80:81], v[44:45], v[136:137], v[80:81] neg_lo:[1,0,0] neg_hi:[1,0,0]
	v_pk_fma_f32 v[82:83], v[46:47], v[138:139], v[82:83] neg_lo:[1,0,0] neg_hi:[1,0,0]
	ds_read_b128 v[44:47], v28 offset:32624
	s_waitcnt lgkmcnt(11)
	v_pk_fma_f32 v[80:81], v[48:49], v[140:141], v[80:81] neg_lo:[1,0,0] neg_hi:[1,0,0]
	v_pk_fma_f32 v[82:83], v[50:51], v[142:143], v[82:83] neg_lo:[1,0,0] neg_hi:[1,0,0]
	ds_read_b128 v[48:51], v28 offset:32640
	s_waitcnt lgkmcnt(11)
	v_pk_fma_f32 v[80:81], v[52:53], v[144:145], v[80:81] neg_lo:[1,0,0] neg_hi:[1,0,0]
	v_pk_fma_f32 v[82:83], v[54:55], v[146:147], v[82:83] neg_lo:[1,0,0] neg_hi:[1,0,0]
	ds_read_b128 v[52:55], v28 offset:32656
	s_waitcnt lgkmcnt(11)
	v_pk_fma_f32 v[80:81], v[56:57], v[148:149], v[80:81] neg_lo:[1,0,0] neg_hi:[1,0,0]
	v_pk_fma_f32 v[82:83], v[58:59], v[150:151], v[82:83] neg_lo:[1,0,0] neg_hi:[1,0,0]
	ds_read_b128 v[56:59], v28 offset:32672
	s_waitcnt lgkmcnt(11)
	v_pk_fma_f32 v[80:81], v[60:61], v[152:153], v[80:81] neg_lo:[1,0,0] neg_hi:[1,0,0]
	ds_read_b128 v[60:63], v28 offset:32688
	v_add_f32_e32 v80, v80, v81
	v_add_f32_e32 v82, v82, v83
	v_add_f32_e32 v154, v80, v82
	v_cvt_pk_bf16_f32 v91, v154, v154
	global_store_short v[8:9], v91, off offset:2816
	v_cmp_eq_u32_e64 s[56:57], 55, v88
	s_waitcnt lgkmcnt(11)
	s_nop 0
	v_cndmask_b32_e64 v84, 0, 1.0, s[56:57]
	v_fma_f32 v84, -v100, v64, v84
	v_fma_f32 v85, -v65, v101, 0
	v_fma_f32 v86, -v66, v102, 0
	v_fma_f32 v87, -v67, v103, 0
	ds_read_b128 v[64:67], v28 offset:32704
	s_waitcnt lgkmcnt(11)
	v_pk_fma_f32 v[84:85], v[68:69], v[104:105], v[84:85] neg_lo:[1,0,0] neg_hi:[1,0,0]
	v_pk_fma_f32 v[86:87], v[70:71], v[106:107], v[86:87] neg_lo:[1,0,0] neg_hi:[1,0,0]
	ds_read_b128 v[68:71], v28 offset:32720
	s_waitcnt lgkmcnt(11)
	v_pk_fma_f32 v[84:85], v[72:73], v[108:109], v[84:85] neg_lo:[1,0,0] neg_hi:[1,0,0]
	v_pk_fma_f32 v[86:87], v[74:75], v[110:111], v[86:87] neg_lo:[1,0,0] neg_hi:[1,0,0]
	ds_read_b128 v[72:75], v28 offset:32768
	s_waitcnt lgkmcnt(11)
	v_pk_fma_f32 v[84:85], v[76:77], v[112:113], v[84:85] neg_lo:[1,0,0] neg_hi:[1,0,0]
	v_pk_fma_f32 v[86:87], v[78:79], v[114:115], v[86:87] neg_lo:[1,0,0] neg_hi:[1,0,0]
	ds_read_b128 v[76:79], v28 offset:32784
	s_waitcnt lgkmcnt(11)
	v_pk_fma_f32 v[84:85], v[32:33], v[116:117], v[84:85] neg_lo:[1,0,0] neg_hi:[1,0,0]
	v_pk_fma_f32 v[86:87], v[34:35], v[118:119], v[86:87] neg_lo:[1,0,0] neg_hi:[1,0,0]
	ds_read_b128 v[32:35], v28 offset:32800
	s_waitcnt lgkmcnt(11)
	v_pk_fma_f32 v[84:85], v[36:37], v[120:121], v[84:85] neg_lo:[1,0,0] neg_hi:[1,0,0]
	v_pk_fma_f32 v[86:87], v[38:39], v[122:123], v[86:87] neg_lo:[1,0,0] neg_hi:[1,0,0]
	ds_read_b128 v[36:39], v28 offset:32816
	s_waitcnt lgkmcnt(11)
; #define LAS __attribute__((address_space(3)))
; __device__ __forceinline__ bf16_t f2bf(float f) { return (bf16_t)(pk2(f, f) & 0xFFFFu); }
; __device__ NOINL void g1_phase(const LAS Params* lp, int l, LAS unsigned char* lds) {
;     ...
;             for (int i = 0; i < 64; ++i) {
;                 float s0 = (i == lane) ? 1.f : 0.f, s1 = 0.f, s2 = 0.f, s3 = 0.f;
; #pragma unroll
;                 for (int j4 = 0; j4 < (i + 3) / 4; ++j4) {
;                     const f32x4 lv = *(const LAS f32x4*)(Ld + i * 64 + j4 * 4);
;                     if (j4 * 4 + 0 < i) s0 -= lv[0] * xv[j4 * 4 + 0];
;                     if (j4 * 4 + 1 < i) s1 -= lv[1] * xv[j4 * 4 + 1];
;                     if (j4 * 4 + 2 < i) s2 -= lv[2] * xv[j4 * 4 + 2];
;                     if (j4 * 4 + 3 < i) s3 -= lv[3] * xv[j4 * 4 + 3];
;                 }
;                 xv[i] = (s0 + s1) + (s2 + s3);
;             }
;             bf16_t* Tg = p.Tbuf + ((((size_t)b * 4 + h) * 36 + c3 * 3 + s) * 2 + dir) * 4096;
; #pragma unroll
;             for (int i = 0; i < 64; ++i) Tg[i * 64 + lane] = f2bf(xv[i]);
	v_pk_fma_f32 v[84:85], v[40:41], v[124:125], v[84:85] neg_lo:[1,0,0] neg_hi:[1,0,0]
	v_pk_fma_f32 v[86:87], v[42:43], v[126:127], v[86:87] neg_lo:[1,0,0] neg_hi:[1,0,0]
	ds_read_b128 v[40:43], v28 offset:32832
	s_waitcnt lgkmcnt(11)
	v_pk_fma_f32 v[84:85], v[44:45], v[128:129], v[84:85] neg_lo:[1,0,0] neg_hi:[1,0,0]
	v_pk_fma_f32 v[86:87], v[46:47], v[130:131], v[86:87] neg_lo:[1,0,0] neg_hi:[1,0,0]
	ds_read_b128 v[44:47], v28 offset:32848
	s_waitcnt lgkmcnt(11)
	v_pk_fma_f32 v[84:85], v[48:49], v[132:133], v[84:85] neg_lo:[1,0,0] neg_hi:[1,0,0]
	v_pk_fma_f32 v[86:87], v[50:51], v[134:135], v[86:87] neg_lo:[1,0,0] neg_hi:[1,0,0]
	ds_read_b128 v[48:51], v28 offset:32864
	s_waitcnt lgkmcnt(11)
	v_pk_fma_f32 v[84:85], v[52:53], v[136:137], v[84:85] neg_lo:[1,0,0] neg_hi:[1,0,0]
	v_pk_fma_f32 v[86:87], v[54:55], v[138:139], v[86:87] neg_lo:[1,0,0] neg_hi:[1,0,0]
	ds_read_b128 v[52:55], v28 offset:32880
	s_waitcnt lgkmcnt(11)
	v_pk_fma_f32 v[84:85], v[56:57], v[140:141], v[84:85] neg_lo:[1,0,0] neg_hi:[1,0,0]
	v_pk_fma_f32 v[86:87], v[58:59], v[142:143], v[86:87] neg_lo:[1,0,0] neg_hi:[1,0,0]
	ds_read_b128 v[56:59], v28 offset:32896
	s_waitcnt lgkmcnt(11)
	v_pk_fma_f32 v[84:85], v[60:61], v[144:145], v[84:85] neg_lo:[1,0,0] neg_hi:[1,0,0]
	v_pk_fma_f32 v[86:87], v[62:63], v[146:147], v[86:87] neg_lo:[1,0,0] neg_hi:[1,0,0]
	ds_read_b128 v[60:63], v28 offset:32912
	s_waitcnt lgkmcnt(11)
	v_pk_fma_f32 v[84:85], v[64:65], v[148:149], v[84:85] neg_lo:[1,0,0] neg_hi:[1,0,0]
	v_pk_fma_f32 v[86:87], v[66:67], v[150:151], v[86:87] neg_lo:[1,0,0] neg_hi:[1,0,0]
	ds_read_b128 v[64:67], v28 offset:32928
	s_waitcnt lgkmcnt(11)
	v_pk_fma_f32 v[84:85], v[68:69], v[152:153], v[84:85] neg_lo:[1,0,0] neg_hi:[1,0,0]
	v_fma_f32 v86, -v70, v154, v86
	ds_read_b128 v[68:71], v28 offset:32944
	v_add_f32_e32 v84, v84, v85
	v_add_f32_e32 v86, v86, v87
	v_add_f32_e32 v155, v84, v86
	v_cvt_pk_bf16_f32 v92, v155, v155
	global_store_short v[8:9], v92, off offset:2944
	v_cmp_eq_u32_e64 s[56:57], 56, v88
	s_waitcnt lgkmcnt(11)
	s_nop 0
	v_cndmask_b32_e64 v80, 0, 1.0, s[56:57]
	v_fma_f32 v80, -v100, v72, v80
	v_fma_f32 v81, -v73, v101, 0
	v_fma_f32 v82, -v74, v102, 0
	v_fma_f32 v83, -v75, v103, 0
	ds_read_b128 v[72:75], v28 offset:32960
	s_waitcnt lgkmcnt(11)
	v_pk_fma_f32 v[80:81], v[76:77], v[104:105], v[80:81] neg_lo:[1,0,0] neg_hi:[1,0,0]
	v_pk_fma_f32 v[82:83], v[78:79], v[106:107], v[82:83] neg_lo:[1,0,0] neg_hi:[1,0,0]
	ds_read_b128 v[76:79], v28 offset:32976
	s_waitcnt lgkmcnt(11)
	v_pk_fma_f32 v[80:81], v[32:33], v[108:109], v[80:81] neg_lo:[1,0,0] neg_hi:[1,0,0]
	v_pk_fma_f32 v[82:83], v[34:35], v[110:111], v[82:83] neg_lo:[1,0,0] neg_hi:[1,0,0]
	ds_read_b128 v[32:35], v28 offset:33024
	s_waitcnt lgkmcnt(11)
	v_pk_fma_f32 v[80:81], v[36:37], v[112:113], v[80:81] neg_lo:[1,0,0] neg_hi:[1,0,0]
	v_pk_fma_f32 v[82:83], v[38:39], v[114:115], v[82:83] neg_lo:[1,0,0] neg_hi:[1,0,0]
	ds_read_b128 v[36:39], v28 offset:33040
	s_waitcnt lgkmcnt(11)
	v_pk_fma_f32 v[80:81], v[40:41], v[116:117], v[80:81] neg_lo:[1,0,0] neg_hi:[1,0,0]
	v_pk_fma_f32 v[82:83], v[42:43], v[118:119], v[82:83] neg_lo:[1,0,0] neg_hi:[1,0,0]
	ds_read_b128 v[40:43], v28 offset:33056
	s_waitcnt lgkmcnt(11)
	v_pk_fma_f32 v[80:81], v[44:45], v[120:121], v[80:81] neg_lo:[1,0,0] neg_hi:[1,0,0]
	v_pk_fma_f32 v[82:83], v[46:47], v[122:123], v[82:83] neg_lo:[1,0,0] neg_hi:[1,0,0]
	ds_read_b128 v[44:47], v28 offset:33072
	s_waitcnt lgkmcnt(11)
	v_pk_fma_f32 v[80:81], v[48:49], v[124:125], v[80:81] neg_lo:[1,0,0] neg_hi:[1,0,0]
	v_pk_fma_f32 v[82:83], v[50:51], v[126:127], v[82:83] neg_lo:[1,0,0] neg_hi:[1,0,0]
	ds_read_b128 v[48:51], v28 offset:33088
	s_waitcnt lgkmcnt(11)
	v_pk_fma_f32 v[80:81], v[52:53], v[128:129], v[80:81] neg_lo:[1,0,0] neg_hi:[1,0,0]
	v_pk_fma_f32 v[82:83], v[54:55], v[130:131], v[82:83] neg_lo:[1,0,0] neg_hi:[1,0,0]
	ds_read_b128 v[52:55], v28 offset:33104
	s_waitcnt lgkmcnt(11)
	v_pk_fma_f32 v[80:81], v[56:57], v[132:133], v[80:81] neg_lo:[1,0,0] neg_hi:[1,0,0]
	v_pk_fma_f32 v[82:83], v[58:59], v[134:135], v[82:83] neg_lo:[1,0,0] neg_hi:[1,0,0]
	ds_read_b128 v[56:59], v28 offset:33120
	s_waitcnt lgkmcnt(11)
	v_pk_fma_f32 v[80:81], v[60:61], v[136:137], v[80:81] neg_lo:[1,0,0] neg_hi:[1,0,0]
	v_pk_fma_f32 v[82:83], v[62:63], v[138:139], v[82:83] neg_lo:[1,0,0] neg_hi:[1,0,0]
	ds_read_b128 v[60:63], v28 offset:33136
	s_waitcnt lgkmcnt(11)
	v_pk_fma_f32 v[80:81], v[64:65], v[140:141], v[80:81] neg_lo:[1,0,0] neg_hi:[1,0,0]
	v_pk_fma_f32 v[82:83], v[66:67], v[142:143], v[82:83] neg_lo:[1,0,0] neg_hi:[1,0,0]
	ds_read_b128 v[64:67], v28 offset:33152
	s_waitcnt lgkmcnt(11)
	v_pk_fma_f32 v[80:81], v[68:69], v[144:145], v[80:81] neg_lo:[1,0,0] neg_hi:[1,0,0]
	v_pk_fma_f32 v[82:83], v[70:71], v[146:147], v[82:83] neg_lo:[1,0,0] neg_hi:[1,0,0]
	ds_read_b128 v[68:71], v28 offset:33168
	s_waitcnt lgkmcnt(11)
	v_pk_fma_f32 v[80:81], v[72:73], v[148:149], v[80:81] neg_lo:[1,0,0] neg_hi:[1,0,0]
	v_pk_fma_f32 v[82:83], v[74:75], v[150:151], v[82:83] neg_lo:[1,0,0] neg_hi:[1,0,0]
	ds_read_b128 v[72:75], v28 offset:33184
	s_waitcnt lgkmcnt(11)
	v_pk_fma_f32 v[80:81], v[76:77], v[152:153], v[80:81] neg_lo:[1,0,0] neg_hi:[1,0,0]
	v_pk_fma_f32 v[82:83], v[78:79], v[154:155], v[82:83] neg_lo:[1,0,0] neg_hi:[1,0,0]
	ds_read_b128 v[76:79], v28 offset:33200
	v_add_f32_e32 v80, v80, v81
	v_add_f32_e32 v82, v82, v83
	v_add_f32_e32 v156, v80, v82
	v_cvt_pk_bf16_f32 v89, v156, v156
	global_store_short v[8:9], v89, off offset:3072
	v_cmp_eq_u32_e64 s[56:57], 57, v88
	s_waitcnt lgkmcnt(11)
	s_nop 0
	v_cndmask_b32_e64 v84, 0, 1.0, s[56:57]
	v_fma_f32 v84, -v100, v32, v84
	v_fma_f32 v85, -v33, v101, 0
	v_fma_f32 v86, -v34, v102, 0
	v_fma_f32 v87, -v35, v103, 0
	ds_read_b128 v[32:35], v28 offset:33216
	s_waitcnt lgkmcnt(11)
; #define LAS __attribute__((address_space(3)))
; __device__ __forceinline__ bf16_t f2bf(float f) { return (bf16_t)(pk2(f, f) & 0xFFFFu); }
; __device__ NOINL void g1_phase(const LAS Params* lp, int l, LAS unsigned char* lds) {
;     ...
;             for (int i = 0; i < 64; ++i) {
;                 float s0 = (i == lane) ? 1.f : 0.f, s1 = 0.f, s2 = 0.f, s3 = 0.f;
; #pragma unroll
;                 for (int j4 = 0; j4 < (i + 3) / 4; ++j4) {
;                     const f32x4 lv = *(const LAS f32x4*)(Ld + i * 64 + j4 * 4);
;                     if (j4 * 4 + 0 < i) s0 -= lv[0] * xv[j4 * 4 + 0];
;                     if (j4 * 4 + 1 < i) s1 -= lv[1] * xv[j4 * 4 + 1];
;                     if (j4 * 4 + 2 < i) s2 -= lv[2] * xv[j4 * 4 + 2];
;                     if (j4 * 4 + 3 < i) s3 -= lv[3] * xv[j4 * 4 + 3];
;                 }
;                 xv[i] = (s0 + s1) + (s2 + s3);
;             }
;             bf16_t* Tg = p.Tbuf + ((((size_t)b * 4 + h) * 36 + c3 * 3 + s) * 2 + dir) * 4096;
; #pragma unroll
;             for (int i = 0; i < 64; ++i) Tg[i * 64 + lane] = f2bf(xv[i]);
	v_pk_fma_f32 v[84:85], v[36:37], v[104:105], v[84:85] neg_lo:[1,0,0] neg_hi:[1,0,0]
	v_pk_fma_f32 v[86:87], v[38:39], v[106:107], v[86:87] neg_lo:[1,0,0] neg_hi:[1,0,0]
	ds_read_b128 v[36:39], v28 offset:33232
	s_waitcnt lgkmcnt(11)
	v_pk_fma_f32 v[84:85], v[40:41], v[108:109], v[84:85] neg_lo:[1,0,0] neg_hi:[1,0,0]
	v_pk_fma_f32 v[86:87], v[42:43], v[110:111], v[86:87] neg_lo:[1,0,0] neg_hi:[1,0,0]
	ds_read_b128 v[40:43], v28 offset:33248
	s_waitcnt lgkmcnt(11)
	v_pk_fma_f32 v[84:85], v[44:45], v[112:113], v[84:85] neg_lo:[1,0,0] neg_hi:[1,0,0]
	v_pk_fma_f32 v[86:87], v[46:47], v[114:115], v[86:87] neg_lo:[1,0,0] neg_hi:[1,0,0]
	ds_read_b128 v[44:47], v28 offset:33280
	s_waitcnt lgkmcnt(11)
	v_pk_fma_f32 v[84:85], v[48:49], v[116:117], v[84:85] neg_lo:[1,0,0] neg_hi:[1,0,0]
	v_pk_fma_f32 v[86:87], v[50:51], v[118:119], v[86:87] neg_lo:[1,0,0] neg_hi:[1,0,0]
	ds_read_b128 v[48:51], v28 offset:33296
	s_waitcnt lgkmcnt(11)
	v_pk_fma_f32 v[84:85], v[52:53], v[120:121], v[84:85] neg_lo:[1,0,0] neg_hi:[1,0,0]
	v_pk_fma_f32 v[86:87], v[54:55], v[122:123], v[86:87] neg_lo:[1,0,0] neg_hi:[1,0,0]
	ds_read_b128 v[52:55], v28 offset:33312
	s_waitcnt lgkmcnt(11)
	v_pk_fma_f32 v[84:85], v[56:57], v[124:125], v[84:85] neg_lo:[1,0,0] neg_hi:[1,0,0]
	v_pk_fma_f32 v[86:87], v[58:59], v[126:127], v[86:87] neg_lo:[1,0,0] neg_hi:[1,0,0]
	ds_read_b128 v[56:59], v28 offset:33328
	s_waitcnt lgkmcnt(11)
	v_pk_fma_f32 v[84:85], v[60:61], v[128:129], v[84:85] neg_lo:[1,0,0] neg_hi:[1,0,0]
	v_pk_fma_f32 v[86:87], v[62:63], v[130:131], v[86:87] neg_lo:[1,0,0] neg_hi:[1,0,0]
	ds_read_b128 v[60:63], v28 offset:33344
	s_waitcnt lgkmcnt(11)
	v_pk_fma_f32 v[84:85], v[64:65], v[132:133], v[84:85] neg_lo:[1,0,0] neg_hi:[1,0,0]
	v_pk_fma_f32 v[86:87], v[66:67], v[134:135], v[86:87] neg_lo:[1,0,0] neg_hi:[1,0,0]
	ds_read_b128 v[64:67], v28 offset:33360
	s_waitcnt lgkmcnt(11)
	v_pk_fma_f32 v[84:85], v[68:69], v[136:137], v[84:85] neg_lo:[1,0,0] neg_hi:[1,0,0]
	v_pk_fma_f32 v[86:87], v[70:71], v[138:139], v[86:87] neg_lo:[1,0,0] neg_hi:[1,0,0]
	ds_read_b128 v[68:71], v28 offset:33376
	s_waitcnt lgkmcnt(11)
	v_pk_fma_f32 v[84:85], v[72:73], v[140:141], v[84:85] neg_lo:[1,0,0] neg_hi:[1,0,0]
	v_pk_fma_f32 v[86:87], v[74:75], v[142:143], v[86:87] neg_lo:[1,0,0] neg_hi:[1,0,0]
	ds_read_b128 v[72:75], v28 offset:33392
	s_waitcnt lgkmcnt(11)
	v_pk_fma_f32 v[84:85], v[76:77], v[144:145], v[84:85] neg_lo:[1,0,0] neg_hi:[1,0,0]
	v_pk_fma_f32 v[86:87], v[78:79], v[146:147], v[86:87] neg_lo:[1,0,0] neg_hi:[1,0,0]
	ds_read_b128 v[76:79], v28 offset:33408
	s_waitcnt lgkmcnt(11)
	v_pk_fma_f32 v[84:85], v[32:33], v[148:149], v[84:85] neg_lo:[1,0,0] neg_hi:[1,0,0]
	v_pk_fma_f32 v[86:87], v[34:35], v[150:151], v[86:87] neg_lo:[1,0,0] neg_hi:[1,0,0]
	ds_read_b128 v[32:35], v28 offset:33424
	s_waitcnt lgkmcnt(11)
	v_pk_fma_f32 v[84:85], v[36:37], v[152:153], v[84:85] neg_lo:[1,0,0] neg_hi:[1,0,0]
	v_pk_fma_f32 v[86:87], v[38:39], v[154:155], v[86:87] neg_lo:[1,0,0] neg_hi:[1,0,0]
	ds_read_b128 v[36:39], v28 offset:33440
	s_waitcnt lgkmcnt(11)
	v_fma_f32 v84, -v40, v156, v84
	ds_read_b128 v[40:43], v28 offset:33456
	v_add_f32_e32 v84, v84, v85
	v_add_f32_e32 v86, v86, v87
	v_add_f32_e32 v157, v84, v86
	v_cvt_pk_bf16_f32 v90, v157, v157
	global_store_short v[8:9], v90, off offset:3200
	v_cmp_eq_u32_e64 s[56:57], 58, v88
	s_waitcnt lgkmcnt(11)
	s_nop 0
	v_cndmask_b32_e64 v80, 0, 1.0, s[56:57]
	v_fma_f32 v80, -v100, v44, v80
	v_fma_f32 v81, -v45, v101, 0
	v_fma_f32 v82, -v46, v102, 0
	v_fma_f32 v83, -v47, v103, 0
	ds_read_b128 v[44:47], v28 offset:33472
	s_waitcnt lgkmcnt(11)
	v_pk_fma_f32 v[80:81], v[48:49], v[104:105], v[80:81] neg_lo:[1,0,0] neg_hi:[1,0,0]
	v_pk_fma_f32 v[82:83], v[50:51], v[106:107], v[82:83] neg_lo:[1,0,0] neg_hi:[1,0,0]
	ds_read_b128 v[48:51], v28 offset:33488
	s_waitcnt lgkmcnt(11)
	v_pk_fma_f32 v[80:81], v[52:53], v[108:109], v[80:81] neg_lo:[1,0,0] neg_hi:[1,0,0]
	v_pk_fma_f32 v[82:83], v[54:55], v[110:111], v[82:83] neg_lo:[1,0,0] neg_hi:[1,0,0]
	ds_read_b128 v[52:55], v28 offset:33504
	s_waitcnt lgkmcnt(11)
	v_pk_fma_f32 v[80:81], v[56:57], v[112:113], v[80:81] neg_lo:[1,0,0] neg_hi:[1,0,0]
	v_pk_fma_f32 v[82:83], v[58:59], v[114:115], v[82:83] neg_lo:[1,0,0] neg_hi:[1,0,0]
	ds_read_b128 v[56:59], v28 offset:33536
	s_waitcnt lgkmcnt(11)
	v_pk_fma_f32 v[80:81], v[60:61], v[116:117], v[80:81] neg_lo:[1,0,0] neg_hi:[1,0,0]
	v_pk_fma_f32 v[82:83], v[62:63], v[118:119], v[82:83] neg_lo:[1,0,0] neg_hi:[1,0,0]
	ds_read_b128 v[60:63], v28 offset:33552
	s_waitcnt lgkmcnt(11)
	v_pk_fma_f32 v[80:81], v[64:65], v[120:121], v[80:81] neg_lo:[1,0,0] neg_hi:[1,0,0]
	v_pk_fma_f32 v[82:83], v[66:67], v[122:123], v[82:83] neg_lo:[1,0,0] neg_hi:[1,0,0]
	ds_read_b128 v[64:67], v28 offset:33568
	s_waitcnt lgkmcnt(11)
	v_pk_fma_f32 v[80:81], v[68:69], v[124:125], v[80:81] neg_lo:[1,0,0] neg_hi:[1,0,0]
	v_pk_fma_f32 v[82:83], v[70:71], v[126:127], v[82:83] neg_lo:[1,0,0] neg_hi:[1,0,0]
	ds_read_b128 v[68:71], v28 offset:33584
	s_waitcnt lgkmcnt(11)
	v_pk_fma_f32 v[80:81], v[72:73], v[128:129], v[80:81] neg_lo:[1,0,0] neg_hi:[1,0,0]
	v_pk_fma_f32 v[82:83], v[74:75], v[130:131], v[82:83] neg_lo:[1,0,0] neg_hi:[1,0,0]
	ds_read_b128 v[72:75], v28 offset:33600
	s_waitcnt lgkmcnt(11)
	v_pk_fma_f32 v[80:81], v[76:77], v[132:133], v[80:81] neg_lo:[1,0,0] neg_hi:[1,0,0]
	v_pk_fma_f32 v[82:83], v[78:79], v[134:135], v[82:83] neg_lo:[1,0,0] neg_hi:[1,0,0]
	ds_read_b128 v[76:79], v28 offset:33616
	s_waitcnt lgkmcnt(11)
	v_pk_fma_f32 v[80:81], v[32:33], v[136:137], v[80:81] neg_lo:[1,0,0] neg_hi:[1,0,0]
	v_pk_fma_f32 v[82:83], v[34:35], v[138:139], v[82:83] neg_lo:[1,0,0] neg_hi:[1,0,0]
	ds_read_b128 v[32:35], v28 offset:33632
	s_waitcnt lgkmcnt(11)
; #define LAS __attribute__((address_space(3)))
; __device__ __forceinline__ bf16_t f2bf(float f) { return (bf16_t)(pk2(f, f) & 0xFFFFu); }
; __device__ NOINL void g1_phase(const LAS Params* lp, int l, LAS unsigned char* lds) {
;     ...
;             for (int i = 0; i < 64; ++i) {
;                 float s0 = (i == lane) ? 1.f : 0.f, s1 = 0.f, s2 = 0.f, s3 = 0.f;
; #pragma unroll
;                 for (int j4 = 0; j4 < (i + 3) / 4; ++j4) {
;                     const f32x4 lv = *(const LAS f32x4*)(Ld + i * 64 + j4 * 4);
;                     if (j4 * 4 + 0 < i) s0 -= lv[0] * xv[j4 * 4 + 0];
;                     if (j4 * 4 + 1 < i) s1 -= lv[1] * xv[j4 * 4 + 1];
;                     if (j4 * 4 + 2 < i) s2 -= lv[2] * xv[j4 * 4 + 2];
;                     if (j4 * 4 + 3 < i) s3 -= lv[3] * xv[j4 * 4 + 3];
;                 }
;                 xv[i] = (s0 + s1) + (s2 + s3);
;             }
;             bf16_t* Tg = p.Tbuf + ((((size_t)b * 4 + h) * 36 + c3 * 3 + s) * 2 + dir) * 4096;
; #pragma unroll
;             for (int i = 0; i < 64; ++i) Tg[i * 64 + lane] = f2bf(xv[i]);
	v_pk_fma_f32 v[80:81], v[36:37], v[140:141], v[80:81] neg_lo:[1,0,0] neg_hi:[1,0,0]
	v_pk_fma_f32 v[82:83], v[38:39], v[142:143], v[82:83] neg_lo:[1,0,0] neg_hi:[1,0,0]
	ds_read_b128 v[36:39], v28 offset:33648
	s_waitcnt lgkmcnt(11)
	v_pk_fma_f32 v[80:81], v[40:41], v[144:145], v[80:81] neg_lo:[1,0,0] neg_hi:[1,0,0]
	v_pk_fma_f32 v[82:83], v[42:43], v[146:147], v[82:83] neg_lo:[1,0,0] neg_hi:[1,0,0]
	ds_read_b128 v[40:43], v28 offset:33664
	s_waitcnt lgkmcnt(11)
	v_pk_fma_f32 v[80:81], v[44:45], v[148:149], v[80:81] neg_lo:[1,0,0] neg_hi:[1,0,0]
	v_pk_fma_f32 v[82:83], v[46:47], v[150:151], v[82:83] neg_lo:[1,0,0] neg_hi:[1,0,0]
	ds_read_b128 v[44:47], v28 offset:33680
	s_waitcnt lgkmcnt(11)
	v_pk_fma_f32 v[80:81], v[48:49], v[152:153], v[80:81] neg_lo:[1,0,0] neg_hi:[1,0,0]
	v_pk_fma_f32 v[82:83], v[50:51], v[154:155], v[82:83] neg_lo:[1,0,0] neg_hi:[1,0,0]
	ds_read_b128 v[48:51], v28 offset:33696
	s_waitcnt lgkmcnt(11)
	v_pk_fma_f32 v[80:81], v[52:53], v[156:157], v[80:81] neg_lo:[1,0,0] neg_hi:[1,0,0]
	ds_read_b128 v[52:55], v28 offset:33712
	v_add_f32_e32 v80, v80, v81
	v_add_f32_e32 v82, v82, v83
	v_add_f32_e32 v158, v80, v82
	v_cvt_pk_bf16_f32 v91, v158, v158
	global_store_short v[8:9], v91, off offset:3328
	v_cmp_eq_u32_e64 s[56:57], 59, v88
	s_waitcnt lgkmcnt(11)
	s_nop 0
	v_cndmask_b32_e64 v84, 0, 1.0, s[56:57]
	v_fma_f32 v84, -v100, v56, v84
	v_fma_f32 v85, -v57, v101, 0
	v_fma_f32 v86, -v58, v102, 0
	v_fma_f32 v87, -v59, v103, 0
	ds_read_b128 v[56:59], v28 offset:33728
	s_waitcnt lgkmcnt(11)
	v_pk_fma_f32 v[84:85], v[60:61], v[104:105], v[84:85] neg_lo:[1,0,0] neg_hi:[1,0,0]
	v_pk_fma_f32 v[86:87], v[62:63], v[106:107], v[86:87] neg_lo:[1,0,0] neg_hi:[1,0,0]
	ds_read_b128 v[60:63], v28 offset:33744
	s_waitcnt lgkmcnt(11)
	v_pk_fma_f32 v[84:85], v[64:65], v[108:109], v[84:85] neg_lo:[1,0,0] neg_hi:[1,0,0]
	v_pk_fma_f32 v[86:87], v[66:67], v[110:111], v[86:87] neg_lo:[1,0,0] neg_hi:[1,0,0]
	ds_read_b128 v[64:67], v28 offset:33760
	s_waitcnt lgkmcnt(11)
	v_pk_fma_f32 v[84:85], v[68:69], v[112:113], v[84:85] neg_lo:[1,0,0] neg_hi:[1,0,0]
	v_pk_fma_f32 v[86:87], v[70:71], v[114:115], v[86:87] neg_lo:[1,0,0] neg_hi:[1,0,0]
	ds_read_b128 v[68:71], v28 offset:33792
	s_waitcnt lgkmcnt(11)
	v_pk_fma_f32 v[84:85], v[72:73], v[116:117], v[84:85] neg_lo:[1,0,0] neg_hi:[1,0,0]
	v_pk_fma_f32 v[86:87], v[74:75], v[118:119], v[86:87] neg_lo:[1,0,0] neg_hi:[1,0,0]
	ds_read_b128 v[72:75], v28 offset:33808
	s_waitcnt lgkmcnt(11)
	v_pk_fma_f32 v[84:85], v[76:77], v[120:121], v[84:85] neg_lo:[1,0,0] neg_hi:[1,0,0]
	v_pk_fma_f32 v[86:87], v[78:79], v[122:123], v[86:87] neg_lo:[1,0,0] neg_hi:[1,0,0]
	ds_read_b128 v[76:79], v28 offset:33824
	s_waitcnt lgkmcnt(11)
	v_pk_fma_f32 v[84:85], v[32:33], v[124:125], v[84:85] neg_lo:[1,0,0] neg_hi:[1,0,0]
	v_pk_fma_f32 v[86:87], v[34:35], v[126:127], v[86:87] neg_lo:[1,0,0] neg_hi:[1,0,0]
	ds_read_b128 v[32:35], v28 offset:33840
	s_waitcnt lgkmcnt(11)
	v_pk_fma_f32 v[84:85], v[36:37], v[128:129], v[84:85] neg_lo:[1,0,0] neg_hi:[1,0,0]
	v_pk_fma_f32 v[86:87], v[38:39], v[130:131], v[86:87] neg_lo:[1,0,0] neg_hi:[1,0,0]
	ds_read_b128 v[36:39], v28 offset:33856
	s_waitcnt lgkmcnt(11)
	v_pk_fma_f32 v[84:85], v[40:41], v[132:133], v[84:85] neg_lo:[1,0,0] neg_hi:[1,0,0]
	v_pk_fma_f32 v[86:87], v[42:43], v[134:135], v[86:87] neg_lo:[1,0,0] neg_hi:[1,0,0]
	ds_read_b128 v[40:43], v28 offset:33872
	s_waitcnt lgkmcnt(11)
	v_pk_fma_f32 v[84:85], v[44:45], v[136:137], v[84:85] neg_lo:[1,0,0] neg_hi:[1,0,0]
	v_pk_fma_f32 v[86:87], v[46:47], v[138:139], v[86:87] neg_lo:[1,0,0] neg_hi:[1,0,0]
	ds_read_b128 v[44:47], v28 offset:33888
	s_waitcnt lgkmcnt(11)
	v_pk_fma_f32 v[84:85], v[48:49], v[140:141], v[84:85] neg_lo:[1,0,0] neg_hi:[1,0,0]
	v_pk_fma_f32 v[86:87], v[50:51], v[142:143], v[86:87] neg_lo:[1,0,0] neg_hi:[1,0,0]
	ds_read_b128 v[48:51], v28 offset:33904
	s_waitcnt lgkmcnt(11)
	v_pk_fma_f32 v[84:85], v[52:53], v[144:145], v[84:85] neg_lo:[1,0,0] neg_hi:[1,0,0]
	v_pk_fma_f32 v[86:87], v[54:55], v[146:147], v[86:87] neg_lo:[1,0,0] neg_hi:[1,0,0]
	ds_read_b128 v[52:55], v28 offset:33920
	s_waitcnt lgkmcnt(11)
	v_pk_fma_f32 v[84:85], v[56:57], v[148:149], v[84:85] neg_lo:[1,0,0] neg_hi:[1,0,0]
	v_pk_fma_f32 v[86:87], v[58:59], v[150:151], v[86:87] neg_lo:[1,0,0] neg_hi:[1,0,0]
	ds_read_b128 v[56:59], v28 offset:33936
	s_waitcnt lgkmcnt(11)
	v_pk_fma_f32 v[84:85], v[60:61], v[152:153], v[84:85] neg_lo:[1,0,0] neg_hi:[1,0,0]
	v_pk_fma_f32 v[86:87], v[62:63], v[154:155], v[86:87] neg_lo:[1,0,0] neg_hi:[1,0,0]
	ds_read_b128 v[60:63], v28 offset:33952
	s_waitcnt lgkmcnt(11)
	v_pk_fma_f32 v[84:85], v[64:65], v[156:157], v[84:85] neg_lo:[1,0,0] neg_hi:[1,0,0]
	v_fma_f32 v86, -v66, v158, v86
	ds_read_b128 v[64:67], v28 offset:33968
	v_add_f32_e32 v84, v84, v85
	v_add_f32_e32 v86, v86, v87
	v_add_f32_e32 v159, v84, v86
	v_cvt_pk_bf16_f32 v92, v159, v159
	global_store_short v[8:9], v92, off offset:3456
	v_cmp_eq_u32_e64 s[56:57], 60, v88
	s_waitcnt lgkmcnt(11)
	s_nop 0
	v_cndmask_b32_e64 v80, 0, 1.0, s[56:57]
	v_fma_f32 v80, -v100, v68, v80
	v_fma_f32 v81, -v69, v101, 0
	v_fma_f32 v82, -v70, v102, 0
	v_fma_f32 v83, -v71, v103, 0
	ds_read_b128 v[68:71], v28 offset:33984
	s_waitcnt lgkmcnt(11)
	v_pk_fma_f32 v[80:81], v[72:73], v[104:105], v[80:81] neg_lo:[1,0,0] neg_hi:[1,0,0]
	v_pk_fma_f32 v[82:83], v[74:75], v[106:107], v[82:83] neg_lo:[1,0,0] neg_hi:[1,0,0]
	ds_read_b128 v[72:75], v28 offset:34000
	s_waitcnt lgkmcnt(11)
	v_pk_fma_f32 v[80:81], v[76:77], v[108:109], v[80:81] neg_lo:[1,0,0] neg_hi:[1,0,0]
	v_pk_fma_f32 v[82:83], v[78:79], v[110:111], v[82:83] neg_lo:[1,0,0] neg_hi:[1,0,0]
	ds_read_b128 v[76:79], v28 offset:34016
	s_waitcnt lgkmcnt(11)
; #define LAS __attribute__((address_space(3)))
; __device__ __forceinline__ bf16_t f2bf(float f) { return (bf16_t)(pk2(f, f) & 0xFFFFu); }
; __device__ NOINL void g1_phase(const LAS Params* lp, int l, LAS unsigned char* lds) {
;     ...
;             for (int i = 0; i < 64; ++i) {
;                 float s0 = (i == lane) ? 1.f : 0.f, s1 = 0.f, s2 = 0.f, s3 = 0.f;
; #pragma unroll
;                 for (int j4 = 0; j4 < (i + 3) / 4; ++j4) {
;                     const f32x4 lv = *(const LAS f32x4*)(Ld + i * 64 + j4 * 4);
;                     if (j4 * 4 + 0 < i) s0 -= lv[0] * xv[j4 * 4 + 0];
;                     if (j4 * 4 + 1 < i) s1 -= lv[1] * xv[j4 * 4 + 1];
;                     if (j4 * 4 + 2 < i) s2 -= lv[2] * xv[j4 * 4 + 2];
;                     if (j4 * 4 + 3 < i) s3 -= lv[3] * xv[j4 * 4 + 3];
;                 }
;                 xv[i] = (s0 + s1) + (s2 + s3);
;             }
;             bf16_t* Tg = p.Tbuf + ((((size_t)b * 4 + h) * 36 + c3 * 3 + s) * 2 + dir) * 4096;
; #pragma unroll
;             for (int i = 0; i < 64; ++i) Tg[i * 64 + lane] = f2bf(xv[i]);
	v_pk_fma_f32 v[80:81], v[32:33], v[112:113], v[80:81] neg_lo:[1,0,0] neg_hi:[1,0,0]
	v_pk_fma_f32 v[82:83], v[34:35], v[114:115], v[82:83] neg_lo:[1,0,0] neg_hi:[1,0,0]
	ds_read_b128 v[32:35], v28 offset:34048
	s_waitcnt lgkmcnt(11)
	v_pk_fma_f32 v[80:81], v[36:37], v[116:117], v[80:81] neg_lo:[1,0,0] neg_hi:[1,0,0]
	v_pk_fma_f32 v[82:83], v[38:39], v[118:119], v[82:83] neg_lo:[1,0,0] neg_hi:[1,0,0]
	ds_read_b128 v[36:39], v28 offset:34064
	s_waitcnt lgkmcnt(11)
	v_pk_fma_f32 v[80:81], v[40:41], v[120:121], v[80:81] neg_lo:[1,0,0] neg_hi:[1,0,0]
	v_pk_fma_f32 v[82:83], v[42:43], v[122:123], v[82:83] neg_lo:[1,0,0] neg_hi:[1,0,0]
	ds_read_b128 v[40:43], v28 offset:34080
	s_waitcnt lgkmcnt(11)
	v_pk_fma_f32 v[80:81], v[44:45], v[124:125], v[80:81] neg_lo:[1,0,0] neg_hi:[1,0,0]
	v_pk_fma_f32 v[82:83], v[46:47], v[126:127], v[82:83] neg_lo:[1,0,0] neg_hi:[1,0,0]
	ds_read_b128 v[44:47], v28 offset:34096
	s_waitcnt lgkmcnt(11)
	v_pk_fma_f32 v[80:81], v[48:49], v[128:129], v[80:81] neg_lo:[1,0,0] neg_hi:[1,0,0]
	v_pk_fma_f32 v[82:83], v[50:51], v[130:131], v[82:83] neg_lo:[1,0,0] neg_hi:[1,0,0]
	ds_read_b128 v[48:51], v28 offset:34112
	s_waitcnt lgkmcnt(11)
	v_pk_fma_f32 v[80:81], v[52:53], v[132:133], v[80:81] neg_lo:[1,0,0] neg_hi:[1,0,0]
	v_pk_fma_f32 v[82:83], v[54:55], v[134:135], v[82:83] neg_lo:[1,0,0] neg_hi:[1,0,0]
	ds_read_b128 v[52:55], v28 offset:34128
	s_waitcnt lgkmcnt(11)
	v_pk_fma_f32 v[80:81], v[56:57], v[136:137], v[80:81] neg_lo:[1,0,0] neg_hi:[1,0,0]
	v_pk_fma_f32 v[82:83], v[58:59], v[138:139], v[82:83] neg_lo:[1,0,0] neg_hi:[1,0,0]
	ds_read_b128 v[56:59], v28 offset:34144
	s_waitcnt lgkmcnt(11)
	v_pk_fma_f32 v[80:81], v[60:61], v[140:141], v[80:81] neg_lo:[1,0,0] neg_hi:[1,0,0]
	v_pk_fma_f32 v[82:83], v[62:63], v[142:143], v[82:83] neg_lo:[1,0,0] neg_hi:[1,0,0]
	ds_read_b128 v[60:63], v28 offset:34160
	s_waitcnt lgkmcnt(11)
	v_pk_fma_f32 v[80:81], v[64:65], v[144:145], v[80:81] neg_lo:[1,0,0] neg_hi:[1,0,0]
	v_pk_fma_f32 v[82:83], v[66:67], v[146:147], v[82:83] neg_lo:[1,0,0] neg_hi:[1,0,0]
	ds_read_b128 v[64:67], v28 offset:34176
	s_waitcnt lgkmcnt(11)
	v_pk_fma_f32 v[80:81], v[68:69], v[148:149], v[80:81] neg_lo:[1,0,0] neg_hi:[1,0,0]
	v_pk_fma_f32 v[82:83], v[70:71], v[150:151], v[82:83] neg_lo:[1,0,0] neg_hi:[1,0,0]
	ds_read_b128 v[68:71], v28 offset:34192
	s_waitcnt lgkmcnt(11)
	v_pk_fma_f32 v[80:81], v[72:73], v[152:153], v[80:81] neg_lo:[1,0,0] neg_hi:[1,0,0]
	v_pk_fma_f32 v[82:83], v[74:75], v[154:155], v[82:83] neg_lo:[1,0,0] neg_hi:[1,0,0]
	ds_read_b128 v[72:75], v28 offset:34208
	s_waitcnt lgkmcnt(11)
	v_pk_fma_f32 v[80:81], v[76:77], v[156:157], v[80:81] neg_lo:[1,0,0] neg_hi:[1,0,0]
	v_pk_fma_f32 v[82:83], v[78:79], v[158:159], v[82:83] neg_lo:[1,0,0] neg_hi:[1,0,0]
	ds_read_b128 v[76:79], v28 offset:34224
	v_add_f32_e32 v80, v80, v81
	v_add_f32_e32 v82, v82, v83
	v_add_f32_e32 v160, v80, v82
	v_cvt_pk_bf16_f32 v89, v160, v160
	global_store_short v[8:9], v89, off offset:3584
	v_cmp_eq_u32_e64 s[56:57], 61, v88
	s_waitcnt lgkmcnt(11)
	s_nop 0
	v_cndmask_b32_e64 v84, 0, 1.0, s[56:57]
	v_fma_f32 v84, -v100, v32, v84
	v_fma_f32 v85, -v33, v101, 0
	v_fma_f32 v86, -v34, v102, 0
	v_fma_f32 v87, -v35, v103, 0
	ds_read_b128 v[32:35], v28 offset:34240
	s_waitcnt lgkmcnt(11)
	v_pk_fma_f32 v[84:85], v[36:37], v[104:105], v[84:85] neg_lo:[1,0,0] neg_hi:[1,0,0]
	v_pk_fma_f32 v[86:87], v[38:39], v[106:107], v[86:87] neg_lo:[1,0,0] neg_hi:[1,0,0]
	ds_read_b128 v[36:39], v28 offset:34256
	s_waitcnt lgkmcnt(11)
	v_pk_fma_f32 v[84:85], v[40:41], v[108:109], v[84:85] neg_lo:[1,0,0] neg_hi:[1,0,0]
	v_pk_fma_f32 v[86:87], v[42:43], v[110:111], v[86:87] neg_lo:[1,0,0] neg_hi:[1,0,0]
	ds_read_b128 v[40:43], v28 offset:34272
	s_waitcnt lgkmcnt(11)
	v_pk_fma_f32 v[84:85], v[44:45], v[112:113], v[84:85] neg_lo:[1,0,0] neg_hi:[1,0,0]
	v_pk_fma_f32 v[86:87], v[46:47], v[114:115], v[86:87] neg_lo:[1,0,0] neg_hi:[1,0,0]
	ds_read_b128 v[44:47], v28 offset:34288
	s_waitcnt lgkmcnt(11)
	v_pk_fma_f32 v[84:85], v[48:49], v[116:117], v[84:85] neg_lo:[1,0,0] neg_hi:[1,0,0]
	v_pk_fma_f32 v[86:87], v[50:51], v[118:119], v[86:87] neg_lo:[1,0,0] neg_hi:[1,0,0]
	ds_read_b128 v[48:51], v28 offset:34304
	s_waitcnt lgkmcnt(11)
	v_pk_fma_f32 v[84:85], v[52:53], v[120:121], v[84:85] neg_lo:[1,0,0] neg_hi:[1,0,0]
	v_pk_fma_f32 v[86:87], v[54:55], v[122:123], v[86:87] neg_lo:[1,0,0] neg_hi:[1,0,0]
	ds_read_b128 v[52:55], v28 offset:34320
	s_waitcnt lgkmcnt(11)
	v_pk_fma_f32 v[84:85], v[56:57], v[124:125], v[84:85] neg_lo:[1,0,0] neg_hi:[1,0,0]
	v_pk_fma_f32 v[86:87], v[58:59], v[126:127], v[86:87] neg_lo:[1,0,0] neg_hi:[1,0,0]
	ds_read_b128 v[56:59], v28 offset:34336
	s_waitcnt lgkmcnt(11)
	v_pk_fma_f32 v[84:85], v[60:61], v[128:129], v[84:85] neg_lo:[1,0,0] neg_hi:[1,0,0]
	v_pk_fma_f32 v[86:87], v[62:63], v[130:131], v[86:87] neg_lo:[1,0,0] neg_hi:[1,0,0]
	ds_read_b128 v[60:63], v28 offset:34352
	s_waitcnt lgkmcnt(11)
	v_pk_fma_f32 v[84:85], v[64:65], v[132:133], v[84:85] neg_lo:[1,0,0] neg_hi:[1,0,0]
	v_pk_fma_f32 v[86:87], v[66:67], v[134:135], v[86:87] neg_lo:[1,0,0] neg_hi:[1,0,0]
	ds_read_b128 v[64:67], v28 offset:34368
	s_waitcnt lgkmcnt(11)
	v_pk_fma_f32 v[84:85], v[68:69], v[136:137], v[84:85] neg_lo:[1,0,0] neg_hi:[1,0,0]
	v_pk_fma_f32 v[86:87], v[70:71], v[138:139], v[86:87] neg_lo:[1,0,0] neg_hi:[1,0,0]
	ds_read_b128 v[68:71], v28 offset:34384
	s_waitcnt lgkmcnt(11)
	v_pk_fma_f32 v[84:85], v[72:73], v[140:141], v[84:85] neg_lo:[1,0,0] neg_hi:[1,0,0]
	v_pk_fma_f32 v[86:87], v[74:75], v[142:143], v[86:87] neg_lo:[1,0,0] neg_hi:[1,0,0]
	ds_read_b128 v[72:75], v28 offset:34400
	s_waitcnt lgkmcnt(11)
; #define LAS __attribute__((address_space(3)))
; __device__ __forceinline__ bf16_t f2bf(float f) { return (bf16_t)(pk2(f, f) & 0xFFFFu); }
; __device__ NOINL void g1_phase(const LAS Params* lp, int l, LAS unsigned char* lds) {
;     ...
;             for (int i = 0; i < 64; ++i) {
;                 float s0 = (i == lane) ? 1.f : 0.f, s1 = 0.f, s2 = 0.f, s3 = 0.f;
; #pragma unroll
;                 for (int j4 = 0; j4 < (i + 3) / 4; ++j4) {
;                     const f32x4 lv = *(const LAS f32x4*)(Ld + i * 64 + j4 * 4);
;                     if (j4 * 4 + 0 < i) s0 -= lv[0] * xv[j4 * 4 + 0];
;                     if (j4 * 4 + 1 < i) s1 -= lv[1] * xv[j4 * 4 + 1];
;                     if (j4 * 4 + 2 < i) s2 -= lv[2] * xv[j4 * 4 + 2];
;                     if (j4 * 4 + 3 < i) s3 -= lv[3] * xv[j4 * 4 + 3];
;                 }
;                 xv[i] = (s0 + s1) + (s2 + s3);
;             }
;             bf16_t* Tg = p.Tbuf + ((((size_t)b * 4 + h) * 36 + c3 * 3 + s) * 2 + dir) * 4096;
; #pragma unroll
;             for (int i = 0; i < 64; ++i) Tg[i * 64 + lane] = f2bf(xv[i]);
	v_pk_fma_f32 v[84:85], v[76:77], v[144:145], v[84:85] neg_lo:[1,0,0] neg_hi:[1,0,0]
	v_pk_fma_f32 v[86:87], v[78:79], v[146:147], v[86:87] neg_lo:[1,0,0] neg_hi:[1,0,0]
	ds_read_b128 v[76:79], v28 offset:34416
	s_waitcnt lgkmcnt(11)
	v_pk_fma_f32 v[84:85], v[32:33], v[148:149], v[84:85] neg_lo:[1,0,0] neg_hi:[1,0,0]
	v_pk_fma_f32 v[86:87], v[34:35], v[150:151], v[86:87] neg_lo:[1,0,0] neg_hi:[1,0,0]
	ds_read_b128 v[32:35], v28 offset:34432
	s_waitcnt lgkmcnt(11)
	v_pk_fma_f32 v[84:85], v[36:37], v[152:153], v[84:85] neg_lo:[1,0,0] neg_hi:[1,0,0]
	v_pk_fma_f32 v[86:87], v[38:39], v[154:155], v[86:87] neg_lo:[1,0,0] neg_hi:[1,0,0]
	ds_read_b128 v[36:39], v28 offset:34448
	s_waitcnt lgkmcnt(11)
	v_pk_fma_f32 v[84:85], v[40:41], v[156:157], v[84:85] neg_lo:[1,0,0] neg_hi:[1,0,0]
	v_pk_fma_f32 v[86:87], v[42:43], v[158:159], v[86:87] neg_lo:[1,0,0] neg_hi:[1,0,0]
	ds_read_b128 v[40:43], v28 offset:34464
	s_waitcnt lgkmcnt(11)
	v_fma_f32 v84, -v44, v160, v84
	ds_read_b128 v[44:47], v28 offset:34480
	v_add_f32_e32 v84, v84, v85
	v_add_f32_e32 v86, v86, v87
	v_add_f32_e32 v161, v84, v86
	v_cvt_pk_bf16_f32 v90, v161, v161
	global_store_short v[8:9], v90, off offset:3712
	v_cmp_eq_u32_e64 s[56:57], 62, v88
	s_waitcnt lgkmcnt(11)
	s_nop 0
	v_cndmask_b32_e64 v80, 0, 1.0, s[56:57]
	v_fma_f32 v80, -v100, v48, v80
	v_fma_f32 v81, -v49, v101, 0
	v_fma_f32 v82, -v50, v102, 0
	v_fma_f32 v83, -v51, v103, 0
	ds_read_b128 v[48:51], v28 offset:34496
	s_waitcnt lgkmcnt(11)
	v_pk_fma_f32 v[80:81], v[52:53], v[104:105], v[80:81] neg_lo:[1,0,0] neg_hi:[1,0,0]
	v_pk_fma_f32 v[82:83], v[54:55], v[106:107], v[82:83] neg_lo:[1,0,0] neg_hi:[1,0,0]
	ds_read_b128 v[52:55], v28 offset:34512
	s_waitcnt lgkmcnt(11)
	v_pk_fma_f32 v[80:81], v[56:57], v[108:109], v[80:81] neg_lo:[1,0,0] neg_hi:[1,0,0]
	v_pk_fma_f32 v[82:83], v[58:59], v[110:111], v[82:83] neg_lo:[1,0,0] neg_hi:[1,0,0]
	ds_read_b128 v[56:59], v28 offset:34528
	s_waitcnt lgkmcnt(11)
	v_pk_fma_f32 v[80:81], v[60:61], v[112:113], v[80:81] neg_lo:[1,0,0] neg_hi:[1,0,0]
	v_pk_fma_f32 v[82:83], v[62:63], v[114:115], v[82:83] neg_lo:[1,0,0] neg_hi:[1,0,0]
	ds_read_b128 v[60:63], v28 offset:34544
	s_waitcnt lgkmcnt(11)
	v_pk_fma_f32 v[80:81], v[64:65], v[116:117], v[80:81] neg_lo:[1,0,0] neg_hi:[1,0,0]
	v_pk_fma_f32 v[82:83], v[66:67], v[118:119], v[82:83] neg_lo:[1,0,0] neg_hi:[1,0,0]
	ds_read_b128 v[64:67], v28 offset:34560
	s_waitcnt lgkmcnt(11)
	v_pk_fma_f32 v[80:81], v[68:69], v[120:121], v[80:81] neg_lo:[1,0,0] neg_hi:[1,0,0]
	v_pk_fma_f32 v[82:83], v[70:71], v[122:123], v[82:83] neg_lo:[1,0,0] neg_hi:[1,0,0]
	ds_read_b128 v[68:71], v28 offset:34576
	s_waitcnt lgkmcnt(11)
	v_pk_fma_f32 v[80:81], v[72:73], v[124:125], v[80:81] neg_lo:[1,0,0] neg_hi:[1,0,0]
	v_pk_fma_f32 v[82:83], v[74:75], v[126:127], v[82:83] neg_lo:[1,0,0] neg_hi:[1,0,0]
	ds_read_b128 v[72:75], v28 offset:34592
	s_waitcnt lgkmcnt(11)
	v_pk_fma_f32 v[80:81], v[76:77], v[128:129], v[80:81] neg_lo:[1,0,0] neg_hi:[1,0,0]
	v_pk_fma_f32 v[82:83], v[78:79], v[130:131], v[82:83] neg_lo:[1,0,0] neg_hi:[1,0,0]
	ds_read_b128 v[76:79], v28 offset:34608
	s_waitcnt lgkmcnt(11)
	v_pk_fma_f32 v[80:81], v[32:33], v[132:133], v[80:81] neg_lo:[1,0,0] neg_hi:[1,0,0]
	v_pk_fma_f32 v[82:83], v[34:35], v[134:135], v[82:83] neg_lo:[1,0,0] neg_hi:[1,0,0]
	ds_read_b128 v[32:35], v28 offset:34624
	s_waitcnt lgkmcnt(11)
	v_pk_fma_f32 v[80:81], v[36:37], v[136:137], v[80:81] neg_lo:[1,0,0] neg_hi:[1,0,0]
	v_pk_fma_f32 v[82:83], v[38:39], v[138:139], v[82:83] neg_lo:[1,0,0] neg_hi:[1,0,0]
	ds_read_b128 v[36:39], v28 offset:34640
	s_waitcnt lgkmcnt(11)
	v_pk_fma_f32 v[80:81], v[40:41], v[140:141], v[80:81] neg_lo:[1,0,0] neg_hi:[1,0,0]
	v_pk_fma_f32 v[82:83], v[42:43], v[142:143], v[82:83] neg_lo:[1,0,0] neg_hi:[1,0,0]
	ds_read_b128 v[40:43], v28 offset:34656
	s_waitcnt lgkmcnt(11)
	v_pk_fma_f32 v[80:81], v[44:45], v[144:145], v[80:81] neg_lo:[1,0,0] neg_hi:[1,0,0]
	v_pk_fma_f32 v[82:83], v[46:47], v[146:147], v[82:83] neg_lo:[1,0,0] neg_hi:[1,0,0]
	ds_read_b128 v[44:47], v28 offset:34672
	s_waitcnt lgkmcnt(11)
	v_pk_fma_f32 v[80:81], v[48:49], v[148:149], v[80:81] neg_lo:[1,0,0] neg_hi:[1,0,0]
	v_pk_fma_f32 v[82:83], v[50:51], v[150:151], v[82:83] neg_lo:[1,0,0] neg_hi:[1,0,0]
	ds_read_b128 v[48:51], v28 offset:34688
	s_waitcnt lgkmcnt(11)
; #define LAS __attribute__((address_space(3)))
; __device__ __forceinline__ bf16_t f2bf(float f) { return (bf16_t)(pk2(f, f) & 0xFFFFu); }
; __device__ NOINL void g1_phase(const LAS Params* lp, int l, LAS unsigned char* lds) {
;     ...
;             for (int i = 0; i < 64; ++i) {
;                 float s0 = (i == lane) ? 1.f : 0.f, s1 = 0.f, s2 = 0.f, s3 = 0.f;
; #pragma unroll
;                 for (int j4 = 0; j4 < (i + 3) / 4; ++j4) {
;                     const f32x4 lv = *(const LAS f32x4*)(Ld + i * 64 + j4 * 4);
;                     if (j4 * 4 + 0 < i) s0 -= lv[0] * xv[j4 * 4 + 0];
;                     if (j4 * 4 + 1 < i) s1 -= lv[1] * xv[j4 * 4 + 1];
;                     if (j4 * 4 + 2 < i) s2 -= lv[2] * xv[j4 * 4 + 2];
;                     if (j4 * 4 + 3 < i) s3 -= lv[3] * xv[j4 * 4 + 3];
;                 }
;                 xv[i] = (s0 + s1) + (s2 + s3);
;             }
;             bf16_t* Tg = p.Tbuf + ((((size_t)b * 4 + h) * 36 + c3 * 3 + s) * 2 + dir) * 4096;
; #pragma unroll
;             for (int i = 0; i < 64; ++i) Tg[i * 64 + lane] = f2bf(xv[i]);
	v_pk_fma_f32 v[80:81], v[52:53], v[152:153], v[80:81] neg_lo:[1,0,0] neg_hi:[1,0,0]
	v_pk_fma_f32 v[82:83], v[54:55], v[154:155], v[82:83] neg_lo:[1,0,0] neg_hi:[1,0,0]
	ds_read_b128 v[52:55], v28 offset:34704
	s_waitcnt lgkmcnt(11)
	v_pk_fma_f32 v[80:81], v[56:57], v[156:157], v[80:81] neg_lo:[1,0,0] neg_hi:[1,0,0]
	v_pk_fma_f32 v[82:83], v[58:59], v[158:159], v[82:83] neg_lo:[1,0,0] neg_hi:[1,0,0]
	ds_read_b128 v[56:59], v28 offset:34720
	s_waitcnt lgkmcnt(11)
	v_pk_fma_f32 v[80:81], v[60:61], v[160:161], v[80:81] neg_lo:[1,0,0] neg_hi:[1,0,0]
	ds_read_b128 v[60:63], v28 offset:34736
	v_add_f32_e32 v80, v80, v81
	v_add_f32_e32 v82, v82, v83
	v_add_f32_e32 v162, v80, v82
	v_cvt_pk_bf16_f32 v91, v162, v162
	global_store_short v[8:9], v91, off offset:3840
	v_cmp_eq_u32_e64 s[56:57], 63, v88
	s_waitcnt lgkmcnt(11)
	s_nop 0
	v_cndmask_b32_e64 v84, 0, 1.0, s[56:57]
	v_fma_f32 v84, -v100, v64, v84
	v_fma_f32 v85, -v65, v101, 0
	v_fma_f32 v86, -v66, v102, 0
	v_fma_f32 v87, -v67, v103, 0
	ds_read_b128 v[64:67], v28 offset:34752
	s_waitcnt lgkmcnt(11)
	v_pk_fma_f32 v[84:85], v[68:69], v[104:105], v[84:85] neg_lo:[1,0,0] neg_hi:[1,0,0]
	v_pk_fma_f32 v[86:87], v[70:71], v[106:107], v[86:87] neg_lo:[1,0,0] neg_hi:[1,0,0]
	ds_read_b128 v[68:71], v28 offset:34768
	s_waitcnt lgkmcnt(11)
	v_pk_fma_f32 v[84:85], v[72:73], v[108:109], v[84:85] neg_lo:[1,0,0] neg_hi:[1,0,0]
	v_pk_fma_f32 v[86:87], v[74:75], v[110:111], v[86:87] neg_lo:[1,0,0] neg_hi:[1,0,0]
	ds_read_b128 v[72:75], v28 offset:34784
	s_waitcnt lgkmcnt(11)
	v_pk_fma_f32 v[84:85], v[76:77], v[112:113], v[84:85] neg_lo:[1,0,0] neg_hi:[1,0,0]
	v_pk_fma_f32 v[86:87], v[78:79], v[114:115], v[86:87] neg_lo:[1,0,0] neg_hi:[1,0,0]
	ds_read_b128 v[76:79], v28 offset:34800
	s_waitcnt lgkmcnt(11)
	v_pk_fma_f32 v[84:85], v[32:33], v[116:117], v[84:85] neg_lo:[1,0,0] neg_hi:[1,0,0]
	v_pk_fma_f32 v[86:87], v[34:35], v[118:119], v[86:87] neg_lo:[1,0,0] neg_hi:[1,0,0]
	s_waitcnt lgkmcnt(10)
	v_pk_fma_f32 v[84:85], v[36:37], v[120:121], v[84:85] neg_lo:[1,0,0] neg_hi:[1,0,0]
	v_pk_fma_f32 v[86:87], v[38:39], v[122:123], v[86:87] neg_lo:[1,0,0] neg_hi:[1,0,0]
	s_waitcnt lgkmcnt(9)
	v_pk_fma_f32 v[84:85], v[40:41], v[124:125], v[84:85] neg_lo:[1,0,0] neg_hi:[1,0,0]
	v_pk_fma_f32 v[86:87], v[42:43], v[126:127], v[86:87] neg_lo:[1,0,0] neg_hi:[1,0,0]
	s_waitcnt lgkmcnt(8)
	v_pk_fma_f32 v[84:85], v[44:45], v[128:129], v[84:85] neg_lo:[1,0,0] neg_hi:[1,0,0]
	v_pk_fma_f32 v[86:87], v[46:47], v[130:131], v[86:87] neg_lo:[1,0,0] neg_hi:[1,0,0]
	s_waitcnt lgkmcnt(7)
	v_pk_fma_f32 v[84:85], v[48:49], v[132:133], v[84:85] neg_lo:[1,0,0] neg_hi:[1,0,0]
	v_pk_fma_f32 v[86:87], v[50:51], v[134:135], v[86:87] neg_lo:[1,0,0] neg_hi:[1,0,0]
	s_waitcnt lgkmcnt(6)
	v_pk_fma_f32 v[84:85], v[52:53], v[136:137], v[84:85] neg_lo:[1,0,0] neg_hi:[1,0,0]
	v_pk_fma_f32 v[86:87], v[54:55], v[138:139], v[86:87] neg_lo:[1,0,0] neg_hi:[1,0,0]
	s_waitcnt lgkmcnt(5)
	v_pk_fma_f32 v[84:85], v[56:57], v[140:141], v[84:85] neg_lo:[1,0,0] neg_hi:[1,0,0]
	v_pk_fma_f32 v[86:87], v[58:59], v[142:143], v[86:87] neg_lo:[1,0,0] neg_hi:[1,0,0]
	s_waitcnt lgkmcnt(4)
	v_pk_fma_f32 v[84:85], v[60:61], v[144:145], v[84:85] neg_lo:[1,0,0] neg_hi:[1,0,0]
	v_pk_fma_f32 v[86:87], v[62:63], v[146:147], v[86:87] neg_lo:[1,0,0] neg_hi:[1,0,0]
	s_waitcnt lgkmcnt(3)
	v_pk_fma_f32 v[84:85], v[64:65], v[148:149], v[84:85] neg_lo:[1,0,0] neg_hi:[1,0,0]
	v_pk_fma_f32 v[86:87], v[66:67], v[150:151], v[86:87] neg_lo:[1,0,0] neg_hi:[1,0,0]
	s_waitcnt lgkmcnt(2)
	v_pk_fma_f32 v[84:85], v[68:69], v[152:153], v[84:85] neg_lo:[1,0,0] neg_hi:[1,0,0]
	v_pk_fma_f32 v[86:87], v[70:71], v[154:155], v[86:87] neg_lo:[1,0,0] neg_hi:[1,0,0]
	s_waitcnt lgkmcnt(1)
	v_pk_fma_f32 v[84:85], v[72:73], v[156:157], v[84:85] neg_lo:[1,0,0] neg_hi:[1,0,0]
	v_pk_fma_f32 v[86:87], v[74:75], v[158:159], v[86:87] neg_lo:[1,0,0] neg_hi:[1,0,0]
	s_waitcnt lgkmcnt(0)
	v_pk_fma_f32 v[84:85], v[76:77], v[160:161], v[84:85] neg_lo:[1,0,0] neg_hi:[1,0,0]
	v_fma_f32 v86, -v78, v162, v86
	v_add_f32_e32 v84, v84, v85
	v_add_f32_e32 v86, v86, v87
	v_add_f32_e32 v163, v84, v86
	v_cvt_pk_bf16_f32 v92, v163, v163
	global_store_short v[8:9], v92, off offset:3968
	s_branch .LBB0_1044
